# peeled hybrid K-loops: steady trips stage A/B tiles by LDS-DMA (global_load_lds_dwordx4, source-side swizzle), first/last trip keep register hand-off; FFN1/FFN2/W_o/gemm1
# speedup vs baseline: 1.0213x; 1.0132x over previous
.LBB0_127:
	v_mov_b32_e32 v67, v169
	s_mov_b32 s11, s8
	v_lshrrev_b32_e32 v69, 4, v67
	v_ashrrev_i32_e32 v71, 3, v67
	v_lshrrev_b32_e32 v77, 1, v67
	v_and_b32_e32 v80, 4, v69
	v_and_b32_e32 v81, 3, v71
	v_and_b32_e32 v73, 7, v67
	v_xor_b32_e32 v75, v71, v67
	v_and_b32_e32 v77, 16, v77
	v_and_b32_e32 v79, 8, v69
	v_or_b32_e32 v82, v80, v81
	v_lshlrev_b32_e32 v75, 4, v75
	v_or3_b32 v77, v77, v79, v82
	v_bitop3_b32 v79, v80, v73, v81 bitop3:0x36
	v_lshlrev_b32_e32 v71, 7, v71
	v_lshlrev_b32_e32 v79, 4, v79
	v_and_or_b32 v122, v75, s24, v71
	v_lshl_or_b32 v121, v77, 7, v79
	s_waitcnt vmcnt(15)
	ds_write_b128 v122, v[34:37]
	s_waitcnt vmcnt(13)
	ds_write_b128 v121, v[38:41] offset:16384
	s_waitcnt vmcnt(11)
	ds_write_b128 v122, v[42:45] offset:4096
	s_waitcnt vmcnt(9)
	ds_write_b128 v121, v[46:49] offset:20480
	s_waitcnt vmcnt(7)
	ds_write_b128 v122, v[50:53] offset:8192
	s_waitcnt vmcnt(5)
	ds_write_b128 v121, v[54:57] offset:24576
	s_waitcnt vmcnt(3)
	ds_write_b128 v122, v[58:61] offset:12288
	s_waitcnt vmcnt(1)
	ds_write_b128 v121, v[62:65] offset:28672
	v_lshlrev_b32_e32 v34, 7, v67
	v_and_b32_e32 v35, 0x780, v34
	v_and_b32_e32 v123, 0x2780, v34
	v_bitop3_b32 v34, v69, v73, 3 bitop3:0x6c
	v_bfe_u32 v77, v67, 4, 2
	v_lshlrev_b32_e32 v124, 4, v34
	v_lshlrev_b32_e32 v34, 6, v67
	v_mov_b32_e32 v75, v1
	v_and_or_b32 v125, v34, s30, v35
	v_bitop3_b32 v34, v77, v73, 4 bitop3:0x36
	v_mov_b32_e32 v73, v1
	v_mov_b32_e32 v67, v1
	v_mov_b32_e32 v69, v1
	v_mov_b32_e32 v77, v1
	v_mov_b32_e32 v71, v1
	v_mov_b32_e32 v79, v1
	v_lshl_add_u64 v[100:101], v[74:75], 1, s[28:29]
	v_mov_b32_e32 v74, 0
	s_mov_b32 s5, s10
	s_mov_b32 s4, s9
	v_lshlrev_b32_e32 v126, 4, v34
	v_lshl_add_u64 v[98:99], v[72:73], 1, s[28:29]
	v_lshl_add_u64 v[102:103], v[76:77], 1, s[28:29]
	v_lshl_add_u64 v[104:105], v[78:79], 1, s[28:29]
	v_lshlrev_b64 v[106:107], 1, v[0:1]
	v_lshlrev_b64 v[108:109], 1, v[66:67]
	v_lshlrev_b64 v[110:111], 1, v[68:69]
	v_lshlrev_b64 v[112:113], 1, v[70:71]
	s_mov_b32 s8, -2
	s_mov_b64 s[42:43], s[72:73]
	v_mov_b32_e32 v75, v74
	v_mov_b32_e32 v76, v74
	v_mov_b32_e32 v77, v74
	v_mov_b32_e32 v62, v74
	v_mov_b32_e32 v63, v74
	v_mov_b32_e32 v64, v74
	v_mov_b32_e32 v65, v74
	v_mov_b32_e32 v66, v74
	v_mov_b32_e32 v67, v74
	v_mov_b32_e32 v68, v74
	v_mov_b32_e32 v69, v74
	v_mov_b32_e32 v58, v74
	v_mov_b32_e32 v59, v74
	v_mov_b32_e32 v60, v74
	v_mov_b32_e32 v61, v74
	v_mov_b32_e32 v70, v74
	v_mov_b32_e32 v71, v74
	v_mov_b32_e32 v72, v74
	v_mov_b32_e32 v73, v74
	v_mov_b32_e32 v54, v74
	v_mov_b32_e32 v55, v74
	v_mov_b32_e32 v56, v74
	v_mov_b32_e32 v57, v74
	v_mov_b32_e32 v78, v74
	v_mov_b32_e32 v79, v74
	v_mov_b32_e32 v80, v74
	v_mov_b32_e32 v81, v74
	v_mov_b32_e32 v50, v74
	v_mov_b32_e32 v51, v74
	v_mov_b32_e32 v52, v74
	v_mov_b32_e32 v53, v74
	v_mov_b32_e32 v82, v74
	v_mov_b32_e32 v83, v74
	v_mov_b32_e32 v84, v74
	v_mov_b32_e32 v85, v74
	v_mov_b32_e32 v46, v74
	v_mov_b32_e32 v47, v74
	v_mov_b32_e32 v48, v74
	v_mov_b32_e32 v49, v74
	v_mov_b32_e32 v86, v74
	v_mov_b32_e32 v87, v74
	v_mov_b32_e32 v88, v74
	v_mov_b32_e32 v89, v74
	v_mov_b32_e32 v42, v74
	v_mov_b32_e32 v43, v74
	v_mov_b32_e32 v44, v74
	v_mov_b32_e32 v45, v74
	v_mov_b32_e32 v90, v74
	v_mov_b32_e32 v91, v74
	v_mov_b32_e32 v92, v74
	v_mov_b32_e32 v93, v74
	v_mov_b32_e32 v38, v74
	v_mov_b32_e32 v39, v74
	v_mov_b32_e32 v40, v74
	v_mov_b32_e32 v41, v74
	v_mov_b32_e32 v94, v74
	v_mov_b32_e32 v95, v74
	v_mov_b32_e32 v96, v74
	v_mov_b32_e32 v97, v74
	v_mov_b32_e32 v34, v74
	v_mov_b32_e32 v35, v74
	v_mov_b32_e32 v36, v74
	v_mov_b32_e32 v37, v74
	s_waitcnt lgkmcnt(0)
	s_barrier
	v_add_u32_e32 v127, v124, v123
	v_add_u32_e32 v129, v124, v125
	v_add_u32_e32 v128, v126, v125
	v_add_u32_e32 v130, v126, v123
	v_lshrrev_b32_e32 v218, 6, v169
	v_lshlrev_b32_e32 v218, 10, v218
	v_lshrrev_b32_e32 v219, 3, v169
	v_readfirstlane_b32 s100, v218
	v_and_b32_e32 v218, 3, v219
	v_bfe_u32 v220, v219, 4, 1
	v_lshl_or_b32 v218, v220, 2, v218
	v_bfe_u32 v220, v219, 2, 1
	v_lshl_or_b32 v218, v220, 3, v218
	v_bfe_u32 v220, v219, 3, 1
	v_lshl_or_b32 v218, v220, 4, v218
	v_sub_u32_e32 v218, v218, v219
	v_mul_i32_i24_e32 v218, 0x1600, v218
	v_and_b32_e32 v219, 7, v219
	v_lshlrev_b32_e32 v219, 4, v219
	v_add_u32_e32 v206, 0x7511000, v106
	v_xor_b32_e32 v194, v206, v219
	v_mov_b32_e32 v207, v98
	v_add_u32_e32 v195, v207, v218
	v_xor_b32_e32 v195, v195, v219
	v_add_u32_e32 v208, 0x7511000, v108
	v_xor_b32_e32 v196, v208, v219
	v_mov_b32_e32 v209, v100
	v_add_u32_e32 v197, v209, v218
	v_xor_b32_e32 v197, v197, v219
	v_add_u32_e32 v214, 0x7511000, v110
	v_xor_b32_e32 v202, v214, v219
	v_mov_b32_e32 v215, v102
	v_add_u32_e32 v203, v215, v218
	v_xor_b32_e32 v203, v203, v219
	v_add_u32_e32 v216, 0x7511000, v112
	v_xor_b32_e32 v204, v216, v219
	v_mov_b32_e32 v217, v104
	v_add_u32_e32 v205, v217, v218
	v_xor_b32_e32 v205, v205, v219
.LBB0_128:
	s_setprio 1
	s_add_u32 s98, s42, s27
	s_addc_u32 s99, s43, 0
	s_add_u32 s98, s98, 0x80
	s_addc_u32 s99, s99, 0
	ds_read_b128 v[132:135], v127 offset:16384
	ds_read_b128 v[152:155], v127 offset:18432
	ds_read_b128 v[160:163], v127 offset:20480
	ds_read_b128 v[164:167], v127 offset:22528
	ds_read_b128 v[140:143], v129
	ds_read_b128 v[144:147], v129 offset:2048
	ds_read_b128 v[148:151], v129 offset:4096
	ds_read_b128 v[156:159], v129 offset:6144
	s_waitcnt lgkmcnt(3)
	v_mfma_f32_16x16x32_bf16 v[34:37], v[132:135], v[140:143], v[34:37]
	v_mfma_f32_16x16x32_bf16 v[94:97], v[152:155], v[140:143], v[94:97]
	ds_read_b128 v[198:201], v128
	v_mfma_f32_16x16x32_bf16 v[38:41], v[160:163], v[140:143], v[38:41]
	v_mfma_f32_16x16x32_bf16 v[90:93], v[164:167], v[140:143], v[90:93]
	ds_read_b128 v[140:143], v128 offset:2048
	s_waitcnt lgkmcnt(4)
	v_mfma_f32_16x16x32_bf16 v[42:45], v[132:135], v[144:147], v[42:45]
	v_mfma_f32_16x16x32_bf16 v[86:89], v[152:155], v[144:147], v[86:89]
	ds_read_b128 v[210:213], v128 offset:4096
	v_mfma_f32_16x16x32_bf16 v[46:49], v[160:163], v[144:147], v[46:49]
	v_mfma_f32_16x16x32_bf16 v[82:85], v[164:167], v[144:147], v[82:85]
	ds_read_b128 v[144:147], v128 offset:6144
	s_waitcnt lgkmcnt(5)
	v_mfma_f32_16x16x32_bf16 v[50:53], v[132:135], v[148:151], v[50:53]
	v_mfma_f32_16x16x32_bf16 v[78:81], v[152:155], v[148:151], v[78:81]
	ds_read_b128 v[222:225], v130 offset:16384
	v_mfma_f32_16x16x32_bf16 v[54:57], v[160:163], v[148:151], v[54:57]
	v_mfma_f32_16x16x32_bf16 v[70:73], v[164:167], v[148:151], v[70:73]
	ds_read_b128 v[148:151], v130 offset:18432
	s_waitcnt lgkmcnt(6)
	v_mfma_f32_16x16x32_bf16 v[58:61], v[132:135], v[156:159], v[58:61]
	v_mfma_f32_16x16x32_bf16 v[66:69], v[152:155], v[156:159], v[66:69]
	ds_read_b128 v[152:155], v130 offset:20480
	v_mfma_f32_16x16x32_bf16 v[62:65], v[160:163], v[156:159], v[62:65]
	v_mfma_f32_16x16x32_bf16 v[74:77], v[164:167], v[156:159], v[74:77]
	ds_read_b128 v[156:159], v130 offset:22528
	s_waitcnt lgkmcnt(3)
	v_mfma_f32_16x16x32_bf16 v[34:37], v[222:225], v[198:201], v[34:37]
	s_waitcnt vmcnt(7)
	ds_write_b128 v122, v[2:5] offset:32768
	s_waitcnt lgkmcnt(3)
	v_mfma_f32_16x16x32_bf16 v[94:97], v[148:151], v[198:201], v[94:97]
	s_waitcnt lgkmcnt(2)
	v_mfma_f32_16x16x32_bf16 v[38:41], v[152:155], v[198:201], v[38:41]
	s_waitcnt vmcnt(6)
	ds_write_b128 v121, v[6:9] offset:49152
	s_waitcnt lgkmcnt(2)
	v_mfma_f32_16x16x32_bf16 v[90:93], v[156:159], v[198:201], v[90:93]
	v_mfma_f32_16x16x32_bf16 v[42:45], v[222:225], v[140:143], v[42:45]
	s_waitcnt vmcnt(5)
	ds_write_b128 v122, v[10:13] offset:36864
	v_mfma_f32_16x16x32_bf16 v[86:89], v[148:151], v[140:143], v[86:89]
	v_mfma_f32_16x16x32_bf16 v[46:49], v[152:155], v[140:143], v[46:49]
	s_waitcnt vmcnt(4)
	ds_write_b128 v121, v[14:17] offset:53248
	v_mfma_f32_16x16x32_bf16 v[82:85], v[156:159], v[140:143], v[82:85]
	v_mfma_f32_16x16x32_bf16 v[50:53], v[222:225], v[210:213], v[50:53]
	s_waitcnt vmcnt(3)
	ds_write_b128 v122, v[18:21] offset:40960
	v_mfma_f32_16x16x32_bf16 v[78:81], v[148:151], v[210:213], v[78:81]
	v_mfma_f32_16x16x32_bf16 v[54:57], v[152:155], v[210:213], v[54:57]
	s_waitcnt vmcnt(2)
	ds_write_b128 v121, v[22:25] offset:57344
	v_mfma_f32_16x16x32_bf16 v[70:73], v[156:159], v[210:213], v[70:73]
	v_mfma_f32_16x16x32_bf16 v[58:61], v[222:225], v[144:147], v[58:61]
	s_waitcnt vmcnt(1)
	ds_write_b128 v122, v[26:29] offset:45056
	v_mfma_f32_16x16x32_bf16 v[66:69], v[148:151], v[144:147], v[66:69]
	v_mfma_f32_16x16x32_bf16 v[62:65], v[152:155], v[144:147], v[62:65]
	s_waitcnt vmcnt(0)
	ds_write_b128 v121, v[30:33] offset:61440
	v_mfma_f32_16x16x32_bf16 v[74:77], v[156:159], v[144:147], v[74:77]
	s_setprio 0
	s_waitcnt lgkmcnt(0)
	s_barrier
	s_setprio 1
	s_add_u32 s98, s98, 0x80
	s_addc_u32 s99, s99, 0
	ds_read_b128 v[26:29], v127 offset:49152
	ds_read_b128 v[30:33], v127 offset:51200
	ds_read_b128 v[148:151], v127 offset:53248
	ds_read_b128 v[152:155], v127 offset:55296
	ds_read_b128 v[10:13], v129 offset:32768
	ds_read_b128 v[18:21], v129 offset:34816
	ds_read_b128 v[140:143], v129 offset:36864
	ds_read_b128 v[144:147], v129 offset:38912
	s_add_u32 m0, s100, 0x0
	s_waitcnt lgkmcnt(3)
	v_mfma_f32_16x16x32_bf16 v[34:37], v[26:29], v[10:13], v[34:37]
	global_load_lds_dwordx4 v194, s[98:99]
	v_mfma_f32_16x16x32_bf16 v[94:97], v[30:33], v[10:13], v[94:97]
	ds_read_b128 v[156:159], v128 offset:32768
	s_add_u32 m0, s100, 0x4000
	v_mfma_f32_16x16x32_bf16 v[38:41], v[148:151], v[10:13], v[38:41]
	global_load_lds_dwordx4 v195, s[98:99]
	v_mfma_f32_16x16x32_bf16 v[90:93], v[152:155], v[10:13], v[90:93]
	ds_read_b128 v[164:167], v128 offset:34816
	s_add_u32 m0, s100, 0x1000
	s_waitcnt lgkmcnt(4)
	v_mfma_f32_16x16x32_bf16 v[42:45], v[26:29], v[18:21], v[42:45]
	global_load_lds_dwordx4 v196, s[98:99]
	v_mfma_f32_16x16x32_bf16 v[86:89], v[30:33], v[18:21], v[86:89]
	ds_read_b128 v[198:201], v128 offset:36864
	s_add_u32 m0, s100, 0x5000
	v_mfma_f32_16x16x32_bf16 v[46:49], v[148:151], v[18:21], v[46:49]
	global_load_lds_dwordx4 v197, s[98:99]
	v_mfma_f32_16x16x32_bf16 v[82:85], v[152:155], v[18:21], v[82:85]
	ds_read_b128 v[210:213], v128 offset:38912
	s_add_u32 m0, s100, 0x2000
	s_waitcnt lgkmcnt(5)
	v_mfma_f32_16x16x32_bf16 v[50:53], v[26:29], v[140:143], v[50:53]
	global_load_lds_dwordx4 v202, s[98:99]
	v_mfma_f32_16x16x32_bf16 v[78:81], v[30:33], v[140:143], v[78:81]
	ds_read_b128 v[222:225], v130 offset:49152
	s_add_u32 m0, s100, 0x6000
	v_mfma_f32_16x16x32_bf16 v[54:57], v[148:151], v[140:143], v[54:57]
	global_load_lds_dwordx4 v203, s[98:99]
	v_mfma_f32_16x16x32_bf16 v[70:73], v[152:155], v[140:143], v[70:73]
	ds_read_b128 v[140:143], v130 offset:51200
	s_add_u32 m0, s100, 0x3000
	s_waitcnt lgkmcnt(6)
	v_mfma_f32_16x16x32_bf16 v[58:61], v[26:29], v[144:147], v[58:61]
	global_load_lds_dwordx4 v204, s[98:99]
	v_mfma_f32_16x16x32_bf16 v[66:69], v[30:33], v[144:147], v[66:69]
	ds_read_b128 v[230:233], v130 offset:53248
	s_add_u32 m0, s100, 0x7000
	v_mfma_f32_16x16x32_bf16 v[62:65], v[148:151], v[144:147], v[62:65]
	global_load_lds_dwordx4 v205, s[98:99]
	v_mfma_f32_16x16x32_bf16 v[74:77], v[152:155], v[144:147], v[74:77]
	ds_read_b128 v[144:147], v130 offset:55296
	s_waitcnt lgkmcnt(3)
	v_mfma_f32_16x16x32_bf16 v[34:37], v[222:225], v[156:159], v[34:37]
	s_waitcnt lgkmcnt(2)
	v_mfma_f32_16x16x32_bf16 v[94:97], v[140:143], v[156:159], v[94:97]
	s_waitcnt lgkmcnt(1)
	v_mfma_f32_16x16x32_bf16 v[38:41], v[230:233], v[156:159], v[38:41]
	s_waitcnt lgkmcnt(0)
	v_mfma_f32_16x16x32_bf16 v[90:93], v[144:147], v[156:159], v[90:93]
	v_mfma_f32_16x16x32_bf16 v[42:45], v[222:225], v[164:167], v[42:45]
	v_mfma_f32_16x16x32_bf16 v[86:89], v[140:143], v[164:167], v[86:89]
	v_mfma_f32_16x16x32_bf16 v[46:49], v[230:233], v[164:167], v[46:49]
	v_mfma_f32_16x16x32_bf16 v[82:85], v[144:147], v[164:167], v[82:85]
	v_mfma_f32_16x16x32_bf16 v[50:53], v[222:225], v[198:201], v[50:53]
	v_mfma_f32_16x16x32_bf16 v[78:81], v[140:143], v[198:201], v[78:81]
	v_mfma_f32_16x16x32_bf16 v[54:57], v[230:233], v[198:201], v[54:57]
	v_mfma_f32_16x16x32_bf16 v[70:73], v[144:147], v[198:201], v[70:73]
	v_mfma_f32_16x16x32_bf16 v[58:61], v[222:225], v[210:213], v[58:61]
	v_mfma_f32_16x16x32_bf16 v[66:69], v[140:143], v[210:213], v[66:69]
	v_mfma_f32_16x16x32_bf16 v[62:65], v[230:233], v[210:213], v[62:65]
	v_mfma_f32_16x16x32_bf16 v[74:77], v[144:147], v[210:213], v[74:77]
	s_waitcnt vmcnt(0)
	s_setprio 0
	s_add_i32 s8, s8, 2
	s_add_u32 s42, s42, 0x100
	s_addc_u32 s43, s43, 0
	s_waitcnt lgkmcnt(0)
	s_barrier
.Lk3_mid_128:
	s_setprio 1
	s_add_u32 s98, s42, s27
	s_addc_u32 s99, s43, 0
	s_add_u32 s98, s98, 0x80
	s_addc_u32 s99, s99, 0
	ds_read_b128 v[132:135], v127 offset:16384
	ds_read_b128 v[152:155], v127 offset:18432
	ds_read_b128 v[160:163], v127 offset:20480
	ds_read_b128 v[164:167], v127 offset:22528
	ds_read_b128 v[140:143], v129
	ds_read_b128 v[144:147], v129 offset:2048
	ds_read_b128 v[148:151], v129 offset:4096
	ds_read_b128 v[156:159], v129 offset:6144
	s_add_u32 m0, s100, 0x8000
	s_waitcnt lgkmcnt(3)
	v_mfma_f32_16x16x32_bf16 v[34:37], v[132:135], v[140:143], v[34:37]
	global_load_lds_dwordx4 v194, s[98:99]
	v_mfma_f32_16x16x32_bf16 v[94:97], v[152:155], v[140:143], v[94:97]
	ds_read_b128 v[198:201], v128
	s_add_u32 m0, s100, 0xc000
	v_mfma_f32_16x16x32_bf16 v[38:41], v[160:163], v[140:143], v[38:41]
	global_load_lds_dwordx4 v195, s[98:99]
	v_mfma_f32_16x16x32_bf16 v[90:93], v[164:167], v[140:143], v[90:93]
	ds_read_b128 v[140:143], v128 offset:2048
	s_add_u32 m0, s100, 0x9000
	s_waitcnt lgkmcnt(4)
	v_mfma_f32_16x16x32_bf16 v[42:45], v[132:135], v[144:147], v[42:45]
	global_load_lds_dwordx4 v196, s[98:99]
	v_mfma_f32_16x16x32_bf16 v[86:89], v[152:155], v[144:147], v[86:89]
	ds_read_b128 v[210:213], v128 offset:4096
	s_add_u32 m0, s100, 0xd000
	v_mfma_f32_16x16x32_bf16 v[46:49], v[160:163], v[144:147], v[46:49]
	global_load_lds_dwordx4 v197, s[98:99]
	v_mfma_f32_16x16x32_bf16 v[82:85], v[164:167], v[144:147], v[82:85]
	ds_read_b128 v[144:147], v128 offset:6144
	s_add_u32 m0, s100, 0xa000
	s_waitcnt lgkmcnt(5)
	v_mfma_f32_16x16x32_bf16 v[50:53], v[132:135], v[148:151], v[50:53]
	global_load_lds_dwordx4 v202, s[98:99]
	v_mfma_f32_16x16x32_bf16 v[78:81], v[152:155], v[148:151], v[78:81]
	ds_read_b128 v[222:225], v130 offset:16384
	s_add_u32 m0, s100, 0xe000
	v_mfma_f32_16x16x32_bf16 v[54:57], v[160:163], v[148:151], v[54:57]
	global_load_lds_dwordx4 v203, s[98:99]
	v_mfma_f32_16x16x32_bf16 v[70:73], v[164:167], v[148:151], v[70:73]
	ds_read_b128 v[148:151], v130 offset:18432
	s_add_u32 m0, s100, 0xb000
	s_waitcnt lgkmcnt(6)
	v_mfma_f32_16x16x32_bf16 v[58:61], v[132:135], v[156:159], v[58:61]
	global_load_lds_dwordx4 v204, s[98:99]
	v_mfma_f32_16x16x32_bf16 v[66:69], v[152:155], v[156:159], v[66:69]
	ds_read_b128 v[152:155], v130 offset:20480
	s_add_u32 m0, s100, 0xf000
	v_mfma_f32_16x16x32_bf16 v[62:65], v[160:163], v[156:159], v[62:65]
	global_load_lds_dwordx4 v205, s[98:99]
	v_mfma_f32_16x16x32_bf16 v[74:77], v[164:167], v[156:159], v[74:77]
	ds_read_b128 v[156:159], v130 offset:22528
	s_waitcnt lgkmcnt(3)
	v_mfma_f32_16x16x32_bf16 v[34:37], v[222:225], v[198:201], v[34:37]
	s_waitcnt lgkmcnt(2)
	v_mfma_f32_16x16x32_bf16 v[94:97], v[148:151], v[198:201], v[94:97]
	s_waitcnt lgkmcnt(1)
	v_mfma_f32_16x16x32_bf16 v[38:41], v[152:155], v[198:201], v[38:41]
	s_waitcnt lgkmcnt(0)
	v_mfma_f32_16x16x32_bf16 v[90:93], v[156:159], v[198:201], v[90:93]
	v_mfma_f32_16x16x32_bf16 v[42:45], v[222:225], v[140:143], v[42:45]
	v_mfma_f32_16x16x32_bf16 v[86:89], v[148:151], v[140:143], v[86:89]
	v_mfma_f32_16x16x32_bf16 v[46:49], v[152:155], v[140:143], v[46:49]
	v_mfma_f32_16x16x32_bf16 v[82:85], v[156:159], v[140:143], v[82:85]
	v_mfma_f32_16x16x32_bf16 v[50:53], v[222:225], v[210:213], v[50:53]
	v_mfma_f32_16x16x32_bf16 v[78:81], v[148:151], v[210:213], v[78:81]
	v_mfma_f32_16x16x32_bf16 v[54:57], v[152:155], v[210:213], v[54:57]
	v_mfma_f32_16x16x32_bf16 v[70:73], v[156:159], v[210:213], v[70:73]
	v_mfma_f32_16x16x32_bf16 v[58:61], v[222:225], v[144:147], v[58:61]
	v_mfma_f32_16x16x32_bf16 v[66:69], v[148:151], v[144:147], v[66:69]
	v_mfma_f32_16x16x32_bf16 v[62:65], v[152:155], v[144:147], v[62:65]
	v_mfma_f32_16x16x32_bf16 v[74:77], v[156:159], v[144:147], v[74:77]
	s_waitcnt vmcnt(0)
	s_setprio 0
	s_waitcnt lgkmcnt(0)
	s_barrier
	s_setprio 1
	s_add_u32 s98, s98, 0x80
	s_addc_u32 s99, s99, 0
	ds_read_b128 v[26:29], v127 offset:49152
	ds_read_b128 v[30:33], v127 offset:51200
	ds_read_b128 v[148:151], v127 offset:53248
	ds_read_b128 v[152:155], v127 offset:55296
	ds_read_b128 v[10:13], v129 offset:32768
	ds_read_b128 v[18:21], v129 offset:34816
	ds_read_b128 v[140:143], v129 offset:36864
	ds_read_b128 v[144:147], v129 offset:38912
	s_add_u32 m0, s100, 0x0
	s_waitcnt lgkmcnt(3)
	v_mfma_f32_16x16x32_bf16 v[34:37], v[26:29], v[10:13], v[34:37]
	global_load_lds_dwordx4 v194, s[98:99]
	v_mfma_f32_16x16x32_bf16 v[94:97], v[30:33], v[10:13], v[94:97]
	ds_read_b128 v[156:159], v128 offset:32768
	s_add_u32 m0, s100, 0x4000
	v_mfma_f32_16x16x32_bf16 v[38:41], v[148:151], v[10:13], v[38:41]
	global_load_lds_dwordx4 v195, s[98:99]
	v_mfma_f32_16x16x32_bf16 v[90:93], v[152:155], v[10:13], v[90:93]
	ds_read_b128 v[164:167], v128 offset:34816
	s_add_u32 m0, s100, 0x1000
	s_waitcnt lgkmcnt(4)
	v_mfma_f32_16x16x32_bf16 v[42:45], v[26:29], v[18:21], v[42:45]
	global_load_lds_dwordx4 v196, s[98:99]
	v_mfma_f32_16x16x32_bf16 v[86:89], v[30:33], v[18:21], v[86:89]
	ds_read_b128 v[198:201], v128 offset:36864
	s_add_u32 m0, s100, 0x5000
	v_mfma_f32_16x16x32_bf16 v[46:49], v[148:151], v[18:21], v[46:49]
	global_load_lds_dwordx4 v197, s[98:99]
	v_mfma_f32_16x16x32_bf16 v[82:85], v[152:155], v[18:21], v[82:85]
	ds_read_b128 v[210:213], v128 offset:38912
	s_add_u32 m0, s100, 0x2000
	s_waitcnt lgkmcnt(5)
	v_mfma_f32_16x16x32_bf16 v[50:53], v[26:29], v[140:143], v[50:53]
	global_load_lds_dwordx4 v202, s[98:99]
	v_mfma_f32_16x16x32_bf16 v[78:81], v[30:33], v[140:143], v[78:81]
	ds_read_b128 v[222:225], v130 offset:49152
	s_add_u32 m0, s100, 0x6000
	v_mfma_f32_16x16x32_bf16 v[54:57], v[148:151], v[140:143], v[54:57]
	global_load_lds_dwordx4 v203, s[98:99]
	v_mfma_f32_16x16x32_bf16 v[70:73], v[152:155], v[140:143], v[70:73]
	ds_read_b128 v[140:143], v130 offset:51200
	s_add_u32 m0, s100, 0x3000
	s_waitcnt lgkmcnt(6)
	v_mfma_f32_16x16x32_bf16 v[58:61], v[26:29], v[144:147], v[58:61]
	global_load_lds_dwordx4 v204, s[98:99]
	v_mfma_f32_16x16x32_bf16 v[66:69], v[30:33], v[144:147], v[66:69]
	ds_read_b128 v[230:233], v130 offset:53248
	s_add_u32 m0, s100, 0x7000
	v_mfma_f32_16x16x32_bf16 v[62:65], v[148:151], v[144:147], v[62:65]
	global_load_lds_dwordx4 v205, s[98:99]
	v_mfma_f32_16x16x32_bf16 v[74:77], v[152:155], v[144:147], v[74:77]
	ds_read_b128 v[144:147], v130 offset:55296
	s_waitcnt lgkmcnt(3)
	v_mfma_f32_16x16x32_bf16 v[34:37], v[222:225], v[156:159], v[34:37]
	s_waitcnt lgkmcnt(2)
	v_mfma_f32_16x16x32_bf16 v[94:97], v[140:143], v[156:159], v[94:97]
	s_waitcnt lgkmcnt(1)
	v_mfma_f32_16x16x32_bf16 v[38:41], v[230:233], v[156:159], v[38:41]
	s_waitcnt lgkmcnt(0)
	v_mfma_f32_16x16x32_bf16 v[90:93], v[144:147], v[156:159], v[90:93]
	v_mfma_f32_16x16x32_bf16 v[42:45], v[222:225], v[164:167], v[42:45]
	v_mfma_f32_16x16x32_bf16 v[86:89], v[140:143], v[164:167], v[86:89]
	v_mfma_f32_16x16x32_bf16 v[46:49], v[230:233], v[164:167], v[46:49]
	v_mfma_f32_16x16x32_bf16 v[82:85], v[144:147], v[164:167], v[82:85]
	v_mfma_f32_16x16x32_bf16 v[50:53], v[222:225], v[198:201], v[50:53]
	v_mfma_f32_16x16x32_bf16 v[78:81], v[140:143], v[198:201], v[78:81]
	v_mfma_f32_16x16x32_bf16 v[54:57], v[230:233], v[198:201], v[54:57]
	v_mfma_f32_16x16x32_bf16 v[70:73], v[144:147], v[198:201], v[70:73]
	v_mfma_f32_16x16x32_bf16 v[58:61], v[222:225], v[210:213], v[58:61]
	v_mfma_f32_16x16x32_bf16 v[66:69], v[140:143], v[210:213], v[66:69]
	v_mfma_f32_16x16x32_bf16 v[62:65], v[230:233], v[210:213], v[62:65]
	v_mfma_f32_16x16x32_bf16 v[74:77], v[144:147], v[210:213], v[74:77]
	s_waitcnt vmcnt(0)
	s_setprio 0
	s_add_i32 s8, s8, 2
	s_add_u32 s42, s42, 0x100
	s_addc_u32 s43, s43, 0
	s_cmp_lt_u32 s8, 38
	s_waitcnt lgkmcnt(0)
	s_barrier
	s_cbranch_scc1 .Lk3_mid_128
	s_setprio 1
	s_add_u32 s98, s42, s27
	s_addc_u32 s99, s43, 0
	s_add_u32 s98, s98, 0x80
	s_addc_u32 s99, s99, 0
	ds_read_b128 v[132:135], v127 offset:16384
	ds_read_b128 v[152:155], v127 offset:18432
	ds_read_b128 v[160:163], v127 offset:20480
	ds_read_b128 v[164:167], v127 offset:22528
	ds_read_b128 v[140:143], v129
	ds_read_b128 v[144:147], v129 offset:2048
	ds_read_b128 v[148:151], v129 offset:4096
	ds_read_b128 v[156:159], v129 offset:6144
	s_add_u32 m0, s100, 0x8000
	s_waitcnt lgkmcnt(3)
	v_mfma_f32_16x16x32_bf16 v[34:37], v[132:135], v[140:143], v[34:37]
	global_load_lds_dwordx4 v194, s[98:99]
	v_mfma_f32_16x16x32_bf16 v[94:97], v[152:155], v[140:143], v[94:97]
	ds_read_b128 v[198:201], v128
	s_add_u32 m0, s100, 0xc000
	v_mfma_f32_16x16x32_bf16 v[38:41], v[160:163], v[140:143], v[38:41]
	global_load_lds_dwordx4 v195, s[98:99]
	v_mfma_f32_16x16x32_bf16 v[90:93], v[164:167], v[140:143], v[90:93]
	ds_read_b128 v[140:143], v128 offset:2048
	s_add_u32 m0, s100, 0x9000
	s_waitcnt lgkmcnt(4)
	v_mfma_f32_16x16x32_bf16 v[42:45], v[132:135], v[144:147], v[42:45]
	global_load_lds_dwordx4 v196, s[98:99]
	v_mfma_f32_16x16x32_bf16 v[86:89], v[152:155], v[144:147], v[86:89]
	ds_read_b128 v[210:213], v128 offset:4096
	s_add_u32 m0, s100, 0xd000
	v_mfma_f32_16x16x32_bf16 v[46:49], v[160:163], v[144:147], v[46:49]
	global_load_lds_dwordx4 v197, s[98:99]
	v_mfma_f32_16x16x32_bf16 v[82:85], v[164:167], v[144:147], v[82:85]
	ds_read_b128 v[144:147], v128 offset:6144
	s_add_u32 m0, s100, 0xa000
	s_waitcnt lgkmcnt(5)
	v_mfma_f32_16x16x32_bf16 v[50:53], v[132:135], v[148:151], v[50:53]
	global_load_lds_dwordx4 v202, s[98:99]
	v_mfma_f32_16x16x32_bf16 v[78:81], v[152:155], v[148:151], v[78:81]
	ds_read_b128 v[222:225], v130 offset:16384
	s_add_u32 m0, s100, 0xe000
	v_mfma_f32_16x16x32_bf16 v[54:57], v[160:163], v[148:151], v[54:57]
	global_load_lds_dwordx4 v203, s[98:99]
	v_mfma_f32_16x16x32_bf16 v[70:73], v[164:167], v[148:151], v[70:73]
	ds_read_b128 v[148:151], v130 offset:18432
	s_add_u32 m0, s100, 0xb000
	s_waitcnt lgkmcnt(6)
	v_mfma_f32_16x16x32_bf16 v[58:61], v[132:135], v[156:159], v[58:61]
	global_load_lds_dwordx4 v204, s[98:99]
	v_mfma_f32_16x16x32_bf16 v[66:69], v[152:155], v[156:159], v[66:69]
	ds_read_b128 v[152:155], v130 offset:20480
	s_add_u32 m0, s100, 0xf000
	v_mfma_f32_16x16x32_bf16 v[62:65], v[160:163], v[156:159], v[62:65]
	global_load_lds_dwordx4 v205, s[98:99]
	v_mfma_f32_16x16x32_bf16 v[74:77], v[164:167], v[156:159], v[74:77]
	ds_read_b128 v[156:159], v130 offset:22528
	s_waitcnt lgkmcnt(3)
	v_mfma_f32_16x16x32_bf16 v[34:37], v[222:225], v[198:201], v[34:37]
	s_waitcnt lgkmcnt(2)
	v_mfma_f32_16x16x32_bf16 v[94:97], v[148:151], v[198:201], v[94:97]
	s_waitcnt lgkmcnt(1)
	v_mfma_f32_16x16x32_bf16 v[38:41], v[152:155], v[198:201], v[38:41]
	s_waitcnt lgkmcnt(0)
	v_mfma_f32_16x16x32_bf16 v[90:93], v[156:159], v[198:201], v[90:93]
	v_mfma_f32_16x16x32_bf16 v[42:45], v[222:225], v[140:143], v[42:45]
	v_mfma_f32_16x16x32_bf16 v[86:89], v[148:151], v[140:143], v[86:89]
	v_mfma_f32_16x16x32_bf16 v[46:49], v[152:155], v[140:143], v[46:49]
	v_mfma_f32_16x16x32_bf16 v[82:85], v[156:159], v[140:143], v[82:85]
	v_mfma_f32_16x16x32_bf16 v[50:53], v[222:225], v[210:213], v[50:53]
	v_mfma_f32_16x16x32_bf16 v[78:81], v[148:151], v[210:213], v[78:81]
	v_mfma_f32_16x16x32_bf16 v[54:57], v[152:155], v[210:213], v[54:57]
	v_mfma_f32_16x16x32_bf16 v[70:73], v[156:159], v[210:213], v[70:73]
	v_mfma_f32_16x16x32_bf16 v[58:61], v[222:225], v[144:147], v[58:61]
	v_mfma_f32_16x16x32_bf16 v[66:69], v[148:151], v[144:147], v[66:69]
	v_mfma_f32_16x16x32_bf16 v[62:65], v[152:155], v[144:147], v[62:65]
	v_mfma_f32_16x16x32_bf16 v[74:77], v[156:159], v[144:147], v[74:77]
	s_waitcnt vmcnt(0)
	s_setprio 0
	s_waitcnt lgkmcnt(0)
	s_barrier
	s_setprio 1
	s_add_u32 s98, s98, 0x80
	s_addc_u32 s99, s99, 0
	ds_read_b128 v[26:29], v127 offset:49152
	ds_read_b128 v[30:33], v127 offset:51200
	ds_read_b128 v[148:151], v127 offset:53248
	ds_read_b128 v[152:155], v127 offset:55296
	ds_read_b128 v[10:13], v129 offset:32768
	ds_read_b128 v[18:21], v129 offset:34816
	ds_read_b128 v[140:143], v129 offset:36864
	ds_read_b128 v[144:147], v129 offset:38912
	s_add_u32 m0, s100, 0x0
	s_waitcnt lgkmcnt(3)
	v_mfma_f32_16x16x32_bf16 v[34:37], v[26:29], v[10:13], v[34:37]
	global_load_lds_dwordx4 v194, s[98:99]
	v_mfma_f32_16x16x32_bf16 v[94:97], v[30:33], v[10:13], v[94:97]
	ds_read_b128 v[156:159], v128 offset:32768
	s_add_u32 m0, s100, 0x4000
	v_mfma_f32_16x16x32_bf16 v[38:41], v[148:151], v[10:13], v[38:41]
	global_load_lds_dwordx4 v195, s[98:99]
	v_mfma_f32_16x16x32_bf16 v[90:93], v[152:155], v[10:13], v[90:93]
	ds_read_b128 v[164:167], v128 offset:34816
	s_add_u32 m0, s100, 0x1000
	s_waitcnt lgkmcnt(4)
	v_mfma_f32_16x16x32_bf16 v[42:45], v[26:29], v[18:21], v[42:45]
	global_load_lds_dwordx4 v196, s[98:99]
	v_mfma_f32_16x16x32_bf16 v[86:89], v[30:33], v[18:21], v[86:89]
	ds_read_b128 v[198:201], v128 offset:36864
	s_add_u32 m0, s100, 0x5000
	v_mfma_f32_16x16x32_bf16 v[46:49], v[148:151], v[18:21], v[46:49]
	global_load_lds_dwordx4 v197, s[98:99]
	v_mfma_f32_16x16x32_bf16 v[82:85], v[152:155], v[18:21], v[82:85]
	ds_read_b128 v[210:213], v128 offset:38912
	s_add_u32 m0, s100, 0x2000
	s_waitcnt lgkmcnt(5)
	v_mfma_f32_16x16x32_bf16 v[50:53], v[26:29], v[140:143], v[50:53]
	global_load_lds_dwordx4 v202, s[98:99]
	v_mfma_f32_16x16x32_bf16 v[78:81], v[30:33], v[140:143], v[78:81]
	ds_read_b128 v[222:225], v130 offset:49152
	s_add_u32 m0, s100, 0x6000
	v_mfma_f32_16x16x32_bf16 v[54:57], v[148:151], v[140:143], v[54:57]
	global_load_lds_dwordx4 v203, s[98:99]
	v_mfma_f32_16x16x32_bf16 v[70:73], v[152:155], v[140:143], v[70:73]
	ds_read_b128 v[140:143], v130 offset:51200
	s_add_u32 m0, s100, 0x3000
	s_waitcnt lgkmcnt(6)
	v_mfma_f32_16x16x32_bf16 v[58:61], v[26:29], v[144:147], v[58:61]
	global_load_lds_dwordx4 v204, s[98:99]
	v_mfma_f32_16x16x32_bf16 v[66:69], v[30:33], v[144:147], v[66:69]
	ds_read_b128 v[230:233], v130 offset:53248
	s_add_u32 m0, s100, 0x7000
	v_mfma_f32_16x16x32_bf16 v[62:65], v[148:151], v[144:147], v[62:65]
	global_load_lds_dwordx4 v205, s[98:99]
	v_mfma_f32_16x16x32_bf16 v[74:77], v[152:155], v[144:147], v[74:77]
	ds_read_b128 v[144:147], v130 offset:55296
	s_waitcnt lgkmcnt(3)
	v_mfma_f32_16x16x32_bf16 v[34:37], v[222:225], v[156:159], v[34:37]
	global_load_dwordx4 v[2:5], v206, s[98:99] offset:128
	s_waitcnt lgkmcnt(2)
	v_mfma_f32_16x16x32_bf16 v[94:97], v[140:143], v[156:159], v[94:97]
	s_waitcnt lgkmcnt(1)
	v_mfma_f32_16x16x32_bf16 v[38:41], v[230:233], v[156:159], v[38:41]
	global_load_dwordx4 v[6:9], v207, s[98:99] offset:128
	s_waitcnt lgkmcnt(0)
	v_mfma_f32_16x16x32_bf16 v[90:93], v[144:147], v[156:159], v[90:93]
	v_mfma_f32_16x16x32_bf16 v[42:45], v[222:225], v[164:167], v[42:45]
	global_load_dwordx4 v[10:13], v208, s[98:99] offset:128
	v_mfma_f32_16x16x32_bf16 v[86:89], v[140:143], v[164:167], v[86:89]
	v_mfma_f32_16x16x32_bf16 v[46:49], v[230:233], v[164:167], v[46:49]
	global_load_dwordx4 v[14:17], v209, s[98:99] offset:128
	v_mfma_f32_16x16x32_bf16 v[82:85], v[144:147], v[164:167], v[82:85]
	v_mfma_f32_16x16x32_bf16 v[50:53], v[222:225], v[198:201], v[50:53]
	global_load_dwordx4 v[18:21], v214, s[98:99] offset:128
	v_mfma_f32_16x16x32_bf16 v[78:81], v[140:143], v[198:201], v[78:81]
	v_mfma_f32_16x16x32_bf16 v[54:57], v[230:233], v[198:201], v[54:57]
	global_load_dwordx4 v[22:25], v215, s[98:99] offset:128
	v_mfma_f32_16x16x32_bf16 v[70:73], v[144:147], v[198:201], v[70:73]
	v_mfma_f32_16x16x32_bf16 v[58:61], v[222:225], v[210:213], v[58:61]
	global_load_dwordx4 v[26:29], v216, s[98:99] offset:128
	v_mfma_f32_16x16x32_bf16 v[66:69], v[140:143], v[210:213], v[66:69]
	v_mfma_f32_16x16x32_bf16 v[62:65], v[230:233], v[210:213], v[62:65]
	global_load_dwordx4 v[30:33], v217, s[98:99] offset:128
	v_mfma_f32_16x16x32_bf16 v[74:77], v[144:147], v[210:213], v[74:77]
	s_waitcnt vmcnt(8)
	s_setprio 0
	s_add_i32 s8, s8, 2
	s_add_u32 s42, s42, 0x100
	s_addc_u32 s43, s43, 0
	s_waitcnt lgkmcnt(0)
	s_barrier
	s_add_i32 s8, s11, s2
	s_cmpk_lt_u32 s8, 0x100
	s_cselect_b32 s10, s8, s11
	s_lshr_b32 s9, s10, 3
	s_and_b32 s9, s9, 0x1fffff8
	s_add_i32 s9, s9, s21
	s_and_b32 s11, s10, 7
	s_or_b32 s9, s9, s11
	v_mov_b32_e32 v0, v169
	s_lshl_b32 s9, s9, 7
	s_movk_i32 s11, 0xb00
	v_lshrrev_b32_e32 v98, 3, v0
	v_add_u32_e32 v98, s9, v98
	v_lshlrev_b32_e32 v0, 3, v0
	v_mul_lo_u32 v98, v98, s11
	s_lshl_b32 s10, s10, 4
	v_and_or_b32 v0, v0, 56, v98
	v_mov_b32_e32 v98, v169
	s_and_b32 s10, s10, 0x380
	s_cmpk_gt_u32 s8, 0xff
	v_lshrrev_b32_e32 v99, 3, v98
	v_add_u32_e32 v99, s10, v99
	v_lshlrev_b32_e32 v98, 3, v98
	v_mul_lo_u32 v99, v99, s11
	v_and_or_b32 v164, v98, 56, v99
	v_add_u32_e32 v114, 0x16000, v0
	v_add_u32_e32 v124, 0x2c000, v0
	v_add_u32_e32 v136, 0x42000, v0
	v_add_u32_e32 v174, 0x16000, v164
	v_add_u32_e32 v176, 0x2c000, v164
	v_add_u32_e32 v178, 0x42000, v164
	s_setprio 1
	ds_read_b128 v[98:101], v127 offset:16384
	ds_read_b128 v[110:113], v127 offset:18432
	ds_read_b128 v[144:147], v127 offset:20480
	ds_read_b128 v[148:151], v127 offset:22528
	ds_read_b128 v[102:105], v129
	ds_read_b128 v[106:109], v129 offset:2048
	ds_read_b128 v[132:135], v129 offset:4096
	ds_read_b128 v[140:143], v129 offset:6144
	v_readlane_b32 s14, v254, 33
	v_readlane_b32 s15, v254, 34
	v_mov_b32_e32 v165, v1
	v_mov_b32_e32 v115, v1
	v_mov_b32_e32 v175, v1
	v_mov_b32_e32 v125, v1
	v_mov_b32_e32 v177, v1
	v_mov_b32_e32 v137, v1
	v_mov_b32_e32 v179, v1
	v_lshl_add_u64 v[180:181], v[0:1], 1, s[14:15]
	v_lshl_add_u64 v[186:187], v[164:165], 1, s[38:39]
	v_lshl_add_u64 v[114:115], v[114:115], 1, s[14:15]
	v_lshl_add_u64 v[174:175], v[174:175], 1, s[38:39]
	v_lshl_add_u64 v[188:189], v[124:125], 1, s[14:15]
	v_lshl_add_u64 v[176:177], v[176:177], 1, s[38:39]
	v_lshl_add_u64 v[136:137], v[136:137], 1, s[14:15]
	v_lshl_add_u64 v[178:179], v[178:179], 1, s[38:39]
	s_waitcnt lgkmcnt(3)
	v_mfma_f32_16x16x32_bf16 v[152:155], v[98:101], v[102:105], v[34:37]
	s_nop 2
	global_load_dwordx4 v[34:37], v[180:181], off
	v_mfma_f32_16x16x32_bf16 v[94:97], v[110:113], v[102:105], v[94:97]
	ds_read_b128 v[156:159], v128
	v_mfma_f32_16x16x32_bf16 v[160:163], v[144:147], v[102:105], v[38:41]
	s_nop 2
	global_load_dwordx4 v[38:41], v[186:187], off
	v_mfma_f32_16x16x32_bf16 v[90:93], v[148:151], v[102:105], v[90:93]
	ds_read_b128 v[102:105], v128 offset:2048
	s_waitcnt lgkmcnt(4)
	v_mfma_f32_16x16x32_bf16 v[164:167], v[98:101], v[106:109], v[42:45]
	s_nop 2
	global_load_dwordx4 v[42:45], v[114:115], off
	v_mfma_f32_16x16x32_bf16 v[86:89], v[110:113], v[106:109], v[86:89]
	ds_read_b128 v[194:197], v128 offset:4096
	v_mfma_f32_16x16x32_bf16 v[198:201], v[144:147], v[106:109], v[46:49]
	s_nop 2
	global_load_dwordx4 v[46:49], v[174:175], off
	v_mfma_f32_16x16x32_bf16 v[82:85], v[148:151], v[106:109], v[82:85]
	ds_read_b128 v[106:109], v128 offset:6144
	s_waitcnt lgkmcnt(5)
	v_mfma_f32_16x16x32_bf16 v[202:205], v[98:101], v[132:135], v[50:53]
	s_nop 2
	global_load_dwordx4 v[50:53], v[188:189], off
	v_mfma_f32_16x16x32_bf16 v[78:81], v[110:113], v[132:135], v[78:81]
	ds_read_b128 v[206:209], v130 offset:16384
	v_mfma_f32_16x16x32_bf16 v[210:213], v[144:147], v[132:135], v[54:57]
	s_nop 2
	global_load_dwordx4 v[54:57], v[176:177], off
	v_mfma_f32_16x16x32_bf16 v[70:73], v[148:151], v[132:135], v[70:73]
	ds_read_b128 v[132:135], v130 offset:18432
	s_waitcnt lgkmcnt(6)
	v_mfma_f32_16x16x32_bf16 v[98:101], v[98:101], v[140:143], v[58:61]
	s_nop 2
	global_load_dwordx4 v[58:61], v[136:137], off
	v_mfma_f32_16x16x32_bf16 v[66:69], v[110:113], v[140:143], v[66:69]
	ds_read_b128 v[110:113], v130 offset:20480
	v_mfma_f32_16x16x32_bf16 v[144:147], v[144:147], v[140:143], v[62:65]
	s_nop 2
	global_load_dwordx4 v[62:65], v[178:179], off
	v_mfma_f32_16x16x32_bf16 v[74:77], v[148:151], v[140:143], v[74:77]
	ds_read_b128 v[140:143], v130 offset:22528
	s_waitcnt lgkmcnt(3)
	v_mfma_f32_16x16x32_bf16 v[148:151], v[206:209], v[156:159], v[152:155]
	s_waitcnt vmcnt(15)
	ds_write_b128 v122, v[2:5] offset:32768
	s_waitcnt lgkmcnt(3)
	v_mfma_f32_16x16x32_bf16 v[94:97], v[132:135], v[156:159], v[94:97]
	s_waitcnt lgkmcnt(2)
	v_mfma_f32_16x16x32_bf16 v[152:155], v[110:113], v[156:159], v[160:163]
	s_waitcnt vmcnt(14)
	ds_write_b128 v121, v[6:9] offset:49152
	s_waitcnt lgkmcnt(2)
	v_mfma_f32_16x16x32_bf16 v[90:93], v[140:143], v[156:159], v[90:93]
	v_mfma_f32_16x16x32_bf16 v[156:159], v[206:209], v[102:105], v[164:167]
	s_waitcnt vmcnt(13)
	ds_write_b128 v122, v[10:13] offset:36864
	v_mfma_f32_16x16x32_bf16 v[86:89], v[132:135], v[102:105], v[86:89]
	v_mfma_f32_16x16x32_bf16 v[160:163], v[110:113], v[102:105], v[198:201]
	s_waitcnt vmcnt(12)
	ds_write_b128 v121, v[14:17] offset:53248
	v_mfma_f32_16x16x32_bf16 v[82:85], v[140:143], v[102:105], v[82:85]
	v_mfma_f32_16x16x32_bf16 v[102:105], v[206:209], v[194:197], v[202:205]
	s_waitcnt vmcnt(11)
	ds_write_b128 v122, v[18:21] offset:40960
	v_mfma_f32_16x16x32_bf16 v[78:81], v[132:135], v[194:197], v[78:81]
	v_mfma_f32_16x16x32_bf16 v[164:167], v[110:113], v[194:197], v[210:213]
	s_waitcnt vmcnt(10)
	ds_write_b128 v121, v[22:25] offset:57344
	v_mfma_f32_16x16x32_bf16 v[70:73], v[140:143], v[194:197], v[70:73]
	v_mfma_f32_16x16x32_bf16 v[98:101], v[206:209], v[106:109], v[98:101]
	s_waitcnt vmcnt(9)
	ds_write_b128 v122, v[26:29] offset:45056
	v_mfma_f32_16x16x32_bf16 v[66:69], v[132:135], v[106:109], v[66:69]
	v_mfma_f32_16x16x32_bf16 v[110:113], v[110:113], v[106:109], v[144:147]
	s_waitcnt vmcnt(8)
	ds_write_b128 v121, v[30:33] offset:61440
	v_mfma_f32_16x16x32_bf16 v[74:77], v[140:143], v[106:109], v[74:77]
	s_setprio 0
	s_waitcnt lgkmcnt(0)
	s_barrier
	s_setprio 1
	ds_read_b128 v[26:29], v127 offset:49152
	ds_read_b128 v[30:33], v127 offset:51200
	ds_read_b128 v[132:135], v127 offset:53248
	ds_read_b128 v[140:143], v127 offset:55296
	ds_read_b128 v[10:13], v129 offset:32768
	ds_read_b128 v[18:21], v129 offset:34816
	ds_read_b128 v[106:109], v129 offset:36864
	ds_read_b128 v[122:125], v129 offset:38912
	s_waitcnt lgkmcnt(3)
	v_mfma_f32_16x16x32_bf16 v[144:147], v[26:29], v[10:13], v[148:151]
	global_load_dwordx4 v[2:5], v[180:181], off offset:128
	v_mfma_f32_16x16x32_bf16 v[94:97], v[30:33], v[10:13], v[94:97]
	s_nop 0
	ds_read_b128 v[148:151], v128 offset:32768
	v_mfma_f32_16x16x32_bf16 v[152:155], v[132:135], v[10:13], v[152:155]
	global_load_dwordx4 v[6:9], v[186:187], off offset:128
	v_mfma_f32_16x16x32_bf16 v[90:93], v[140:143], v[10:13], v[90:93]
	ds_read_b128 v[194:197], v128 offset:34816
	s_waitcnt lgkmcnt(4)
	v_mfma_f32_16x16x32_bf16 v[156:159], v[26:29], v[18:21], v[156:159]
	global_load_dwordx4 v[10:13], v[114:115], off offset:128
	v_mfma_f32_16x16x32_bf16 v[86:89], v[30:33], v[18:21], v[86:89]
	ds_read_b128 v[198:201], v128 offset:36864
	v_mfma_f32_16x16x32_bf16 v[160:163], v[132:135], v[18:21], v[160:163]
	global_load_dwordx4 v[14:17], v[174:175], off offset:128
	v_mfma_f32_16x16x32_bf16 v[82:85], v[140:143], v[18:21], v[82:85]
	ds_read_b128 v[126:129], v128 offset:38912
	s_waitcnt lgkmcnt(5)
	v_mfma_f32_16x16x32_bf16 v[202:205], v[26:29], v[106:109], v[102:105]
	global_load_dwordx4 v[18:21], v[188:189], off offset:128
	v_mfma_f32_16x16x32_bf16 v[78:81], v[30:33], v[106:109], v[78:81]
	ds_read_b128 v[206:209], v130 offset:49152
	v_mfma_f32_16x16x32_bf16 v[164:167], v[132:135], v[106:109], v[164:167]
	global_load_dwordx4 v[22:25], v[176:177], off offset:128
	v_mfma_f32_16x16x32_bf16 v[70:73], v[140:143], v[106:109], v[70:73]
	ds_read_b128 v[210:213], v130 offset:51200
	s_waitcnt lgkmcnt(6)
	v_mfma_f32_16x16x32_bf16 v[214:217], v[26:29], v[122:125], v[98:101]
	global_load_dwordx4 v[26:29], v[136:137], off offset:128
	v_mfma_f32_16x16x32_bf16 v[66:69], v[30:33], v[122:125], v[66:69]
	ds_read_b128 v[218:221], v130 offset:53248
	v_mfma_f32_16x16x32_bf16 v[110:113], v[132:135], v[122:125], v[110:113]
	global_load_dwordx4 v[30:33], v[178:179], off offset:128
	v_mfma_f32_16x16x32_bf16 v[122:125], v[140:143], v[122:125], v[74:77]
	s_waitcnt lgkmcnt(2)
	v_mfma_f32_16x16x32_bf16 v[132:135], v[206:209], v[148:151], v[144:147]
	s_waitcnt lgkmcnt(0)
	v_mfma_f32_16x16x32_bf16 v[144:147], v[218:221], v[148:151], v[152:155]
	s_nop 2
	ds_read_b128 v[152:155], v130 offset:55296
	v_mfma_f32_16x16x32_bf16 v[140:143], v[210:213], v[148:151], v[94:97]
	s_waitcnt lgkmcnt(0)
	v_mfma_f32_16x16x32_bf16 v[148:151], v[152:155], v[148:151], v[90:93]
	v_mfma_f32_16x16x32_bf16 v[98:101], v[152:155], v[194:197], v[82:85]
	v_mfma_f32_16x16x32_bf16 v[90:93], v[210:213], v[198:201], v[78:81]
	v_mfma_f32_16x16x32_bf16 v[82:85], v[152:155], v[198:201], v[70:73]
	v_mfma_f32_16x16x32_bf16 v[78:81], v[206:209], v[126:129], v[214:217]
	v_mfma_f32_16x16x32_bf16 v[74:77], v[210:213], v[126:129], v[66:69]
	v_mfma_f32_16x16x32_bf16 v[66:69], v[218:221], v[126:129], v[110:113]
	v_mfma_f32_16x16x32_bf16 v[70:73], v[152:155], v[126:129], v[122:125]
	v_mfma_f32_16x16x32_bf16 v[156:159], v[206:209], v[194:197], v[156:159]
	v_mfma_f32_16x16x32_bf16 v[106:109], v[210:213], v[194:197], v[86:89]
	v_mfma_f32_16x16x32_bf16 v[102:105], v[218:221], v[194:197], v[160:163]
	v_mfma_f32_16x16x32_bf16 v[94:97], v[206:209], v[198:201], v[202:205]
	v_mfma_f32_16x16x32_bf16 v[86:89], v[218:221], v[198:201], v[164:167]
	s_setprio 0
	v_add_u32_e32 v110, s4, v116
	v_ashrrev_i32_e32 v111, 31, v110
	v_readlane_b32 s44, v253, 18
	v_lshlrev_b64 v[112:113], 12, v[110:111]
	v_or_b32_e32 v0, s5, v117
	v_readlane_b32 s58, v253, 32
	v_readlane_b32 s59, v253, 33
	v_lshlrev_b64 v[114:115], 2, v[0:1]
	v_lshl_add_u64 v[166:167], v[110:111], 3, s[0:1]
	v_lshl_add_u64 v[112:113], s[58:59], 0, v[112:113]
	v_lshl_add_u64 v[164:165], v[112:113], 0, v[114:115]
	s_barrier
	global_load_dwordx2 v[130:131], v[166:167], off
	global_load_dwordx4 v[122:125], v[164:165], off
	v_lshl_add_u64 v[112:113], s[34:35], 0, v[114:115]
	v_lshl_add_u64 v[110:111], s[40:41], 0, v[114:115]
	global_load_dwordx4 v[126:129], v[112:113], off
	global_load_dwordx4 v[152:155], v[110:111], off
	s_mov_b32 s14, 0x3fb504f3
	global_load_dwordx4 v[160:163], v[164:165], off offset:16
	s_mov_b64 s[42:43], -1
	v_readlane_b32 s45, v253, 19
	v_readlane_b32 s46, v253, 20
	v_readlane_b32 s47, v253, 21
	v_readlane_b32 s48, v253, 22
	v_readlane_b32 s49, v253, 23
	v_readlane_b32 s50, v253, 24
	v_readlane_b32 s51, v253, 25
	v_readlane_b32 s52, v253, 26
	v_readlane_b32 s53, v253, 27
	v_readlane_b32 s54, v253, 28
	v_readlane_b32 s55, v253, 29
	v_readlane_b32 s56, v253, 30
	v_readlane_b32 s57, v253, 31
	s_waitcnt vmcnt(3)
	v_pk_add_f32 v[122:123], v[122:123], v[130:131] op_sel_hi:[1,0] neg_lo:[0,1] neg_hi:[0,1]
	v_pk_add_f32 v[124:125], v[124:125], v[130:131] op_sel_hi:[1,0] neg_lo:[0,1] neg_hi:[0,1]
	v_pk_mul_f32 v[122:123], v[122:123], v[130:131] op_sel:[0,1]
	v_pk_mul_f32 v[124:125], v[124:125], v[130:131] op_sel:[0,1]
	s_waitcnt vmcnt(1)
	v_pk_fma_f32 v[122:123], v[122:123], v[126:127], v[152:153]
	v_pk_fma_f32 v[124:125], v[124:125], v[128:129], v[154:155]
	v_pk_fma_f32 v[122:123], v[122:123], s[14:15], v[132:133] op_sel_hi:[1,0,1]
	v_pk_fma_f32 v[124:125], v[124:125], s[14:15], v[134:135] op_sel_hi:[1,0,1]
	global_store_dwordx4 v[164:165], v[122:125], off
	global_load_dwordx2 v[134:135], v[166:167], off
	global_load_dwordx4 v[126:129], v[110:111], off offset:16
	global_load_dwordx4 v[130:133], v[164:165], off offset:128
	s_waitcnt vmcnt(2)
	v_pk_add_f32 v[136:137], v[160:161], v[134:135] op_sel_hi:[1,0] neg_lo:[0,1] neg_hi:[0,1]
	global_load_dwordx4 v[122:125], v[112:113], off offset:16
	v_pk_add_f32 v[152:153], v[162:163], v[134:135] op_sel_hi:[1,0] neg_lo:[0,1] neg_hi:[0,1]
	v_pk_mul_f32 v[136:137], v[136:137], v[134:135] op_sel:[0,1]
	v_pk_mul_f32 v[134:135], v[152:153], v[134:135] op_sel:[0,1]
	s_waitcnt vmcnt(0)
	v_pk_fma_f32 v[122:123], v[136:137], v[122:123], v[126:127]
	v_pk_fma_f32 v[124:125], v[134:135], v[124:125], v[128:129]
	v_pk_fma_f32 v[122:123], v[122:123], s[14:15], v[140:141] op_sel_hi:[1,0,1]
	v_pk_fma_f32 v[124:125], v[124:125], s[14:15], v[142:143] op_sel_hi:[1,0,1]
	global_store_dwordx4 v[164:165], v[122:125], off offset:16
	global_load_dwordx2 v[140:141], v[166:167], off
	global_load_dwordx4 v[126:129], v[110:111], off offset:128
	global_load_dwordx4 v[134:137], v[164:165], off offset:144
	s_waitcnt vmcnt(2)
	v_pk_add_f32 v[130:131], v[130:131], v[140:141] op_sel_hi:[1,0] neg_lo:[0,1] neg_hi:[0,1]
	global_load_dwordx4 v[122:125], v[112:113], off offset:128
	v_pk_add_f32 v[132:133], v[132:133], v[140:141] op_sel_hi:[1,0] neg_lo:[0,1] neg_hi:[0,1]
	v_pk_mul_f32 v[130:131], v[130:131], v[140:141] op_sel:[0,1]
	v_pk_mul_f32 v[132:133], v[132:133], v[140:141] op_sel:[0,1]
	s_waitcnt vmcnt(0)
	v_pk_fma_f32 v[122:123], v[130:131], v[122:123], v[126:127]
	v_pk_fma_f32 v[124:125], v[132:133], v[124:125], v[128:129]
	v_pk_fma_f32 v[122:123], v[122:123], s[14:15], v[144:145] op_sel_hi:[1,0,1]
	v_pk_fma_f32 v[124:125], v[124:125], s[14:15], v[146:147] op_sel_hi:[1,0,1]
	global_store_dwordx4 v[164:165], v[122:125], off offset:128
	global_load_dwordx2 v[140:141], v[166:167], off
	global_load_dwordx4 v[126:129], v[110:111], off offset:144
	v_add_u32_e32 v130, s4, v118
	global_load_dwordx4 v[122:125], v[112:113], off offset:144
	v_ashrrev_i32_e32 v131, 31, v130
	v_lshlrev_b64 v[132:133], 12, v[130:131]
	v_lshl_add_u64 v[142:143], v[130:131], 3, s[0:1]
	v_lshl_add_u64 v[130:131], s[58:59], 0, v[132:133]
	v_lshl_add_u64 v[144:145], v[130:131], 0, v[114:115]
	global_load_dwordx4 v[130:133], v[144:145], off
	s_waitcnt vmcnt(3)
	v_pk_add_f32 v[134:135], v[134:135], v[140:141] op_sel_hi:[1,0] neg_lo:[0,1] neg_hi:[0,1]
	v_pk_add_f32 v[136:137], v[136:137], v[140:141] op_sel_hi:[1,0] neg_lo:[0,1] neg_hi:[0,1]
	v_pk_mul_f32 v[134:135], v[134:135], v[140:141] op_sel:[0,1]
	v_pk_mul_f32 v[136:137], v[136:137], v[140:141] op_sel:[0,1]
	s_waitcnt vmcnt(1)
	v_pk_fma_f32 v[122:123], v[134:135], v[122:123], v[126:127]
	v_pk_fma_f32 v[124:125], v[136:137], v[124:125], v[128:129]
	v_pk_fma_f32 v[122:123], v[122:123], s[14:15], v[148:149] op_sel_hi:[1,0,1]
	v_pk_fma_f32 v[124:125], v[124:125], s[14:15], v[150:151] op_sel_hi:[1,0,1]
	global_store_dwordx4 v[164:165], v[122:125], off offset:144
	global_load_dwordx2 v[140:141], v[142:143], off
	global_load_dwordx4 v[126:129], v[110:111], off
	global_load_dwordx4 v[134:137], v[144:145], off offset:16
	s_waitcnt vmcnt(2)
	v_pk_add_f32 v[130:131], v[130:131], v[140:141] op_sel_hi:[1,0] neg_lo:[0,1] neg_hi:[0,1]
	global_load_dwordx4 v[122:125], v[112:113], off
	v_pk_add_f32 v[132:133], v[132:133], v[140:141] op_sel_hi:[1,0] neg_lo:[0,1] neg_hi:[0,1]
	v_pk_mul_f32 v[130:131], v[130:131], v[140:141] op_sel:[0,1]
	v_pk_mul_f32 v[132:133], v[132:133], v[140:141] op_sel:[0,1]
	s_waitcnt vmcnt(0)
	v_pk_fma_f32 v[122:123], v[130:131], v[122:123], v[126:127]
	v_pk_fma_f32 v[124:125], v[132:133], v[124:125], v[128:129]
	v_pk_fma_f32 v[122:123], v[122:123], s[14:15], v[156:157] op_sel_hi:[1,0,1]
	v_pk_fma_f32 v[124:125], v[124:125], s[14:15], v[158:159] op_sel_hi:[1,0,1]
	global_store_dwordx4 v[144:145], v[122:125], off
	global_load_dwordx2 v[140:141], v[142:143], off
	global_load_dwordx4 v[126:129], v[110:111], off offset:16
	global_load_dwordx4 v[130:133], v[144:145], off offset:128
	s_waitcnt vmcnt(2)
	v_pk_add_f32 v[134:135], v[134:135], v[140:141] op_sel_hi:[1,0] neg_lo:[0,1] neg_hi:[0,1]
	global_load_dwordx4 v[122:125], v[112:113], off offset:16
	v_pk_add_f32 v[136:137], v[136:137], v[140:141] op_sel_hi:[1,0] neg_lo:[0,1] neg_hi:[0,1]
	v_pk_mul_f32 v[134:135], v[134:135], v[140:141] op_sel:[0,1]
	v_pk_mul_f32 v[136:137], v[136:137], v[140:141] op_sel:[0,1]
	s_waitcnt vmcnt(0)
	v_pk_fma_f32 v[122:123], v[134:135], v[122:123], v[126:127]
	v_pk_fma_f32 v[124:125], v[136:137], v[124:125], v[128:129]
	v_pk_fma_f32 v[106:107], v[122:123], s[14:15], v[106:107] op_sel_hi:[1,0,1]
	v_pk_fma_f32 v[108:109], v[124:125], s[14:15], v[108:109] op_sel_hi:[1,0,1]
	global_store_dwordx4 v[144:145], v[106:109], off offset:16
	global_load_dwordx2 v[134:135], v[142:143], off
	global_load_dwordx4 v[122:125], v[110:111], off offset:128
	global_load_dwordx4 v[126:129], v[144:145], off offset:144
	s_waitcnt vmcnt(2)
	v_pk_add_f32 v[130:131], v[130:131], v[134:135] op_sel_hi:[1,0] neg_lo:[0,1] neg_hi:[0,1]
	global_load_dwordx4 v[106:109], v[112:113], off offset:128
	v_pk_add_f32 v[132:133], v[132:133], v[134:135] op_sel_hi:[1,0] neg_lo:[0,1] neg_hi:[0,1]
	v_pk_mul_f32 v[130:131], v[130:131], v[134:135] op_sel:[0,1]
	v_pk_mul_f32 v[132:133], v[132:133], v[134:135] op_sel:[0,1]
	s_waitcnt vmcnt(0)
	v_pk_fma_f32 v[106:107], v[130:131], v[106:107], v[122:123]
	v_pk_fma_f32 v[108:109], v[132:133], v[108:109], v[124:125]
	v_pk_fma_f32 v[102:103], v[106:107], s[14:15], v[102:103] op_sel_hi:[1,0,1]
	v_pk_fma_f32 v[104:105], v[108:109], s[14:15], v[104:105] op_sel_hi:[1,0,1]
	global_store_dwordx4 v[144:145], v[102:105], off offset:128
	global_load_dwordx2 v[130:131], v[142:143], off
	global_load_dwordx4 v[106:109], v[110:111], off offset:144
	v_add_u32_e32 v122, s4, v119
	global_load_dwordx4 v[102:105], v[112:113], off offset:144
	v_ashrrev_i32_e32 v123, 31, v122
	v_lshlrev_b64 v[124:125], 12, v[122:123]
	v_lshl_add_u64 v[132:133], v[122:123], 3, s[0:1]
	v_lshl_add_u64 v[122:123], s[58:59], 0, v[124:125]
	v_lshl_add_u64 v[134:135], v[122:123], 0, v[114:115]
	global_load_dwordx4 v[122:125], v[134:135], off
	s_waitcnt vmcnt(3)
	v_pk_add_f32 v[126:127], v[126:127], v[130:131] op_sel_hi:[1,0] neg_lo:[0,1] neg_hi:[0,1]
	v_pk_add_f32 v[128:129], v[128:129], v[130:131] op_sel_hi:[1,0] neg_lo:[0,1] neg_hi:[0,1]
	v_pk_mul_f32 v[126:127], v[126:127], v[130:131] op_sel:[0,1]
	v_pk_mul_f32 v[128:129], v[128:129], v[130:131] op_sel:[0,1]
	s_waitcnt vmcnt(1)
	v_pk_fma_f32 v[102:103], v[126:127], v[102:103], v[106:107]
	v_pk_fma_f32 v[104:105], v[128:129], v[104:105], v[108:109]
	v_pk_fma_f32 v[98:99], v[102:103], s[14:15], v[98:99] op_sel_hi:[1,0,1]
	v_pk_fma_f32 v[100:101], v[104:105], s[14:15], v[100:101] op_sel_hi:[1,0,1]
	global_store_dwordx4 v[144:145], v[98:101], off offset:144
	global_load_dwordx2 v[126:127], v[132:133], off
	global_load_dwordx4 v[102:105], v[110:111], off
	global_load_dwordx4 v[106:109], v[134:135], off offset:16
	s_waitcnt vmcnt(2)
	v_pk_add_f32 v[122:123], v[122:123], v[126:127] op_sel_hi:[1,0] neg_lo:[0,1] neg_hi:[0,1]
	global_load_dwordx4 v[98:101], v[112:113], off
	v_pk_add_f32 v[124:125], v[124:125], v[126:127] op_sel_hi:[1,0] neg_lo:[0,1] neg_hi:[0,1]
	v_pk_mul_f32 v[122:123], v[122:123], v[126:127] op_sel:[0,1]
	v_pk_mul_f32 v[124:125], v[124:125], v[126:127] op_sel:[0,1]
	s_waitcnt vmcnt(0)
	v_pk_fma_f32 v[98:99], v[122:123], v[98:99], v[102:103]
	v_pk_fma_f32 v[100:101], v[124:125], v[100:101], v[104:105]
	v_pk_fma_f32 v[94:95], v[98:99], s[14:15], v[94:95] op_sel_hi:[1,0,1]
	v_pk_fma_f32 v[96:97], v[100:101], s[14:15], v[96:97] op_sel_hi:[1,0,1]
	global_store_dwordx4 v[134:135], v[94:97], off
	global_load_dwordx2 v[122:123], v[132:133], off
	global_load_dwordx4 v[98:101], v[110:111], off offset:16
	global_load_dwordx4 v[102:105], v[134:135], off offset:128
	s_waitcnt vmcnt(2)
	v_pk_add_f32 v[106:107], v[106:107], v[122:123] op_sel_hi:[1,0] neg_lo:[0,1] neg_hi:[0,1]
	global_load_dwordx4 v[94:97], v[112:113], off offset:16
	v_pk_add_f32 v[108:109], v[108:109], v[122:123] op_sel_hi:[1,0] neg_lo:[0,1] neg_hi:[0,1]
	v_pk_mul_f32 v[106:107], v[106:107], v[122:123] op_sel:[0,1]
	v_pk_mul_f32 v[108:109], v[108:109], v[122:123] op_sel:[0,1]
	s_waitcnt vmcnt(0)
	v_pk_fma_f32 v[94:95], v[106:107], v[94:95], v[98:99]
	v_pk_fma_f32 v[96:97], v[108:109], v[96:97], v[100:101]
	v_pk_fma_f32 v[90:91], v[94:95], s[14:15], v[90:91] op_sel_hi:[1,0,1]
	v_pk_fma_f32 v[92:93], v[96:97], s[14:15], v[92:93] op_sel_hi:[1,0,1]
	global_store_dwordx4 v[134:135], v[90:93], off offset:16
	global_load_dwordx2 v[106:107], v[132:133], off
	global_load_dwordx4 v[94:97], v[110:111], off offset:128
	global_load_dwordx4 v[98:101], v[134:135], off offset:144
	s_waitcnt vmcnt(2)
	v_pk_add_f32 v[102:103], v[102:103], v[106:107] op_sel_hi:[1,0] neg_lo:[0,1] neg_hi:[0,1]
	global_load_dwordx4 v[90:93], v[112:113], off offset:128
	v_pk_add_f32 v[104:105], v[104:105], v[106:107] op_sel_hi:[1,0] neg_lo:[0,1] neg_hi:[0,1]
	v_pk_mul_f32 v[102:103], v[102:103], v[106:107] op_sel:[0,1]
	v_pk_mul_f32 v[104:105], v[104:105], v[106:107] op_sel:[0,1]
	s_waitcnt vmcnt(0)
	v_pk_fma_f32 v[90:91], v[102:103], v[90:91], v[94:95]
	v_pk_fma_f32 v[92:93], v[104:105], v[92:93], v[96:97]
	v_pk_fma_f32 v[86:87], v[90:91], s[14:15], v[86:87] op_sel_hi:[1,0,1]
	v_pk_fma_f32 v[88:89], v[92:93], s[14:15], v[88:89] op_sel_hi:[1,0,1]
	global_store_dwordx4 v[134:135], v[86:89], off offset:128
	global_load_dwordx2 v[102:103], v[132:133], off
	global_load_dwordx4 v[90:93], v[110:111], off offset:144
	v_add_u32_e32 v94, s4, v120
	global_load_dwordx4 v[86:89], v[112:113], off offset:144
	v_ashrrev_i32_e32 v95, 31, v94
	v_lshlrev_b64 v[96:97], 12, v[94:95]
	v_lshl_add_u64 v[104:105], v[94:95], 3, s[0:1]
	v_lshl_add_u64 v[94:95], s[58:59], 0, v[96:97]
	v_lshl_add_u64 v[106:107], v[94:95], 0, v[114:115]
	global_load_dwordx4 v[94:97], v[106:107], off
	s_waitcnt vmcnt(3)
	v_pk_add_f32 v[98:99], v[98:99], v[102:103] op_sel_hi:[1,0] neg_lo:[0,1] neg_hi:[0,1]
	v_pk_add_f32 v[100:101], v[100:101], v[102:103] op_sel_hi:[1,0] neg_lo:[0,1] neg_hi:[0,1]
	v_pk_mul_f32 v[98:99], v[98:99], v[102:103] op_sel:[0,1]
	v_pk_mul_f32 v[100:101], v[100:101], v[102:103] op_sel:[0,1]
	s_waitcnt vmcnt(1)
	v_pk_fma_f32 v[86:87], v[98:99], v[86:87], v[90:91]
	v_pk_fma_f32 v[88:89], v[100:101], v[88:89], v[92:93]
	v_pk_fma_f32 v[82:83], v[86:87], s[14:15], v[82:83] op_sel_hi:[1,0,1]
	v_pk_fma_f32 v[84:85], v[88:89], s[14:15], v[84:85] op_sel_hi:[1,0,1]
	global_store_dwordx4 v[134:135], v[82:85], off offset:144
	global_load_dwordx2 v[98:99], v[104:105], off
	global_load_dwordx4 v[86:89], v[110:111], off
	global_load_dwordx4 v[90:93], v[106:107], off offset:16
	s_waitcnt vmcnt(2)
	v_pk_add_f32 v[94:95], v[94:95], v[98:99] op_sel_hi:[1,0] neg_lo:[0,1] neg_hi:[0,1]
	global_load_dwordx4 v[82:85], v[112:113], off
	v_pk_add_f32 v[96:97], v[96:97], v[98:99] op_sel_hi:[1,0] neg_lo:[0,1] neg_hi:[0,1]
	v_pk_mul_f32 v[94:95], v[94:95], v[98:99] op_sel:[0,1]
	v_pk_mul_f32 v[96:97], v[96:97], v[98:99] op_sel:[0,1]
	s_waitcnt vmcnt(0)
	v_pk_fma_f32 v[82:83], v[94:95], v[82:83], v[86:87]
	v_pk_fma_f32 v[84:85], v[96:97], v[84:85], v[88:89]
	v_pk_fma_f32 v[78:79], v[82:83], s[14:15], v[78:79] op_sel_hi:[1,0,1]
	v_pk_fma_f32 v[80:81], v[84:85], s[14:15], v[80:81] op_sel_hi:[1,0,1]
	global_store_dwordx4 v[106:107], v[78:81], off
	global_load_dwordx2 v[94:95], v[104:105], off
	global_load_dwordx4 v[82:85], v[110:111], off offset:16
	global_load_dwordx4 v[86:89], v[106:107], off offset:128
	s_waitcnt vmcnt(2)
	v_pk_add_f32 v[90:91], v[90:91], v[94:95] op_sel_hi:[1,0] neg_lo:[0,1] neg_hi:[0,1]
	global_load_dwordx4 v[78:81], v[112:113], off offset:16
	v_pk_add_f32 v[92:93], v[92:93], v[94:95] op_sel_hi:[1,0] neg_lo:[0,1] neg_hi:[0,1]
	v_pk_mul_f32 v[90:91], v[90:91], v[94:95] op_sel:[0,1]
	v_pk_mul_f32 v[92:93], v[92:93], v[94:95] op_sel:[0,1]
	s_waitcnt vmcnt(0)
	v_pk_fma_f32 v[78:79], v[90:91], v[78:79], v[82:83]
	v_pk_fma_f32 v[80:81], v[92:93], v[80:81], v[84:85]
	v_pk_fma_f32 v[74:75], v[78:79], s[14:15], v[74:75] op_sel_hi:[1,0,1]
	v_pk_fma_f32 v[76:77], v[80:81], s[14:15], v[76:77] op_sel_hi:[1,0,1]
	global_store_dwordx4 v[106:107], v[74:77], off offset:16
	global_load_dwordx2 v[90:91], v[104:105], off
	global_load_dwordx4 v[78:81], v[110:111], off offset:128
	global_load_dwordx4 v[82:85], v[106:107], off offset:144
	s_waitcnt vmcnt(2)
	v_pk_add_f32 v[86:87], v[86:87], v[90:91] op_sel_hi:[1,0] neg_lo:[0,1] neg_hi:[0,1]
	global_load_dwordx4 v[74:77], v[112:113], off offset:128
	v_pk_add_f32 v[88:89], v[88:89], v[90:91] op_sel_hi:[1,0] neg_lo:[0,1] neg_hi:[0,1]
	v_pk_mul_f32 v[86:87], v[86:87], v[90:91] op_sel:[0,1]
	v_pk_mul_f32 v[88:89], v[88:89], v[90:91] op_sel:[0,1]
	s_waitcnt vmcnt(0)
	v_pk_fma_f32 v[74:75], v[86:87], v[74:75], v[78:79]
	v_pk_fma_f32 v[76:77], v[88:89], v[76:77], v[80:81]
	v_pk_fma_f32 v[66:67], v[74:75], s[14:15], v[66:67] op_sel_hi:[1,0,1]
	v_pk_fma_f32 v[68:69], v[76:77], s[14:15], v[68:69] op_sel_hi:[1,0,1]
	global_store_dwordx4 v[106:107], v[66:69], off offset:128
	global_load_dwordx2 v[78:79], v[104:105], off
	global_load_dwordx4 v[74:77], v[110:111], off offset:144
	s_waitcnt vmcnt(1)
	v_pk_add_f32 v[80:81], v[82:83], v[78:79] op_sel_hi:[1,0] neg_lo:[0,1] neg_hi:[0,1]
	global_load_dwordx4 v[66:69], v[112:113], off offset:144
	v_pk_add_f32 v[82:83], v[84:85], v[78:79] op_sel_hi:[1,0] neg_lo:[0,1] neg_hi:[0,1]
	v_pk_mul_f32 v[80:81], v[80:81], v[78:79] op_sel:[0,1]
	v_pk_mul_f32 v[78:79], v[82:83], v[78:79] op_sel:[0,1]
	s_waitcnt vmcnt(0)
	v_pk_fma_f32 v[66:67], v[80:81], v[66:67], v[74:75]
	v_pk_fma_f32 v[68:69], v[78:79], v[68:69], v[76:77]
	v_pk_fma_f32 v[66:67], v[66:67], s[14:15], v[70:71] op_sel_hi:[1,0,1]
	v_pk_fma_f32 v[68:69], v[68:69], s[14:15], v[72:73] op_sel_hi:[1,0,1]
	global_store_dwordx4 v[106:107], v[66:69], off offset:144
	s_cbranch_scc1 .LBB0_126
	v_mov_b32_e32 v0, v169
	v_mov_b32_e32 v67, v169
	s_movk_i32 s4, 0xb00
	v_lshrrev_b32_e32 v66, 3, v0
	v_lshrrev_b32_e32 v69, 3, v67
	v_add_u32_e32 v66, s9, v66
	v_add_u32_e32 v69, s10, v69
	v_lshlrev_b32_e32 v0, 3, v0
	v_mul_lo_u32 v66, v66, s4
	v_lshlrev_b32_e32 v67, 3, v67
	v_mul_lo_u32 v69, v69, s4
	v_and_or_b32 v0, v0, 56, v66
	v_and_or_b32 v72, v67, 56, v69
	v_add_u32_e32 v66, 0x16000, v0
	v_add_u32_e32 v68, 0x2c000, v0
	v_add_u32_e32 v70, 0x42000, v0
	v_add_u32_e32 v74, 0x16000, v72
	v_add_u32_e32 v76, 0x2c000, v72
	v_add_u32_e32 v78, 0x42000, v72
	s_mov_b64 s[42:43], 0
	s_branch .LBB0_126

.LBB0_136:
	v_mov_b32_e32 v67, v169
	s_mov_b32 s8, s9
	v_lshrrev_b32_e32 v69, 4, v67
	v_ashrrev_i32_e32 v71, 3, v67
	v_lshrrev_b32_e32 v77, 1, v67
	v_and_b32_e32 v80, 4, v69
	v_and_b32_e32 v81, 3, v71
	v_and_b32_e32 v73, 7, v67
	v_xor_b32_e32 v75, v71, v67
	v_and_b32_e32 v77, 16, v77
	v_and_b32_e32 v79, 8, v69
	v_or_b32_e32 v82, v80, v81
	v_lshlrev_b32_e32 v75, 4, v75
	v_or3_b32 v77, v77, v79, v82
	v_bitop3_b32 v79, v80, v73, v81 bitop3:0x36
	v_lshlrev_b32_e32 v71, 7, v71
	v_lshlrev_b32_e32 v79, 4, v79
	v_and_or_b32 v123, v75, s24, v71
	v_lshl_or_b32 v99, v77, 7, v79
	s_waitcnt vmcnt(15)
	ds_write_b128 v123, v[34:37]
	s_waitcnt vmcnt(13)
	ds_write_b128 v99, v[38:41] offset:16384
	s_waitcnt vmcnt(11)
	ds_write_b128 v123, v[42:45] offset:4096
	s_waitcnt vmcnt(9)
	ds_write_b128 v99, v[46:49] offset:20480
	s_waitcnt vmcnt(7)
	ds_write_b128 v123, v[50:53] offset:8192
	s_waitcnt vmcnt(5)
	ds_write_b128 v99, v[54:57] offset:24576
	s_waitcnt vmcnt(3)
	ds_write_b128 v123, v[58:61] offset:12288
	s_waitcnt vmcnt(1)
	ds_write_b128 v99, v[62:65] offset:28672
	v_lshlrev_b32_e32 v35, 7, v67
	v_bfe_u32 v34, v67, 4, 2
	v_and_b32_e32 v36, 0x780, v35
	v_and_b32_e32 v124, 0x2780, v35
	v_bitop3_b32 v35, v69, v73, 3 bitop3:0x6c
	v_mov_b32_e32 v75, v1
	v_lshlrev_b32_e32 v125, 4, v35
	v_lshlrev_b32_e32 v35, 6, v67
	v_bitop3_b32 v34, v34, v73, 4 bitop3:0x36
	v_mov_b32_e32 v73, v1
	v_mov_b32_e32 v67, v1
	v_mov_b32_e32 v69, v1
	v_mov_b32_e32 v77, v1
	v_mov_b32_e32 v71, v1
	v_mov_b32_e32 v79, v1
	v_lshl_add_u64 v[102:103], v[74:75], 1, s[0:1]
	v_mov_b32_e32 v74, 0
	s_mov_b32 s5, s10
	v_and_or_b32 v126, v35, s30, v36
	v_lshlrev_b32_e32 v127, 4, v34
	v_lshl_add_u64 v[100:101], v[72:73], 1, s[0:1]
	v_lshl_add_u64 v[104:105], v[76:77], 1, s[0:1]
	v_lshl_add_u64 v[106:107], v[78:79], 1, s[0:1]
	v_lshlrev_b64 v[108:109], 1, v[0:1]
	v_lshlrev_b64 v[110:111], 1, v[66:67]
	v_lshlrev_b64 v[112:113], 1, v[68:69]
	v_lshlrev_b64 v[114:115], 1, v[70:71]
	s_mov_b32 s9, -2
	s_mov_b64 s[46:47], s[28:29]
	v_mov_b32_e32 v75, v74
	v_mov_b32_e32 v76, v74
	v_mov_b32_e32 v77, v74
	v_mov_b32_e32 v62, v74
	v_mov_b32_e32 v63, v74
	v_mov_b32_e32 v64, v74
	v_mov_b32_e32 v65, v74
	v_mov_b32_e32 v66, v74
	v_mov_b32_e32 v67, v74
	v_mov_b32_e32 v68, v74
	v_mov_b32_e32 v69, v74
	v_mov_b32_e32 v58, v74
	v_mov_b32_e32 v59, v74
	v_mov_b32_e32 v60, v74
	v_mov_b32_e32 v61, v74
	v_mov_b32_e32 v70, v74
	v_mov_b32_e32 v71, v74
	v_mov_b32_e32 v72, v74
	v_mov_b32_e32 v73, v74
	v_mov_b32_e32 v54, v74
	v_mov_b32_e32 v55, v74
	v_mov_b32_e32 v56, v74
	v_mov_b32_e32 v57, v74
	v_mov_b32_e32 v78, v74
	v_mov_b32_e32 v79, v74
	v_mov_b32_e32 v80, v74
	v_mov_b32_e32 v81, v74
	v_mov_b32_e32 v50, v74
	v_mov_b32_e32 v51, v74
	v_mov_b32_e32 v52, v74
	v_mov_b32_e32 v53, v74
	v_mov_b32_e32 v82, v74
	v_mov_b32_e32 v83, v74
	v_mov_b32_e32 v84, v74
	v_mov_b32_e32 v85, v74
	v_mov_b32_e32 v46, v74
	v_mov_b32_e32 v47, v74
	v_mov_b32_e32 v48, v74
	v_mov_b32_e32 v49, v74
	v_mov_b32_e32 v86, v74
	v_mov_b32_e32 v87, v74
	v_mov_b32_e32 v88, v74
	v_mov_b32_e32 v89, v74
	v_mov_b32_e32 v42, v74
	v_mov_b32_e32 v43, v74
	v_mov_b32_e32 v44, v74
	v_mov_b32_e32 v45, v74
	v_mov_b32_e32 v90, v74
	v_mov_b32_e32 v91, v74
	v_mov_b32_e32 v92, v74
	v_mov_b32_e32 v93, v74
	v_mov_b32_e32 v38, v74
	v_mov_b32_e32 v39, v74
	v_mov_b32_e32 v40, v74
	v_mov_b32_e32 v41, v74
	v_mov_b32_e32 v94, v74
	v_mov_b32_e32 v95, v74
	v_mov_b32_e32 v96, v74
	v_mov_b32_e32 v97, v74
	v_mov_b32_e32 v34, v74
	v_mov_b32_e32 v35, v74
	v_mov_b32_e32 v36, v74
	v_mov_b32_e32 v37, v74
	s_waitcnt lgkmcnt(0)
	s_barrier
	v_add_u32_e32 v128, v125, v124
	v_add_u32_e32 v130, v125, v126
	v_add_u32_e32 v129, v127, v126
	v_add_u32_e32 v131, v127, v124
	v_lshrrev_b32_e32 v218, 6, v169
	v_lshlrev_b32_e32 v218, 10, v218
	v_lshrrev_b32_e32 v219, 3, v169
	v_readfirstlane_b32 s100, v218
	v_and_b32_e32 v218, 3, v219
	v_bfe_u32 v220, v219, 4, 1
	v_lshl_or_b32 v218, v220, 2, v218
	v_bfe_u32 v220, v219, 2, 1
	v_lshl_or_b32 v218, v220, 3, v218
	v_bfe_u32 v220, v219, 3, 1
	v_lshl_or_b32 v218, v220, 4, v218
	v_sub_u32_e32 v218, v218, v219
	v_mul_i32_i24_e32 v218, 0x800, v218
	v_and_b32_e32 v219, 7, v219
	v_lshlrev_b32_e32 v219, 4, v219
	v_add_u32_e32 v206, 0x2b11000, v108
	v_xor_b32_e32 v194, v206, v219
	v_mov_b32_e32 v207, v100
	v_add_u32_e32 v195, v207, v218
	v_xor_b32_e32 v195, v195, v219
	v_add_u32_e32 v208, 0x2b11000, v110
	v_xor_b32_e32 v196, v208, v219
	v_mov_b32_e32 v209, v102
	v_add_u32_e32 v197, v209, v218
	v_xor_b32_e32 v197, v197, v219
	v_add_u32_e32 v214, 0x2b11000, v112
	v_xor_b32_e32 v202, v214, v219
	v_mov_b32_e32 v215, v104
	v_add_u32_e32 v203, v215, v218
	v_xor_b32_e32 v203, v203, v219
	v_add_u32_e32 v216, 0x2b11000, v114
	v_xor_b32_e32 v204, v216, v219
	v_mov_b32_e32 v217, v106
	v_add_u32_e32 v205, v217, v218
	v_xor_b32_e32 v205, v205, v219
.LBB0_137:
	s_setprio 1
	s_add_u32 s98, s46, s16
	s_addc_u32 s99, s47, 0
	s_add_u32 s98, s98, 0x80
	s_addc_u32 s99, s99, 0
	ds_read_b128 v[132:135], v128 offset:16384
	ds_read_b128 v[152:155], v128 offset:18432
	ds_read_b128 v[160:163], v128 offset:20480
	ds_read_b128 v[164:167], v128 offset:22528
	ds_read_b128 v[140:143], v130
	ds_read_b128 v[144:147], v130 offset:2048
	ds_read_b128 v[148:151], v130 offset:4096
	ds_read_b128 v[156:159], v130 offset:6144
	s_waitcnt lgkmcnt(3)
	v_mfma_f32_16x16x32_bf16 v[34:37], v[132:135], v[140:143], v[34:37]
	v_mfma_f32_16x16x32_bf16 v[94:97], v[152:155], v[140:143], v[94:97]
	ds_read_b128 v[198:201], v129
	v_mfma_f32_16x16x32_bf16 v[38:41], v[160:163], v[140:143], v[38:41]
	v_mfma_f32_16x16x32_bf16 v[90:93], v[164:167], v[140:143], v[90:93]
	ds_read_b128 v[140:143], v129 offset:2048
	s_waitcnt lgkmcnt(4)
	v_mfma_f32_16x16x32_bf16 v[42:45], v[132:135], v[144:147], v[42:45]
	v_mfma_f32_16x16x32_bf16 v[86:89], v[152:155], v[144:147], v[86:89]
	ds_read_b128 v[210:213], v129 offset:4096
	v_mfma_f32_16x16x32_bf16 v[46:49], v[160:163], v[144:147], v[46:49]
	v_mfma_f32_16x16x32_bf16 v[82:85], v[164:167], v[144:147], v[82:85]
	ds_read_b128 v[144:147], v129 offset:6144
	s_waitcnt lgkmcnt(5)
	v_mfma_f32_16x16x32_bf16 v[50:53], v[132:135], v[148:151], v[50:53]
	v_mfma_f32_16x16x32_bf16 v[78:81], v[152:155], v[148:151], v[78:81]
	ds_read_b128 v[222:225], v131 offset:16384
	v_mfma_f32_16x16x32_bf16 v[54:57], v[160:163], v[148:151], v[54:57]
	v_mfma_f32_16x16x32_bf16 v[70:73], v[164:167], v[148:151], v[70:73]
	ds_read_b128 v[148:151], v131 offset:18432
	s_waitcnt lgkmcnt(6)
	v_mfma_f32_16x16x32_bf16 v[58:61], v[132:135], v[156:159], v[58:61]
	v_mfma_f32_16x16x32_bf16 v[66:69], v[152:155], v[156:159], v[66:69]
	ds_read_b128 v[152:155], v131 offset:20480
	v_mfma_f32_16x16x32_bf16 v[62:65], v[160:163], v[156:159], v[62:65]
	v_mfma_f32_16x16x32_bf16 v[74:77], v[164:167], v[156:159], v[74:77]
	ds_read_b128 v[156:159], v131 offset:22528
	s_waitcnt lgkmcnt(3)
	v_mfma_f32_16x16x32_bf16 v[34:37], v[222:225], v[198:201], v[34:37]
	s_waitcnt vmcnt(7)
	ds_write_b128 v123, v[2:5] offset:32768
	s_waitcnt lgkmcnt(3)
	v_mfma_f32_16x16x32_bf16 v[94:97], v[148:151], v[198:201], v[94:97]
	s_waitcnt lgkmcnt(2)
	v_mfma_f32_16x16x32_bf16 v[38:41], v[152:155], v[198:201], v[38:41]
	s_waitcnt vmcnt(6)
	ds_write_b128 v99, v[6:9] offset:49152
	s_waitcnt lgkmcnt(2)
	v_mfma_f32_16x16x32_bf16 v[90:93], v[156:159], v[198:201], v[90:93]
	v_mfma_f32_16x16x32_bf16 v[42:45], v[222:225], v[140:143], v[42:45]
	s_waitcnt vmcnt(5)
	ds_write_b128 v123, v[10:13] offset:36864
	v_mfma_f32_16x16x32_bf16 v[86:89], v[148:151], v[140:143], v[86:89]
	v_mfma_f32_16x16x32_bf16 v[46:49], v[152:155], v[140:143], v[46:49]
	s_waitcnt vmcnt(4)
	ds_write_b128 v99, v[14:17] offset:53248
	v_mfma_f32_16x16x32_bf16 v[82:85], v[156:159], v[140:143], v[82:85]
	v_mfma_f32_16x16x32_bf16 v[50:53], v[222:225], v[210:213], v[50:53]
	s_waitcnt vmcnt(3)
	ds_write_b128 v123, v[18:21] offset:40960
	v_mfma_f32_16x16x32_bf16 v[78:81], v[148:151], v[210:213], v[78:81]
	v_mfma_f32_16x16x32_bf16 v[54:57], v[152:155], v[210:213], v[54:57]
	s_waitcnt vmcnt(2)
	ds_write_b128 v99, v[22:25] offset:57344
	v_mfma_f32_16x16x32_bf16 v[70:73], v[156:159], v[210:213], v[70:73]
	v_mfma_f32_16x16x32_bf16 v[58:61], v[222:225], v[144:147], v[58:61]
	s_waitcnt vmcnt(1)
	ds_write_b128 v123, v[26:29] offset:45056
	v_mfma_f32_16x16x32_bf16 v[66:69], v[148:151], v[144:147], v[66:69]
	v_mfma_f32_16x16x32_bf16 v[62:65], v[152:155], v[144:147], v[62:65]
	s_waitcnt vmcnt(0)
	ds_write_b128 v99, v[30:33] offset:61440
	v_mfma_f32_16x16x32_bf16 v[74:77], v[156:159], v[144:147], v[74:77]
	s_setprio 0
	s_waitcnt lgkmcnt(0)
	s_barrier
	s_setprio 1
	s_add_u32 s98, s98, 0x80
	s_addc_u32 s99, s99, 0
	ds_read_b128 v[26:29], v128 offset:49152
	ds_read_b128 v[30:33], v128 offset:51200
	ds_read_b128 v[148:151], v128 offset:53248
	ds_read_b128 v[152:155], v128 offset:55296
	ds_read_b128 v[10:13], v130 offset:32768
	ds_read_b128 v[18:21], v130 offset:34816
	ds_read_b128 v[140:143], v130 offset:36864
	ds_read_b128 v[144:147], v130 offset:38912
	s_add_u32 m0, s100, 0x0
	s_waitcnt lgkmcnt(3)
	v_mfma_f32_16x16x32_bf16 v[34:37], v[26:29], v[10:13], v[34:37]
	global_load_lds_dwordx4 v194, s[98:99]
	v_mfma_f32_16x16x32_bf16 v[94:97], v[30:33], v[10:13], v[94:97]
	ds_read_b128 v[156:159], v129 offset:32768
	s_add_u32 m0, s100, 0x4000
	v_mfma_f32_16x16x32_bf16 v[38:41], v[148:151], v[10:13], v[38:41]
	global_load_lds_dwordx4 v195, s[98:99]
	v_mfma_f32_16x16x32_bf16 v[90:93], v[152:155], v[10:13], v[90:93]
	ds_read_b128 v[164:167], v129 offset:34816
	s_add_u32 m0, s100, 0x1000
	s_waitcnt lgkmcnt(4)
	v_mfma_f32_16x16x32_bf16 v[42:45], v[26:29], v[18:21], v[42:45]
	global_load_lds_dwordx4 v196, s[98:99]
	v_mfma_f32_16x16x32_bf16 v[86:89], v[30:33], v[18:21], v[86:89]
	ds_read_b128 v[198:201], v129 offset:36864
	s_add_u32 m0, s100, 0x5000
	v_mfma_f32_16x16x32_bf16 v[46:49], v[148:151], v[18:21], v[46:49]
	global_load_lds_dwordx4 v197, s[98:99]
	v_mfma_f32_16x16x32_bf16 v[82:85], v[152:155], v[18:21], v[82:85]
	ds_read_b128 v[210:213], v129 offset:38912
	s_add_u32 m0, s100, 0x2000
	s_waitcnt lgkmcnt(5)
	v_mfma_f32_16x16x32_bf16 v[50:53], v[26:29], v[140:143], v[50:53]
	global_load_lds_dwordx4 v202, s[98:99]
	v_mfma_f32_16x16x32_bf16 v[78:81], v[30:33], v[140:143], v[78:81]
	ds_read_b128 v[222:225], v131 offset:49152
	s_add_u32 m0, s100, 0x6000
	v_mfma_f32_16x16x32_bf16 v[54:57], v[148:151], v[140:143], v[54:57]
	global_load_lds_dwordx4 v203, s[98:99]
	v_mfma_f32_16x16x32_bf16 v[70:73], v[152:155], v[140:143], v[70:73]
	ds_read_b128 v[140:143], v131 offset:51200
	s_add_u32 m0, s100, 0x3000
	s_waitcnt lgkmcnt(6)
	v_mfma_f32_16x16x32_bf16 v[58:61], v[26:29], v[144:147], v[58:61]
	global_load_lds_dwordx4 v204, s[98:99]
	v_mfma_f32_16x16x32_bf16 v[66:69], v[30:33], v[144:147], v[66:69]
	ds_read_b128 v[230:233], v131 offset:53248
	s_add_u32 m0, s100, 0x7000
	v_mfma_f32_16x16x32_bf16 v[62:65], v[148:151], v[144:147], v[62:65]
	global_load_lds_dwordx4 v205, s[98:99]
	v_mfma_f32_16x16x32_bf16 v[74:77], v[152:155], v[144:147], v[74:77]
	ds_read_b128 v[144:147], v131 offset:55296
	s_waitcnt lgkmcnt(3)
	v_mfma_f32_16x16x32_bf16 v[34:37], v[222:225], v[156:159], v[34:37]
	s_waitcnt lgkmcnt(2)
	v_mfma_f32_16x16x32_bf16 v[94:97], v[140:143], v[156:159], v[94:97]
	s_waitcnt lgkmcnt(1)
	v_mfma_f32_16x16x32_bf16 v[38:41], v[230:233], v[156:159], v[38:41]
	s_waitcnt lgkmcnt(0)
	v_mfma_f32_16x16x32_bf16 v[90:93], v[144:147], v[156:159], v[90:93]
	v_mfma_f32_16x16x32_bf16 v[42:45], v[222:225], v[164:167], v[42:45]
	v_mfma_f32_16x16x32_bf16 v[86:89], v[140:143], v[164:167], v[86:89]
	v_mfma_f32_16x16x32_bf16 v[46:49], v[230:233], v[164:167], v[46:49]
	v_mfma_f32_16x16x32_bf16 v[82:85], v[144:147], v[164:167], v[82:85]
	v_mfma_f32_16x16x32_bf16 v[50:53], v[222:225], v[198:201], v[50:53]
	v_mfma_f32_16x16x32_bf16 v[78:81], v[140:143], v[198:201], v[78:81]
	v_mfma_f32_16x16x32_bf16 v[54:57], v[230:233], v[198:201], v[54:57]
	v_mfma_f32_16x16x32_bf16 v[70:73], v[144:147], v[198:201], v[70:73]
	v_mfma_f32_16x16x32_bf16 v[58:61], v[222:225], v[210:213], v[58:61]
	v_mfma_f32_16x16x32_bf16 v[66:69], v[140:143], v[210:213], v[66:69]
	v_mfma_f32_16x16x32_bf16 v[62:65], v[230:233], v[210:213], v[62:65]
	v_mfma_f32_16x16x32_bf16 v[74:77], v[144:147], v[210:213], v[74:77]
	s_waitcnt vmcnt(0)
	s_setprio 0
	s_add_i32 s9, s9, 2
	s_add_u32 s46, s46, 0x100
	s_addc_u32 s47, s47, 0
	s_waitcnt lgkmcnt(0)
	s_barrier
.Lk3_mid_137:
	s_setprio 1
	s_add_u32 s98, s46, s16
	s_addc_u32 s99, s47, 0
	s_add_u32 s98, s98, 0x80
	s_addc_u32 s99, s99, 0
	ds_read_b128 v[132:135], v128 offset:16384
	ds_read_b128 v[152:155], v128 offset:18432
	ds_read_b128 v[160:163], v128 offset:20480
	ds_read_b128 v[164:167], v128 offset:22528
	ds_read_b128 v[140:143], v130
	ds_read_b128 v[144:147], v130 offset:2048
	ds_read_b128 v[148:151], v130 offset:4096
	ds_read_b128 v[156:159], v130 offset:6144
	s_add_u32 m0, s100, 0x8000
	s_waitcnt lgkmcnt(3)
	v_mfma_f32_16x16x32_bf16 v[34:37], v[132:135], v[140:143], v[34:37]
	global_load_lds_dwordx4 v194, s[98:99]
	v_mfma_f32_16x16x32_bf16 v[94:97], v[152:155], v[140:143], v[94:97]
	ds_read_b128 v[198:201], v129
	s_add_u32 m0, s100, 0xc000
	v_mfma_f32_16x16x32_bf16 v[38:41], v[160:163], v[140:143], v[38:41]
	global_load_lds_dwordx4 v195, s[98:99]
	v_mfma_f32_16x16x32_bf16 v[90:93], v[164:167], v[140:143], v[90:93]
	ds_read_b128 v[140:143], v129 offset:2048
	s_add_u32 m0, s100, 0x9000
	s_waitcnt lgkmcnt(4)
	v_mfma_f32_16x16x32_bf16 v[42:45], v[132:135], v[144:147], v[42:45]
	global_load_lds_dwordx4 v196, s[98:99]
	v_mfma_f32_16x16x32_bf16 v[86:89], v[152:155], v[144:147], v[86:89]
	ds_read_b128 v[210:213], v129 offset:4096
	s_add_u32 m0, s100, 0xd000
	v_mfma_f32_16x16x32_bf16 v[46:49], v[160:163], v[144:147], v[46:49]
	global_load_lds_dwordx4 v197, s[98:99]
	v_mfma_f32_16x16x32_bf16 v[82:85], v[164:167], v[144:147], v[82:85]
	ds_read_b128 v[144:147], v129 offset:6144
	s_add_u32 m0, s100, 0xa000
	s_waitcnt lgkmcnt(5)
	v_mfma_f32_16x16x32_bf16 v[50:53], v[132:135], v[148:151], v[50:53]
	global_load_lds_dwordx4 v202, s[98:99]
	v_mfma_f32_16x16x32_bf16 v[78:81], v[152:155], v[148:151], v[78:81]
	ds_read_b128 v[222:225], v131 offset:16384
	s_add_u32 m0, s100, 0xe000
	v_mfma_f32_16x16x32_bf16 v[54:57], v[160:163], v[148:151], v[54:57]
	global_load_lds_dwordx4 v203, s[98:99]
	v_mfma_f32_16x16x32_bf16 v[70:73], v[164:167], v[148:151], v[70:73]
	ds_read_b128 v[148:151], v131 offset:18432
	s_add_u32 m0, s100, 0xb000
	s_waitcnt lgkmcnt(6)
	v_mfma_f32_16x16x32_bf16 v[58:61], v[132:135], v[156:159], v[58:61]
	global_load_lds_dwordx4 v204, s[98:99]
	v_mfma_f32_16x16x32_bf16 v[66:69], v[152:155], v[156:159], v[66:69]
	ds_read_b128 v[152:155], v131 offset:20480
	s_add_u32 m0, s100, 0xf000
	v_mfma_f32_16x16x32_bf16 v[62:65], v[160:163], v[156:159], v[62:65]
	global_load_lds_dwordx4 v205, s[98:99]
	v_mfma_f32_16x16x32_bf16 v[74:77], v[164:167], v[156:159], v[74:77]
	ds_read_b128 v[156:159], v131 offset:22528
	s_waitcnt lgkmcnt(3)
	v_mfma_f32_16x16x32_bf16 v[34:37], v[222:225], v[198:201], v[34:37]
	s_waitcnt lgkmcnt(2)
	v_mfma_f32_16x16x32_bf16 v[94:97], v[148:151], v[198:201], v[94:97]
	s_waitcnt lgkmcnt(1)
	v_mfma_f32_16x16x32_bf16 v[38:41], v[152:155], v[198:201], v[38:41]
	s_waitcnt lgkmcnt(0)
	v_mfma_f32_16x16x32_bf16 v[90:93], v[156:159], v[198:201], v[90:93]
	v_mfma_f32_16x16x32_bf16 v[42:45], v[222:225], v[140:143], v[42:45]
	v_mfma_f32_16x16x32_bf16 v[86:89], v[148:151], v[140:143], v[86:89]
	v_mfma_f32_16x16x32_bf16 v[46:49], v[152:155], v[140:143], v[46:49]
	v_mfma_f32_16x16x32_bf16 v[82:85], v[156:159], v[140:143], v[82:85]
	v_mfma_f32_16x16x32_bf16 v[50:53], v[222:225], v[210:213], v[50:53]
	v_mfma_f32_16x16x32_bf16 v[78:81], v[148:151], v[210:213], v[78:81]
	v_mfma_f32_16x16x32_bf16 v[54:57], v[152:155], v[210:213], v[54:57]
	v_mfma_f32_16x16x32_bf16 v[70:73], v[156:159], v[210:213], v[70:73]
	v_mfma_f32_16x16x32_bf16 v[58:61], v[222:225], v[144:147], v[58:61]
	v_mfma_f32_16x16x32_bf16 v[66:69], v[148:151], v[144:147], v[66:69]
	v_mfma_f32_16x16x32_bf16 v[62:65], v[152:155], v[144:147], v[62:65]
	v_mfma_f32_16x16x32_bf16 v[74:77], v[156:159], v[144:147], v[74:77]
	s_waitcnt vmcnt(0)
	s_setprio 0
	s_waitcnt lgkmcnt(0)
	s_barrier
	s_setprio 1
	s_add_u32 s98, s98, 0x80
	s_addc_u32 s99, s99, 0
	ds_read_b128 v[26:29], v128 offset:49152
	ds_read_b128 v[30:33], v128 offset:51200
	ds_read_b128 v[148:151], v128 offset:53248
	ds_read_b128 v[152:155], v128 offset:55296
	ds_read_b128 v[10:13], v130 offset:32768
	ds_read_b128 v[18:21], v130 offset:34816
	ds_read_b128 v[140:143], v130 offset:36864
	ds_read_b128 v[144:147], v130 offset:38912
	s_add_u32 m0, s100, 0x0
	s_waitcnt lgkmcnt(3)
	v_mfma_f32_16x16x32_bf16 v[34:37], v[26:29], v[10:13], v[34:37]
	global_load_lds_dwordx4 v194, s[98:99]
	v_mfma_f32_16x16x32_bf16 v[94:97], v[30:33], v[10:13], v[94:97]
	ds_read_b128 v[156:159], v129 offset:32768
	s_add_u32 m0, s100, 0x4000
	v_mfma_f32_16x16x32_bf16 v[38:41], v[148:151], v[10:13], v[38:41]
	global_load_lds_dwordx4 v195, s[98:99]
	v_mfma_f32_16x16x32_bf16 v[90:93], v[152:155], v[10:13], v[90:93]
	ds_read_b128 v[164:167], v129 offset:34816
	s_add_u32 m0, s100, 0x1000
	s_waitcnt lgkmcnt(4)
	v_mfma_f32_16x16x32_bf16 v[42:45], v[26:29], v[18:21], v[42:45]
	global_load_lds_dwordx4 v196, s[98:99]
	v_mfma_f32_16x16x32_bf16 v[86:89], v[30:33], v[18:21], v[86:89]
	ds_read_b128 v[198:201], v129 offset:36864
	s_add_u32 m0, s100, 0x5000
	v_mfma_f32_16x16x32_bf16 v[46:49], v[148:151], v[18:21], v[46:49]
	global_load_lds_dwordx4 v197, s[98:99]
	v_mfma_f32_16x16x32_bf16 v[82:85], v[152:155], v[18:21], v[82:85]
	ds_read_b128 v[210:213], v129 offset:38912
	s_add_u32 m0, s100, 0x2000
	s_waitcnt lgkmcnt(5)
	v_mfma_f32_16x16x32_bf16 v[50:53], v[26:29], v[140:143], v[50:53]
	global_load_lds_dwordx4 v202, s[98:99]
	v_mfma_f32_16x16x32_bf16 v[78:81], v[30:33], v[140:143], v[78:81]
	ds_read_b128 v[222:225], v131 offset:49152
	s_add_u32 m0, s100, 0x6000
	v_mfma_f32_16x16x32_bf16 v[54:57], v[148:151], v[140:143], v[54:57]
	global_load_lds_dwordx4 v203, s[98:99]
	v_mfma_f32_16x16x32_bf16 v[70:73], v[152:155], v[140:143], v[70:73]
	ds_read_b128 v[140:143], v131 offset:51200
	s_add_u32 m0, s100, 0x3000
	s_waitcnt lgkmcnt(6)
	v_mfma_f32_16x16x32_bf16 v[58:61], v[26:29], v[144:147], v[58:61]
	global_load_lds_dwordx4 v204, s[98:99]
	v_mfma_f32_16x16x32_bf16 v[66:69], v[30:33], v[144:147], v[66:69]
	ds_read_b128 v[230:233], v131 offset:53248
	s_add_u32 m0, s100, 0x7000
	v_mfma_f32_16x16x32_bf16 v[62:65], v[148:151], v[144:147], v[62:65]
	global_load_lds_dwordx4 v205, s[98:99]
	v_mfma_f32_16x16x32_bf16 v[74:77], v[152:155], v[144:147], v[74:77]
	ds_read_b128 v[144:147], v131 offset:55296
	s_waitcnt lgkmcnt(3)
	v_mfma_f32_16x16x32_bf16 v[34:37], v[222:225], v[156:159], v[34:37]
	s_waitcnt lgkmcnt(2)
	v_mfma_f32_16x16x32_bf16 v[94:97], v[140:143], v[156:159], v[94:97]
	s_waitcnt lgkmcnt(1)
	v_mfma_f32_16x16x32_bf16 v[38:41], v[230:233], v[156:159], v[38:41]
	s_waitcnt lgkmcnt(0)
	v_mfma_f32_16x16x32_bf16 v[90:93], v[144:147], v[156:159], v[90:93]
	v_mfma_f32_16x16x32_bf16 v[42:45], v[222:225], v[164:167], v[42:45]
	v_mfma_f32_16x16x32_bf16 v[86:89], v[140:143], v[164:167], v[86:89]
	v_mfma_f32_16x16x32_bf16 v[46:49], v[230:233], v[164:167], v[46:49]
	v_mfma_f32_16x16x32_bf16 v[82:85], v[144:147], v[164:167], v[82:85]
	v_mfma_f32_16x16x32_bf16 v[50:53], v[222:225], v[198:201], v[50:53]
	v_mfma_f32_16x16x32_bf16 v[78:81], v[140:143], v[198:201], v[78:81]
	v_mfma_f32_16x16x32_bf16 v[54:57], v[230:233], v[198:201], v[54:57]
	v_mfma_f32_16x16x32_bf16 v[70:73], v[144:147], v[198:201], v[70:73]
	v_mfma_f32_16x16x32_bf16 v[58:61], v[222:225], v[210:213], v[58:61]
	v_mfma_f32_16x16x32_bf16 v[66:69], v[140:143], v[210:213], v[66:69]
	v_mfma_f32_16x16x32_bf16 v[62:65], v[230:233], v[210:213], v[62:65]
	v_mfma_f32_16x16x32_bf16 v[74:77], v[144:147], v[210:213], v[74:77]
	s_waitcnt vmcnt(0)
	s_setprio 0
	s_add_i32 s9, s9, 2
	s_add_u32 s46, s46, 0x100
	s_addc_u32 s47, s47, 0
	s_cmp_lt_u32 s9, 10
	s_waitcnt lgkmcnt(0)
	s_barrier
	s_cbranch_scc1 .Lk3_mid_137
	s_setprio 1
	s_add_u32 s98, s46, s16
	s_addc_u32 s99, s47, 0
	s_add_u32 s98, s98, 0x80
	s_addc_u32 s99, s99, 0
	ds_read_b128 v[132:135], v128 offset:16384
	ds_read_b128 v[152:155], v128 offset:18432
	ds_read_b128 v[160:163], v128 offset:20480
	ds_read_b128 v[164:167], v128 offset:22528
	ds_read_b128 v[140:143], v130
	ds_read_b128 v[144:147], v130 offset:2048
	ds_read_b128 v[148:151], v130 offset:4096
	ds_read_b128 v[156:159], v130 offset:6144
	s_add_u32 m0, s100, 0x8000
	s_waitcnt lgkmcnt(3)
	v_mfma_f32_16x16x32_bf16 v[34:37], v[132:135], v[140:143], v[34:37]
	global_load_lds_dwordx4 v194, s[98:99]
	v_mfma_f32_16x16x32_bf16 v[94:97], v[152:155], v[140:143], v[94:97]
	ds_read_b128 v[198:201], v129
	s_add_u32 m0, s100, 0xc000
	v_mfma_f32_16x16x32_bf16 v[38:41], v[160:163], v[140:143], v[38:41]
	global_load_lds_dwordx4 v195, s[98:99]
	v_mfma_f32_16x16x32_bf16 v[90:93], v[164:167], v[140:143], v[90:93]
	ds_read_b128 v[140:143], v129 offset:2048
	s_add_u32 m0, s100, 0x9000
	s_waitcnt lgkmcnt(4)
	v_mfma_f32_16x16x32_bf16 v[42:45], v[132:135], v[144:147], v[42:45]
	global_load_lds_dwordx4 v196, s[98:99]
	v_mfma_f32_16x16x32_bf16 v[86:89], v[152:155], v[144:147], v[86:89]
	ds_read_b128 v[210:213], v129 offset:4096
	s_add_u32 m0, s100, 0xd000
	v_mfma_f32_16x16x32_bf16 v[46:49], v[160:163], v[144:147], v[46:49]
	global_load_lds_dwordx4 v197, s[98:99]
	v_mfma_f32_16x16x32_bf16 v[82:85], v[164:167], v[144:147], v[82:85]
	ds_read_b128 v[144:147], v129 offset:6144
	s_add_u32 m0, s100, 0xa000
	s_waitcnt lgkmcnt(5)
	v_mfma_f32_16x16x32_bf16 v[50:53], v[132:135], v[148:151], v[50:53]
	global_load_lds_dwordx4 v202, s[98:99]
	v_mfma_f32_16x16x32_bf16 v[78:81], v[152:155], v[148:151], v[78:81]
	ds_read_b128 v[222:225], v131 offset:16384
	s_add_u32 m0, s100, 0xe000
	v_mfma_f32_16x16x32_bf16 v[54:57], v[160:163], v[148:151], v[54:57]
	global_load_lds_dwordx4 v203, s[98:99]
	v_mfma_f32_16x16x32_bf16 v[70:73], v[164:167], v[148:151], v[70:73]
	ds_read_b128 v[148:151], v131 offset:18432
	s_add_u32 m0, s100, 0xb000
	s_waitcnt lgkmcnt(6)
	v_mfma_f32_16x16x32_bf16 v[58:61], v[132:135], v[156:159], v[58:61]
	global_load_lds_dwordx4 v204, s[98:99]
	v_mfma_f32_16x16x32_bf16 v[66:69], v[152:155], v[156:159], v[66:69]
	ds_read_b128 v[152:155], v131 offset:20480
	s_add_u32 m0, s100, 0xf000
	v_mfma_f32_16x16x32_bf16 v[62:65], v[160:163], v[156:159], v[62:65]
	global_load_lds_dwordx4 v205, s[98:99]
	v_mfma_f32_16x16x32_bf16 v[74:77], v[164:167], v[156:159], v[74:77]
	ds_read_b128 v[156:159], v131 offset:22528
	s_waitcnt lgkmcnt(3)
	v_mfma_f32_16x16x32_bf16 v[34:37], v[222:225], v[198:201], v[34:37]
	s_waitcnt lgkmcnt(2)
	v_mfma_f32_16x16x32_bf16 v[94:97], v[148:151], v[198:201], v[94:97]
	s_waitcnt lgkmcnt(1)
	v_mfma_f32_16x16x32_bf16 v[38:41], v[152:155], v[198:201], v[38:41]
	s_waitcnt lgkmcnt(0)
	v_mfma_f32_16x16x32_bf16 v[90:93], v[156:159], v[198:201], v[90:93]
	v_mfma_f32_16x16x32_bf16 v[42:45], v[222:225], v[140:143], v[42:45]
	v_mfma_f32_16x16x32_bf16 v[86:89], v[148:151], v[140:143], v[86:89]
	v_mfma_f32_16x16x32_bf16 v[46:49], v[152:155], v[140:143], v[46:49]
	v_mfma_f32_16x16x32_bf16 v[82:85], v[156:159], v[140:143], v[82:85]
	v_mfma_f32_16x16x32_bf16 v[50:53], v[222:225], v[210:213], v[50:53]
	v_mfma_f32_16x16x32_bf16 v[78:81], v[148:151], v[210:213], v[78:81]
	v_mfma_f32_16x16x32_bf16 v[54:57], v[152:155], v[210:213], v[54:57]
	v_mfma_f32_16x16x32_bf16 v[70:73], v[156:159], v[210:213], v[70:73]
	v_mfma_f32_16x16x32_bf16 v[58:61], v[222:225], v[144:147], v[58:61]
	v_mfma_f32_16x16x32_bf16 v[66:69], v[148:151], v[144:147], v[66:69]
	v_mfma_f32_16x16x32_bf16 v[62:65], v[152:155], v[144:147], v[62:65]
	v_mfma_f32_16x16x32_bf16 v[74:77], v[156:159], v[144:147], v[74:77]
	s_waitcnt vmcnt(0)
	s_setprio 0
	s_waitcnt lgkmcnt(0)
	s_barrier
	s_setprio 1
	s_add_u32 s98, s98, 0x80
	s_addc_u32 s99, s99, 0
	ds_read_b128 v[26:29], v128 offset:49152
	ds_read_b128 v[30:33], v128 offset:51200
	ds_read_b128 v[148:151], v128 offset:53248
	ds_read_b128 v[152:155], v128 offset:55296
	ds_read_b128 v[10:13], v130 offset:32768
	ds_read_b128 v[18:21], v130 offset:34816
	ds_read_b128 v[140:143], v130 offset:36864
	ds_read_b128 v[144:147], v130 offset:38912
	s_add_u32 m0, s100, 0x0
	s_waitcnt lgkmcnt(3)
	v_mfma_f32_16x16x32_bf16 v[34:37], v[26:29], v[10:13], v[34:37]
	global_load_lds_dwordx4 v194, s[98:99]
	v_mfma_f32_16x16x32_bf16 v[94:97], v[30:33], v[10:13], v[94:97]
	ds_read_b128 v[156:159], v129 offset:32768
	s_add_u32 m0, s100, 0x4000
	v_mfma_f32_16x16x32_bf16 v[38:41], v[148:151], v[10:13], v[38:41]
	global_load_lds_dwordx4 v195, s[98:99]
	v_mfma_f32_16x16x32_bf16 v[90:93], v[152:155], v[10:13], v[90:93]
	ds_read_b128 v[164:167], v129 offset:34816
	s_add_u32 m0, s100, 0x1000
	s_waitcnt lgkmcnt(4)
	v_mfma_f32_16x16x32_bf16 v[42:45], v[26:29], v[18:21], v[42:45]
	global_load_lds_dwordx4 v196, s[98:99]
	v_mfma_f32_16x16x32_bf16 v[86:89], v[30:33], v[18:21], v[86:89]
	ds_read_b128 v[198:201], v129 offset:36864
	s_add_u32 m0, s100, 0x5000
	v_mfma_f32_16x16x32_bf16 v[46:49], v[148:151], v[18:21], v[46:49]
	global_load_lds_dwordx4 v197, s[98:99]
	v_mfma_f32_16x16x32_bf16 v[82:85], v[152:155], v[18:21], v[82:85]
	ds_read_b128 v[210:213], v129 offset:38912
	s_add_u32 m0, s100, 0x2000
	s_waitcnt lgkmcnt(5)
	v_mfma_f32_16x16x32_bf16 v[50:53], v[26:29], v[140:143], v[50:53]
	global_load_lds_dwordx4 v202, s[98:99]
	v_mfma_f32_16x16x32_bf16 v[78:81], v[30:33], v[140:143], v[78:81]
	ds_read_b128 v[222:225], v131 offset:49152
	s_add_u32 m0, s100, 0x6000
	v_mfma_f32_16x16x32_bf16 v[54:57], v[148:151], v[140:143], v[54:57]
	global_load_lds_dwordx4 v203, s[98:99]
	v_mfma_f32_16x16x32_bf16 v[70:73], v[152:155], v[140:143], v[70:73]
	ds_read_b128 v[140:143], v131 offset:51200
	s_add_u32 m0, s100, 0x3000
	s_waitcnt lgkmcnt(6)
	v_mfma_f32_16x16x32_bf16 v[58:61], v[26:29], v[144:147], v[58:61]
	global_load_lds_dwordx4 v204, s[98:99]
	v_mfma_f32_16x16x32_bf16 v[66:69], v[30:33], v[144:147], v[66:69]
	ds_read_b128 v[230:233], v131 offset:53248
	s_add_u32 m0, s100, 0x7000
	v_mfma_f32_16x16x32_bf16 v[62:65], v[148:151], v[144:147], v[62:65]
	global_load_lds_dwordx4 v205, s[98:99]
	v_mfma_f32_16x16x32_bf16 v[74:77], v[152:155], v[144:147], v[74:77]
	ds_read_b128 v[144:147], v131 offset:55296
	s_waitcnt lgkmcnt(3)
	v_mfma_f32_16x16x32_bf16 v[34:37], v[222:225], v[156:159], v[34:37]
	global_load_dwordx4 v[2:5], v206, s[98:99] offset:128
	s_waitcnt lgkmcnt(2)
	v_mfma_f32_16x16x32_bf16 v[94:97], v[140:143], v[156:159], v[94:97]
	s_waitcnt lgkmcnt(1)
	v_mfma_f32_16x16x32_bf16 v[38:41], v[230:233], v[156:159], v[38:41]
	global_load_dwordx4 v[6:9], v207, s[98:99] offset:128
	s_waitcnt lgkmcnt(0)
	v_mfma_f32_16x16x32_bf16 v[90:93], v[144:147], v[156:159], v[90:93]
	v_mfma_f32_16x16x32_bf16 v[42:45], v[222:225], v[164:167], v[42:45]
	global_load_dwordx4 v[10:13], v208, s[98:99] offset:128
	v_mfma_f32_16x16x32_bf16 v[86:89], v[140:143], v[164:167], v[86:89]
	v_mfma_f32_16x16x32_bf16 v[46:49], v[230:233], v[164:167], v[46:49]
	global_load_dwordx4 v[14:17], v209, s[98:99] offset:128
	v_mfma_f32_16x16x32_bf16 v[82:85], v[144:147], v[164:167], v[82:85]
	v_mfma_f32_16x16x32_bf16 v[50:53], v[222:225], v[198:201], v[50:53]
	global_load_dwordx4 v[18:21], v214, s[98:99] offset:128
	v_mfma_f32_16x16x32_bf16 v[78:81], v[140:143], v[198:201], v[78:81]
	v_mfma_f32_16x16x32_bf16 v[54:57], v[230:233], v[198:201], v[54:57]
	global_load_dwordx4 v[22:25], v215, s[98:99] offset:128
	v_mfma_f32_16x16x32_bf16 v[70:73], v[144:147], v[198:201], v[70:73]
	v_mfma_f32_16x16x32_bf16 v[58:61], v[222:225], v[210:213], v[58:61]
	global_load_dwordx4 v[26:29], v216, s[98:99] offset:128
	v_mfma_f32_16x16x32_bf16 v[66:69], v[140:143], v[210:213], v[66:69]
	v_mfma_f32_16x16x32_bf16 v[62:65], v[230:233], v[210:213], v[62:65]
	global_load_dwordx4 v[30:33], v217, s[98:99] offset:128
	v_mfma_f32_16x16x32_bf16 v[74:77], v[144:147], v[210:213], v[74:77]
	s_waitcnt vmcnt(8)
	s_setprio 0
	s_add_i32 s9, s9, 2
	s_add_u32 s46, s46, 0x100
	s_addc_u32 s47, s47, 0
	s_waitcnt lgkmcnt(0)
	s_barrier
	s_add_i32 s9, s8, s2
	s_cmpk_lt_u32 s9, 0x580
	s_cselect_b32 s8, s9, s8
	s_mul_hi_u32 s10, s8, 0xba2e8ba3
	s_lshr_b32 s10, s10, 8
	s_mul_i32 s11, s10, 0x160
	v_mov_b32_e32 v0, v169
	s_sub_i32 s11, s8, s11
	s_lshl_b32 s8, s10, 3
	s_add_i32 s8, s8, s21
	s_and_b32 s10, s11, 7
	v_lshlrev_b32_e32 v100, 3, v0
	v_lshlrev_b32_e32 v0, 7, v0
	s_or_b32 s8, s8, s10
	v_and_b32_e32 v0, 0xfffffc00, v0
	v_lshl_add_u32 v0, s8, 17, v0
	v_and_or_b32 v0, v100, 56, v0
	v_mov_b32_e32 v100, v169
	s_lshl_b32 s10, s11, 4
	s_and_b32 s10, s10, 0x1f80
	v_lshrrev_b32_e32 v101, 3, v100
	v_lshlrev_b32_e32 v100, 3, v100
	v_add_u32_e32 v101, s10, v101
	v_and_b32_e32 v100, 56, v100
	v_lshl_or_b32 v160, v101, 10, v100
	s_cmpk_gt_u32 s9, 0x57f
	v_add_u32_e32 v116, 0x8000, v0
	v_add_u32_e32 v136, 0x10000, v0
	v_add_u32_e32 v174, 0x18000, v0
	v_add_u32_e32 v176, 0x8000, v160
	v_add_u32_e32 v178, 0x10000, v160
	v_add_u32_e32 v180, 0x18000, v160
	s_setprio 1
	ds_read_b128 v[100:103], v128 offset:16384
	ds_read_b128 v[112:115], v128 offset:18432
	ds_read_b128 v[140:143], v128 offset:20480
	ds_read_b128 v[144:147], v128 offset:22528
	ds_read_b128 v[104:107], v130
	ds_read_b128 v[108:111], v130 offset:2048
	ds_read_b128 v[124:127], v130 offset:4096
	ds_read_b128 v[132:135], v130 offset:6144
	v_mov_b32_e32 v161, v1
	v_mov_b32_e32 v117, v1
	v_mov_b32_e32 v177, v1
	v_mov_b32_e32 v137, v1
	v_mov_b32_e32 v179, v1
	v_mov_b32_e32 v175, v1
	v_mov_b32_e32 v181, v1
	v_lshl_add_u64 v[186:187], v[0:1], 1, s[38:39]
	v_lshl_add_u64 v[188:189], v[160:161], 1, s[42:43]
	v_lshl_add_u64 v[116:117], v[116:117], 1, s[38:39]
	v_lshl_add_u64 v[176:177], v[176:177], 1, s[42:43]
	v_lshl_add_u64 v[136:137], v[136:137], 1, s[38:39]
	v_lshl_add_u64 v[178:179], v[178:179], 1, s[42:43]
	v_lshl_add_u64 v[174:175], v[174:175], 1, s[38:39]
	v_lshl_add_u64 v[180:181], v[180:181], 1, s[42:43]
	s_waitcnt lgkmcnt(3)
	v_mfma_f32_16x16x32_bf16 v[148:151], v[100:103], v[104:107], v[34:37]
	s_nop 2
	global_load_dwordx4 v[34:37], v[186:187], off
	v_mfma_f32_16x16x32_bf16 v[94:97], v[112:115], v[104:107], v[94:97]
	ds_read_b128 v[152:155], v129
	v_mfma_f32_16x16x32_bf16 v[156:159], v[140:143], v[104:107], v[38:41]
	s_nop 2
	global_load_dwordx4 v[38:41], v[188:189], off
	v_mfma_f32_16x16x32_bf16 v[90:93], v[144:147], v[104:107], v[90:93]
	ds_read_b128 v[104:107], v129 offset:2048
	s_waitcnt lgkmcnt(4)
	v_mfma_f32_16x16x32_bf16 v[160:163], v[100:103], v[108:111], v[42:45]
	s_nop 2
	global_load_dwordx4 v[42:45], v[116:117], off
	v_mfma_f32_16x16x32_bf16 v[86:89], v[112:115], v[108:111], v[86:89]
	ds_read_b128 v[164:167], v129 offset:4096
	v_mfma_f32_16x16x32_bf16 v[194:197], v[140:143], v[108:111], v[46:49]
	s_nop 2
	global_load_dwordx4 v[46:49], v[176:177], off
	v_mfma_f32_16x16x32_bf16 v[82:85], v[144:147], v[108:111], v[82:85]
	ds_read_b128 v[108:111], v129 offset:6144
	s_waitcnt lgkmcnt(5)
	v_mfma_f32_16x16x32_bf16 v[198:201], v[100:103], v[124:127], v[50:53]
	s_nop 2
	global_load_dwordx4 v[50:53], v[136:137], off
	v_mfma_f32_16x16x32_bf16 v[78:81], v[112:115], v[124:127], v[78:81]
	ds_read_b128 v[202:205], v131 offset:16384
	v_mfma_f32_16x16x32_bf16 v[206:209], v[140:143], v[124:127], v[54:57]
	s_nop 2
	global_load_dwordx4 v[54:57], v[178:179], off
	v_mfma_f32_16x16x32_bf16 v[70:73], v[144:147], v[124:127], v[70:73]
	ds_read_b128 v[124:127], v131 offset:18432
	s_waitcnt lgkmcnt(6)
	v_mfma_f32_16x16x32_bf16 v[100:103], v[100:103], v[132:135], v[58:61]
	s_nop 2
	global_load_dwordx4 v[58:61], v[174:175], off
	v_mfma_f32_16x16x32_bf16 v[66:69], v[112:115], v[132:135], v[66:69]
	ds_read_b128 v[112:115], v131 offset:20480
	v_mfma_f32_16x16x32_bf16 v[140:143], v[140:143], v[132:135], v[62:65]
	s_nop 2
	global_load_dwordx4 v[62:65], v[180:181], off
	v_mfma_f32_16x16x32_bf16 v[74:77], v[144:147], v[132:135], v[74:77]
	ds_read_b128 v[132:135], v131 offset:22528
	s_waitcnt lgkmcnt(3)
	v_mfma_f32_16x16x32_bf16 v[144:147], v[202:205], v[152:155], v[148:151]
	s_waitcnt vmcnt(15)
	ds_write_b128 v123, v[2:5] offset:32768
	s_waitcnt lgkmcnt(3)
	v_mfma_f32_16x16x32_bf16 v[94:97], v[124:127], v[152:155], v[94:97]
	s_waitcnt lgkmcnt(2)
	v_mfma_f32_16x16x32_bf16 v[148:151], v[112:115], v[152:155], v[156:159]
	s_waitcnt vmcnt(14)
	ds_write_b128 v99, v[6:9] offset:49152
	s_waitcnt lgkmcnt(2)
	v_mfma_f32_16x16x32_bf16 v[90:93], v[132:135], v[152:155], v[90:93]
	v_mfma_f32_16x16x32_bf16 v[152:155], v[202:205], v[104:107], v[160:163]
	s_waitcnt vmcnt(13)
	ds_write_b128 v123, v[10:13] offset:36864
	v_mfma_f32_16x16x32_bf16 v[86:89], v[124:127], v[104:107], v[86:89]
	v_mfma_f32_16x16x32_bf16 v[156:159], v[112:115], v[104:107], v[194:197]
	s_waitcnt vmcnt(12)
	ds_write_b128 v99, v[14:17] offset:53248
	v_mfma_f32_16x16x32_bf16 v[82:85], v[132:135], v[104:107], v[82:85]
	v_mfma_f32_16x16x32_bf16 v[104:107], v[202:205], v[164:167], v[198:201]
	s_waitcnt vmcnt(11)
	ds_write_b128 v123, v[18:21] offset:40960
	v_mfma_f32_16x16x32_bf16 v[78:81], v[124:127], v[164:167], v[78:81]
	v_mfma_f32_16x16x32_bf16 v[160:163], v[112:115], v[164:167], v[206:209]
	s_waitcnt vmcnt(10)
	ds_write_b128 v99, v[22:25] offset:57344
	v_mfma_f32_16x16x32_bf16 v[70:73], v[132:135], v[164:167], v[70:73]
	v_mfma_f32_16x16x32_bf16 v[100:103], v[202:205], v[108:111], v[100:103]
	s_waitcnt vmcnt(9)
	ds_write_b128 v123, v[26:29] offset:45056
	v_mfma_f32_16x16x32_bf16 v[66:69], v[124:127], v[108:111], v[66:69]
	v_mfma_f32_16x16x32_bf16 v[112:115], v[112:115], v[108:111], v[140:143]
	s_waitcnt vmcnt(8)
	ds_write_b128 v99, v[30:33] offset:61440
	v_mfma_f32_16x16x32_bf16 v[74:77], v[132:135], v[108:111], v[74:77]
	s_setprio 0
	s_waitcnt lgkmcnt(0)
	s_barrier
	s_setprio 1
	ds_read_b128 v[26:29], v128 offset:49152
	ds_read_b128 v[30:33], v128 offset:51200
	ds_read_b128 v[132:135], v128 offset:53248
	ds_read_b128 v[140:143], v128 offset:55296
	ds_read_b128 v[10:13], v130 offset:32768
	ds_read_b128 v[18:21], v130 offset:34816
	ds_read_b128 v[108:111], v130 offset:36864
	ds_read_b128 v[124:127], v130 offset:38912
	s_waitcnt lgkmcnt(3)
	v_mfma_f32_16x16x32_bf16 v[144:147], v[26:29], v[10:13], v[144:147]
	global_load_dwordx4 v[2:5], v[186:187], off offset:128
	v_mfma_f32_16x16x32_bf16 v[94:97], v[30:33], v[10:13], v[94:97]
	ds_read_b128 v[164:167], v129 offset:32768
	v_mfma_f32_16x16x32_bf16 v[148:151], v[132:135], v[10:13], v[148:151]
	global_load_dwordx4 v[6:9], v[188:189], off offset:128
	v_mfma_f32_16x16x32_bf16 v[90:93], v[140:143], v[10:13], v[90:93]
	ds_read_b128 v[194:197], v129 offset:34816
	s_waitcnt lgkmcnt(4)
	v_mfma_f32_16x16x32_bf16 v[152:155], v[26:29], v[18:21], v[152:155]
	global_load_dwordx4 v[10:13], v[116:117], off offset:128
	v_mfma_f32_16x16x32_bf16 v[86:89], v[30:33], v[18:21], v[86:89]
	ds_read_b128 v[198:201], v129 offset:36864
	v_mfma_f32_16x16x32_bf16 v[156:159], v[132:135], v[18:21], v[156:159]
	global_load_dwordx4 v[14:17], v[176:177], off offset:128
	v_mfma_f32_16x16x32_bf16 v[82:85], v[140:143], v[18:21], v[82:85]
	ds_read_b128 v[202:205], v129 offset:38912
	s_waitcnt lgkmcnt(5)
	v_mfma_f32_16x16x32_bf16 v[104:107], v[26:29], v[108:111], v[104:107]
	global_load_dwordx4 v[18:21], v[136:137], off offset:128
	v_mfma_f32_16x16x32_bf16 v[78:81], v[30:33], v[108:111], v[78:81]
	ds_read_b128 v[206:209], v131 offset:49152
	v_mfma_f32_16x16x32_bf16 v[160:163], v[132:135], v[108:111], v[160:163]
	global_load_dwordx4 v[22:25], v[178:179], off offset:128
	v_mfma_f32_16x16x32_bf16 v[70:73], v[140:143], v[108:111], v[70:73]
	ds_read_b128 v[108:111], v131 offset:51200
	s_waitcnt lgkmcnt(6)
	v_mfma_f32_16x16x32_bf16 v[100:103], v[26:29], v[124:127], v[100:103]
	global_load_dwordx4 v[26:29], v[174:175], off offset:128
	v_mfma_f32_16x16x32_bf16 v[66:69], v[30:33], v[124:127], v[66:69]
	ds_read_b128 v[210:213], v131 offset:53248
	v_mfma_f32_16x16x32_bf16 v[112:115], v[132:135], v[124:127], v[112:115]
	global_load_dwordx4 v[30:33], v[180:181], off offset:128
	v_mfma_f32_16x16x32_bf16 v[124:127], v[140:143], v[124:127], v[74:77]
	ds_read_b128 v[128:131], v131 offset:55296
	s_waitcnt lgkmcnt(3)
	v_mfma_f32_16x16x32_bf16 v[132:135], v[206:209], v[164:167], v[144:147]
	s_waitcnt lgkmcnt(2)
	v_mfma_f32_16x16x32_bf16 v[140:143], v[108:111], v[164:167], v[94:97]
	s_waitcnt lgkmcnt(1)
	v_mfma_f32_16x16x32_bf16 v[144:147], v[210:213], v[164:167], v[148:151]
	s_waitcnt lgkmcnt(0)
	v_mfma_f32_16x16x32_bf16 v[148:151], v[128:131], v[164:167], v[90:93]
	v_mfma_f32_16x16x32_bf16 v[152:155], v[206:209], v[194:197], v[152:155]
	v_mfma_f32_16x16x32_bf16 v[164:167], v[108:111], v[194:197], v[86:89]
	v_mfma_f32_16x16x32_bf16 v[156:159], v[210:213], v[194:197], v[156:159]
	v_mfma_f32_16x16x32_bf16 v[194:197], v[128:131], v[194:197], v[82:85]
	v_mfma_f32_16x16x32_bf16 v[94:97], v[206:209], v[198:201], v[104:107]
	v_mfma_f32_16x16x32_bf16 v[86:89], v[108:111], v[198:201], v[78:81]
	v_mfma_f32_16x16x32_bf16 v[90:93], v[210:213], v[198:201], v[160:163]
	v_mfma_f32_16x16x32_bf16 v[82:85], v[128:131], v[198:201], v[70:73]
	v_mfma_f32_16x16x32_bf16 v[74:77], v[206:209], v[202:205], v[100:103]
	v_mfma_f32_16x16x32_bf16 v[66:69], v[108:111], v[202:205], v[66:69]
	v_mfma_f32_16x16x32_bf16 v[70:73], v[210:213], v[202:205], v[112:115]
	v_mfma_f32_16x16x32_bf16 v[78:81], v[128:131], v[202:205], v[124:127]
	s_setprio 0
	v_mul_f32_e32 v0, 0xbfb8aa3b, v132
	v_exp_f32_e32 v0, v0
	v_mul_f32_e32 v99, 0xbfb8aa3b, v133
	v_exp_f32_e32 v99, v99
	v_mul_f32_e32 v101, 0xbfb8aa3b, v135
	v_add_f32_e32 v0, 1.0, v0
	v_rcp_f32_e32 v100, v0
	v_add_f32_e32 v0, 1.0, v99
	v_mul_f32_e32 v99, 0xbfb8aa3b, v134
	v_exp_f32_e32 v99, v99
	v_exp_f32_e32 v103, v101
	v_rcp_f32_e32 v101, v0
	v_mul_f32_e32 v108, 0xbfb8aa3b, v152
	v_add_f32_e32 v0, 1.0, v99
	v_mul_f32_e32 v99, 0xbfb8aa3b, v140
	v_rcp_f32_e32 v102, v0
	v_add_f32_e32 v0, 1.0, v103
	v_exp_f32_e32 v99, v99
	v_mul_f32_e32 v103, 0xbfb8aa3b, v141
	v_exp_f32_e32 v105, v103
	v_rcp_f32_e32 v103, v0
	v_add_f32_e32 v0, 1.0, v99
	v_mul_f32_e32 v99, 0xbfb8aa3b, v142
	v_rcp_f32_e32 v104, v0
	v_add_f32_e32 v0, 1.0, v105
	v_exp_f32_e32 v99, v99
	v_mul_f32_e32 v105, 0xbfb8aa3b, v143
	v_exp_f32_e32 v107, v105
	v_rcp_f32_e32 v105, v0
	v_add_f32_e32 v0, 1.0, v99
	v_rcp_f32_e32 v106, v0
	v_add_f32_e32 v0, 1.0, v107
	v_rcp_f32_e32 v107, v0
	v_pk_mul_f32 v[100:101], v[132:133], v[100:101]
	v_pk_mul_f32 v[102:103], v[134:135], v[102:103]
	v_pk_mul_f32 v[100:101], v[144:145], v[100:101]
	v_pk_mul_f32 v[102:103], v[146:147], v[102:103]
	v_cvt_pk_bf16_f32 v100, v100, v101
	v_cvt_pk_bf16_f32 v101, v102, v103
	v_pk_mul_f32 v[102:103], v[140:141], v[104:105]
	v_pk_mul_f32 v[104:105], v[142:143], v[106:107]
	v_pk_mul_f32 v[102:103], v[148:149], v[102:103]
	v_pk_mul_f32 v[104:105], v[150:151], v[104:105]
	v_add_u32_e32 v0, s4, v118
	v_cvt_pk_bf16_f32 v102, v102, v103
	v_cvt_pk_bf16_f32 v103, v104, v105
	v_mov_b64_e32 v[104:105], s[44:45]
	v_mad_i64_i32 v[106:107], s[14:15], v0, s20, v[104:105]
	v_or_b32_e32 v0, s5, v119
	v_mul_f32_e32 v109, 0xbfb8aa3b, v153
	v_lshl_add_u64 v[106:107], v[106:107], 0, v[0:1]
	v_mov_b32_e32 v99, v1
	v_exp_f32_e32 v108, v108
	v_exp_f32_e32 v109, v109
	v_lshl_add_u64 v[106:107], v[106:107], 0, v[98:99]
	s_barrier
	global_store_dwordx4 v[106:107], v[100:103], off
	v_mul_f32_e32 v106, 0xbfb8aa3b, v164
	v_mul_f32_e32 v107, 0xbfb8aa3b, v165
	v_mul_f32_e32 v102, 0xbfb8aa3b, v154
	v_mul_f32_e32 v103, 0xbfb8aa3b, v155
	v_exp_f32_e32 v102, v102
	v_exp_f32_e32 v103, v103
	v_add_f32_e32 v100, 1.0, v108
	v_add_f32_e32 v101, 1.0, v109
	v_mul_f32_e32 v108, 0xbfb8aa3b, v166
	v_mul_f32_e32 v109, 0xbfb8aa3b, v167
	v_exp_f32_e32 v106, v106
	v_exp_f32_e32 v107, v107
	v_exp_f32_e32 v108, v108
	v_exp_f32_e32 v109, v109
	v_add_f32_e32 v102, 1.0, v102
	v_add_f32_e32 v103, 1.0, v103
	v_rcp_f32_e32 v100, v100
	v_rcp_f32_e32 v101, v101
	v_rcp_f32_e32 v102, v102
	v_rcp_f32_e32 v103, v103
	v_add_f32_e32 v106, 1.0, v106
	v_add_f32_e32 v107, 1.0, v107
	v_add_f32_e32 v108, 1.0, v108
	v_add_f32_e32 v109, 1.0, v109
	v_rcp_f32_e32 v106, v106
	v_rcp_f32_e32 v107, v107
	v_rcp_f32_e32 v108, v108
	v_rcp_f32_e32 v109, v109
	v_pk_mul_f32 v[100:101], v[152:153], v[100:101]
	v_pk_mul_f32 v[102:103], v[154:155], v[102:103]
	v_pk_mul_f32 v[100:101], v[156:157], v[100:101]
	v_pk_mul_f32 v[102:103], v[158:159], v[102:103]
	v_cvt_pk_bf16_f32 v100, v100, v101
	v_cvt_pk_bf16_f32 v101, v102, v103
	v_pk_mul_f32 v[102:103], v[164:165], v[106:107]
	v_pk_mul_f32 v[106:107], v[166:167], v[108:109]
	v_add_u32_e32 v110, s4, v120
	v_pk_mul_f32 v[102:103], v[194:195], v[102:103]
	v_pk_mul_f32 v[106:107], v[196:197], v[106:107]
	v_cvt_pk_bf16_f32 v102, v102, v103
	v_cvt_pk_bf16_f32 v103, v106, v107
	v_mad_i64_i32 v[106:107], s[14:15], v110, s20, v[104:105]
	v_mul_f32_e32 v108, 0xbfb8aa3b, v94
	v_mul_f32_e32 v109, 0xbfb8aa3b, v95
	v_lshl_add_u64 v[106:107], v[106:107], 0, v[0:1]
	v_exp_f32_e32 v108, v108
	v_exp_f32_e32 v109, v109
	v_lshl_add_u64 v[106:107], v[106:107], 0, v[98:99]
	global_store_dwordx4 v[106:107], v[100:103], off
	v_mul_f32_e32 v106, 0xbfb8aa3b, v86
	v_mul_f32_e32 v107, 0xbfb8aa3b, v87
	v_mul_f32_e32 v102, 0xbfb8aa3b, v96
	v_mul_f32_e32 v103, 0xbfb8aa3b, v97
	v_exp_f32_e32 v102, v102
	v_exp_f32_e32 v103, v103
	v_exp_f32_e32 v106, v106
	v_exp_f32_e32 v107, v107
	v_add_f32_e32 v100, 1.0, v108
	v_add_f32_e32 v101, 1.0, v109
	v_mul_f32_e32 v108, 0xbfb8aa3b, v88
	v_mul_f32_e32 v109, 0xbfb8aa3b, v89
	v_exp_f32_e32 v108, v108
	v_exp_f32_e32 v109, v109
	v_rcp_f32_e32 v100, v100
	v_rcp_f32_e32 v101, v101
	v_add_f32_e32 v102, 1.0, v102
	v_add_f32_e32 v103, 1.0, v103
	v_add_f32_e32 v106, 1.0, v106
	v_add_f32_e32 v107, 1.0, v107
	v_rcp_f32_e32 v102, v102
	v_rcp_f32_e32 v103, v103
	v_rcp_f32_e32 v106, v106
	v_rcp_f32_e32 v107, v107
	v_add_f32_e32 v108, 1.0, v108
	v_add_f32_e32 v109, 1.0, v109
	v_rcp_f32_e32 v108, v108
	v_rcp_f32_e32 v109, v109
	v_pk_mul_f32 v[94:95], v[94:95], v[100:101]
	v_pk_mul_f32 v[86:87], v[86:87], v[106:107]
	v_pk_mul_f32 v[90:91], v[90:91], v[94:95]
	v_pk_mul_f32 v[94:95], v[96:97], v[102:103]
	v_pk_mul_f32 v[82:83], v[82:83], v[86:87]
	v_pk_mul_f32 v[92:93], v[92:93], v[94:95]
	v_cvt_pk_bf16_f32 v90, v90, v91
	v_cvt_pk_bf16_f32 v91, v92, v93
	v_cvt_pk_bf16_f32 v92, v82, v83
	v_pk_mul_f32 v[82:83], v[88:89], v[108:109]
	v_add_u32_e32 v110, s4, v121
	v_pk_mul_f32 v[82:83], v[84:85], v[82:83]
	v_mul_f32_e32 v84, 0xbfb8aa3b, v74
	v_mul_f32_e32 v85, 0xbfb8aa3b, v75
	v_exp_f32_e32 v84, v84
	v_exp_f32_e32 v85, v85
	v_cvt_pk_bf16_f32 v93, v82, v83
	v_mad_i64_i32 v[82:83], s[14:15], v110, s20, v[104:105]
	v_lshl_add_u64 v[82:83], v[82:83], 0, v[0:1]
	v_lshl_add_u64 v[82:83], v[82:83], 0, v[98:99]
	global_store_dwordx4 v[82:83], v[90:93], off
	v_add_f32_e32 v82, 1.0, v84
	v_add_f32_e32 v83, 1.0, v85
	v_mul_f32_e32 v84, 0xbfb8aa3b, v76
	v_mul_f32_e32 v85, 0xbfb8aa3b, v77
	v_mul_f32_e32 v86, 0xbfb8aa3b, v66
	v_mul_f32_e32 v87, 0xbfb8aa3b, v67
	v_exp_f32_e32 v84, v84
	v_exp_f32_e32 v85, v85
	v_exp_f32_e32 v86, v86
	v_exp_f32_e32 v87, v87
	v_mul_f32_e32 v88, 0xbfb8aa3b, v68
	v_mul_f32_e32 v89, 0xbfb8aa3b, v69
	v_exp_f32_e32 v88, v88
	v_exp_f32_e32 v89, v89
	v_rcp_f32_e32 v82, v82
	v_rcp_f32_e32 v83, v83
	v_add_f32_e32 v84, 1.0, v84
	v_add_f32_e32 v85, 1.0, v85
	v_add_f32_e32 v86, 1.0, v86
	v_add_f32_e32 v87, 1.0, v87
	v_rcp_f32_e32 v84, v84
	v_rcp_f32_e32 v85, v85
	v_rcp_f32_e32 v86, v86
	v_rcp_f32_e32 v87, v87
	v_add_f32_e32 v88, 1.0, v88
	v_add_f32_e32 v89, 1.0, v89
	v_rcp_f32_e32 v88, v88
	v_rcp_f32_e32 v89, v89
	v_pk_mul_f32 v[74:75], v[74:75], v[82:83]
	v_pk_mul_f32 v[66:67], v[66:67], v[86:87]
	v_pk_mul_f32 v[70:71], v[70:71], v[74:75]
	v_pk_mul_f32 v[74:75], v[76:77], v[84:85]
	v_pk_mul_f32 v[66:67], v[78:79], v[66:67]
	v_pk_mul_f32 v[72:73], v[72:73], v[74:75]
	v_cvt_pk_bf16_f32 v70, v70, v71
	v_cvt_pk_bf16_f32 v71, v72, v73
	v_cvt_pk_bf16_f32 v72, v66, v67
	v_pk_mul_f32 v[66:67], v[68:69], v[88:89]
	v_add_u32_e32 v90, s4, v122
	v_pk_mul_f32 v[66:67], v[80:81], v[66:67]
	s_nop 0
	v_cvt_pk_bf16_f32 v73, v66, v67
	v_mad_i64_i32 v[66:67], s[4:5], v90, s20, v[104:105]
	v_lshl_add_u64 v[66:67], v[66:67], 0, v[0:1]
	v_lshl_add_u64 v[66:67], v[66:67], 0, v[98:99]
	global_store_dwordx4 v[66:67], v[70:73], off
	s_cbranch_scc0 .LBB0_135

.LBB0_156:
	v_mov_b32_e32 v67, v169
	s_mov_b32 s11, s5
	v_lshrrev_b32_e32 v69, 4, v67
	v_ashrrev_i32_e32 v71, 3, v67
	v_lshrrev_b32_e32 v77, 1, v67
	v_and_b32_e32 v80, 4, v69
	v_and_b32_e32 v81, 3, v71
	v_and_b32_e32 v73, 7, v67
	v_xor_b32_e32 v75, v71, v67
	v_and_b32_e32 v77, 16, v77
	v_and_b32_e32 v79, 8, v69
	v_or_b32_e32 v82, v80, v81
	v_lshlrev_b32_e32 v75, 4, v75
	v_or3_b32 v77, v77, v79, v82
	v_bitop3_b32 v79, v80, v73, v81 bitop3:0x36
	v_lshlrev_b32_e32 v71, 7, v71
	v_lshlrev_b32_e32 v79, 4, v79
	v_and_or_b32 v117, v75, s24, v71
	v_lshl_or_b32 v116, v77, 7, v79
	s_waitcnt vmcnt(15)
	ds_write_b128 v117, v[34:37]
	s_waitcnt vmcnt(13)
	ds_write_b128 v116, v[38:41] offset:16384
	s_waitcnt vmcnt(11)
	ds_write_b128 v117, v[42:45] offset:4096
	s_waitcnt vmcnt(9)
	ds_write_b128 v116, v[46:49] offset:20480
	s_waitcnt vmcnt(7)
	ds_write_b128 v117, v[50:53] offset:8192
	s_waitcnt vmcnt(5)
	ds_write_b128 v116, v[54:57] offset:24576
	s_waitcnt vmcnt(3)
	ds_write_b128 v117, v[58:61] offset:12288
	s_waitcnt vmcnt(1)
	ds_write_b128 v116, v[62:65] offset:28672
	v_lshlrev_b32_e32 v34, 7, v67
	v_and_b32_e32 v35, 0x780, v34
	v_and_b32_e32 v118, 0x2780, v34
	v_bitop3_b32 v34, v69, v73, 3 bitop3:0x6c
	v_bfe_u32 v77, v67, 4, 2
	v_lshlrev_b32_e32 v119, 4, v34
	v_lshlrev_b32_e32 v34, 6, v67
	v_mov_b32_e32 v75, v1
	v_and_or_b32 v120, v34, s30, v35
	v_bitop3_b32 v34, v77, v73, 4 bitop3:0x36
	v_mov_b32_e32 v73, v1
	v_mov_b32_e32 v67, v1
	v_mov_b32_e32 v69, v1
	v_mov_b32_e32 v77, v1
	v_mov_b32_e32 v71, v1
	v_mov_b32_e32 v79, v1
	v_lshl_add_u64 v[100:101], v[74:75], 1, s[28:29]
	v_mov_b32_e32 v74, 0
	s_mov_b32 s10, s9
	s_mov_b32 s4, s8
	v_lshlrev_b32_e32 v121, 4, v34
	v_lshl_add_u64 v[98:99], v[72:73], 1, s[28:29]
	v_lshl_add_u64 v[102:103], v[76:77], 1, s[28:29]
	v_lshl_add_u64 v[104:105], v[78:79], 1, s[28:29]
	v_lshlrev_b64 v[106:107], 1, v[0:1]
	v_lshlrev_b64 v[108:109], 1, v[66:67]
	v_lshlrev_b64 v[110:111], 1, v[68:69]
	v_lshlrev_b64 v[112:113], 1, v[70:71]
	s_mov_b32 s5, -2
	s_mov_b64 s[38:39], s[72:73]
	v_mov_b32_e32 v75, v74
	v_mov_b32_e32 v76, v74
	v_mov_b32_e32 v77, v74
	v_mov_b32_e32 v62, v74
	v_mov_b32_e32 v63, v74
	v_mov_b32_e32 v64, v74
	v_mov_b32_e32 v65, v74
	v_mov_b32_e32 v66, v74
	v_mov_b32_e32 v67, v74
	v_mov_b32_e32 v68, v74
	v_mov_b32_e32 v69, v74
	v_mov_b32_e32 v58, v74
	v_mov_b32_e32 v59, v74
	v_mov_b32_e32 v60, v74
	v_mov_b32_e32 v61, v74
	v_mov_b32_e32 v70, v74
	v_mov_b32_e32 v71, v74
	v_mov_b32_e32 v72, v74
	v_mov_b32_e32 v73, v74
	v_mov_b32_e32 v54, v74
	v_mov_b32_e32 v55, v74
	v_mov_b32_e32 v56, v74
	v_mov_b32_e32 v57, v74
	v_mov_b32_e32 v78, v74
	v_mov_b32_e32 v79, v74
	v_mov_b32_e32 v80, v74
	v_mov_b32_e32 v81, v74
	v_mov_b32_e32 v50, v74
	v_mov_b32_e32 v51, v74
	v_mov_b32_e32 v52, v74
	v_mov_b32_e32 v53, v74
	v_mov_b32_e32 v82, v74
	v_mov_b32_e32 v83, v74
	v_mov_b32_e32 v84, v74
	v_mov_b32_e32 v85, v74
	v_mov_b32_e32 v46, v74
	v_mov_b32_e32 v47, v74
	v_mov_b32_e32 v48, v74
	v_mov_b32_e32 v49, v74
	v_mov_b32_e32 v86, v74
	v_mov_b32_e32 v87, v74
	v_mov_b32_e32 v88, v74
	v_mov_b32_e32 v89, v74
	v_mov_b32_e32 v42, v74
	v_mov_b32_e32 v43, v74
	v_mov_b32_e32 v44, v74
	v_mov_b32_e32 v45, v74
	v_mov_b32_e32 v90, v74
	v_mov_b32_e32 v91, v74
	v_mov_b32_e32 v92, v74
	v_mov_b32_e32 v93, v74
	v_mov_b32_e32 v38, v74
	v_mov_b32_e32 v39, v74
	v_mov_b32_e32 v40, v74
	v_mov_b32_e32 v41, v74
	v_mov_b32_e32 v94, v74
	v_mov_b32_e32 v95, v74
	v_mov_b32_e32 v96, v74
	v_mov_b32_e32 v97, v74
	v_mov_b32_e32 v34, v74
	v_mov_b32_e32 v35, v74
	v_mov_b32_e32 v36, v74
	v_mov_b32_e32 v37, v74
	s_waitcnt lgkmcnt(0)
	s_barrier
	v_lshrrev_b32_e32 v222, 6, v169
	v_lshlrev_b32_e32 v222, 10, v222
	v_lshrrev_b32_e32 v223, 3, v169
	v_readfirstlane_b32 s100, v222
	v_and_b32_e32 v222, 3, v223
	v_bfe_u32 v224, v223, 4, 1
	v_lshl_or_b32 v222, v224, 2, v222
	v_bfe_u32 v224, v223, 2, 1
	v_lshl_or_b32 v222, v224, 3, v222
	v_bfe_u32 v224, v223, 3, 1
	v_lshl_or_b32 v222, v224, 4, v222
	v_sub_u32_e32 v222, v222, v223
	v_mul_i32_i24_e32 v222, 0x800, v222
	v_and_b32_e32 v223, 7, v223
	v_lshlrev_b32_e32 v223, 4, v223
	v_add_u32_e32 v210, 0xef11000, v106
	v_xor_b32_e32 v194, v210, v223
	v_mov_b32_e32 v211, v98
	v_add_u32_e32 v195, v211, v222
	v_xor_b32_e32 v195, v195, v223
	v_add_u32_e32 v212, 0xef11000, v108
	v_xor_b32_e32 v196, v212, v223
	v_mov_b32_e32 v213, v100
	v_add_u32_e32 v197, v213, v222
	v_xor_b32_e32 v197, v197, v223
	v_add_u32_e32 v218, 0xef11000, v110
	v_xor_b32_e32 v202, v218, v223
	v_mov_b32_e32 v219, v102
	v_add_u32_e32 v203, v219, v222
	v_xor_b32_e32 v203, v203, v223
	v_add_u32_e32 v220, 0xef11000, v112
	v_xor_b32_e32 v204, v220, v223
	v_mov_b32_e32 v221, v104
	v_add_u32_e32 v205, v221, v222
	v_xor_b32_e32 v205, v205, v223
.LBB0_157:
	s_setprio 1
	s_add_u32 s98, s38, s36
	s_addc_u32 s99, s39, 0
	s_add_u32 s98, s98, 0x80
	s_addc_u32 s99, s99, 0
	v_add_u32_e32 v122, v119, v118
	v_add_u32_e32 v124, v119, v120
	v_add_u32_e32 v123, v121, v120
	ds_read_b128 v[126:129], v122 offset:16384
	ds_read_b128 v[144:147], v122 offset:18432
	ds_read_b128 v[158:161], v122 offset:20480
	ds_read_b128 v[162:165], v122 offset:22528
	ds_read_b128 v[130:133], v124
	ds_read_b128 v[134:137], v124 offset:2048
	ds_read_b128 v[140:143], v124 offset:4096
	ds_read_b128 v[148:151], v124 offset:6144
	s_waitcnt lgkmcnt(3)
	v_mfma_f32_16x16x32_bf16 v[34:37], v[126:129], v[130:133], v[34:37]
	v_mfma_f32_16x16x32_bf16 v[94:97], v[144:147], v[130:133], v[94:97]
	ds_read_b128 v[198:201], v123
	v_mfma_f32_16x16x32_bf16 v[38:41], v[158:161], v[130:133], v[38:41]
	v_mfma_f32_16x16x32_bf16 v[90:93], v[162:165], v[130:133], v[90:93]
	ds_read_b128 v[206:209], v123 offset:2048
	s_waitcnt lgkmcnt(4)
	v_mfma_f32_16x16x32_bf16 v[42:45], v[126:129], v[134:137], v[42:45]
	v_mfma_f32_16x16x32_bf16 v[86:89], v[144:147], v[134:137], v[86:89]
	ds_read_b128 v[214:217], v123 offset:4096
	v_mfma_f32_16x16x32_bf16 v[46:49], v[158:161], v[134:137], v[46:49]
	v_mfma_f32_16x16x32_bf16 v[82:85], v[162:165], v[134:137], v[82:85]
	v_add_u32_e32 v130, v121, v118
	ds_read_b128 v[132:135], v123 offset:6144
	s_waitcnt lgkmcnt(5)
	v_mfma_f32_16x16x32_bf16 v[50:53], v[126:129], v[140:143], v[50:53]
	v_mfma_f32_16x16x32_bf16 v[78:81], v[144:147], v[140:143], v[78:81]
	ds_read_b128 v[226:229], v130 offset:16384
	v_mfma_f32_16x16x32_bf16 v[54:57], v[158:161], v[140:143], v[54:57]
	v_mfma_f32_16x16x32_bf16 v[70:73], v[162:165], v[140:143], v[70:73]
	ds_read_b128 v[140:143], v130 offset:18432
	s_waitcnt lgkmcnt(6)
	v_mfma_f32_16x16x32_bf16 v[58:61], v[126:129], v[148:151], v[58:61]
	v_mfma_f32_16x16x32_bf16 v[66:69], v[144:147], v[148:151], v[66:69]
	ds_read_b128 v[144:147], v130 offset:20480
	v_mfma_f32_16x16x32_bf16 v[62:65], v[158:161], v[148:151], v[62:65]
	v_mfma_f32_16x16x32_bf16 v[74:77], v[162:165], v[148:151], v[74:77]
	ds_read_b128 v[148:151], v130 offset:22528
	s_waitcnt lgkmcnt(3)
	v_mfma_f32_16x16x32_bf16 v[34:37], v[226:229], v[198:201], v[34:37]
	s_waitcnt vmcnt(7)
	ds_write_b128 v117, v[2:5] offset:32768
	s_waitcnt lgkmcnt(3)
	v_mfma_f32_16x16x32_bf16 v[94:97], v[140:143], v[198:201], v[94:97]
	s_waitcnt lgkmcnt(2)
	v_mfma_f32_16x16x32_bf16 v[38:41], v[144:147], v[198:201], v[38:41]
	s_waitcnt vmcnt(6)
	ds_write_b128 v116, v[6:9] offset:49152
	s_waitcnt lgkmcnt(2)
	v_mfma_f32_16x16x32_bf16 v[90:93], v[148:151], v[198:201], v[90:93]
	v_mfma_f32_16x16x32_bf16 v[42:45], v[226:229], v[206:209], v[42:45]
	s_waitcnt vmcnt(5)
	ds_write_b128 v117, v[10:13] offset:36864
	v_mfma_f32_16x16x32_bf16 v[86:89], v[140:143], v[206:209], v[86:89]
	v_mfma_f32_16x16x32_bf16 v[46:49], v[144:147], v[206:209], v[46:49]
	s_waitcnt vmcnt(4)
	ds_write_b128 v116, v[14:17] offset:53248
	v_mfma_f32_16x16x32_bf16 v[82:85], v[148:151], v[206:209], v[82:85]
	v_mfma_f32_16x16x32_bf16 v[50:53], v[226:229], v[214:217], v[50:53]
	s_waitcnt vmcnt(3)
	ds_write_b128 v117, v[18:21] offset:40960
	v_mfma_f32_16x16x32_bf16 v[78:81], v[140:143], v[214:217], v[78:81]
	v_mfma_f32_16x16x32_bf16 v[54:57], v[144:147], v[214:217], v[54:57]
	s_waitcnt vmcnt(2)
	ds_write_b128 v116, v[22:25] offset:57344
	v_mfma_f32_16x16x32_bf16 v[70:73], v[148:151], v[214:217], v[70:73]
	v_mfma_f32_16x16x32_bf16 v[58:61], v[226:229], v[132:135], v[58:61]
	s_waitcnt vmcnt(1)
	ds_write_b128 v117, v[26:29] offset:45056
	v_mfma_f32_16x16x32_bf16 v[66:69], v[140:143], v[132:135], v[66:69]
	v_mfma_f32_16x16x32_bf16 v[62:65], v[144:147], v[132:135], v[62:65]
	s_waitcnt vmcnt(0)
	ds_write_b128 v116, v[30:33] offset:61440
	v_mfma_f32_16x16x32_bf16 v[74:77], v[148:151], v[132:135], v[74:77]
	s_setprio 0
	s_waitcnt lgkmcnt(0)
	s_barrier
	s_setprio 1
	s_add_u32 s98, s98, 0x80
	s_addc_u32 s99, s99, 0
	ds_read_b128 v[26:29], v122 offset:49152
	ds_read_b128 v[30:33], v122 offset:51200
	ds_read_b128 v[144:147], v122 offset:53248
	ds_read_b128 v[148:151], v122 offset:55296
	ds_read_b128 v[10:13], v124 offset:32768
	ds_read_b128 v[18:21], v124 offset:34816
	ds_read_b128 v[132:135], v124 offset:36864
	ds_read_b128 v[140:143], v124 offset:38912
	s_add_u32 m0, s100, 0x0
	s_waitcnt lgkmcnt(3)
	v_mfma_f32_16x16x32_bf16 v[34:37], v[26:29], v[10:13], v[34:37]
	global_load_lds_dwordx4 v194, s[98:99]
	v_mfma_f32_16x16x32_bf16 v[94:97], v[30:33], v[10:13], v[94:97]
	ds_read_b128 v[162:165], v123 offset:32768
	s_add_u32 m0, s100, 0x4000
	v_mfma_f32_16x16x32_bf16 v[38:41], v[144:147], v[10:13], v[38:41]
	global_load_lds_dwordx4 v195, s[98:99]
	v_mfma_f32_16x16x32_bf16 v[90:93], v[148:151], v[10:13], v[90:93]
	ds_read_b128 v[198:201], v123 offset:34816
	s_add_u32 m0, s100, 0x1000
	s_waitcnt lgkmcnt(4)
	v_mfma_f32_16x16x32_bf16 v[42:45], v[26:29], v[18:21], v[42:45]
	global_load_lds_dwordx4 v196, s[98:99]
	v_mfma_f32_16x16x32_bf16 v[86:89], v[30:33], v[18:21], v[86:89]
	ds_read_b128 v[206:209], v123 offset:36864
	s_add_u32 m0, s100, 0x5000
	v_mfma_f32_16x16x32_bf16 v[46:49], v[144:147], v[18:21], v[46:49]
	global_load_lds_dwordx4 v197, s[98:99]
	v_mfma_f32_16x16x32_bf16 v[82:85], v[148:151], v[18:21], v[82:85]
	ds_read_b128 v[214:217], v123 offset:38912
	s_add_u32 m0, s100, 0x2000
	s_waitcnt lgkmcnt(5)
	v_mfma_f32_16x16x32_bf16 v[50:53], v[26:29], v[132:135], v[50:53]
	global_load_lds_dwordx4 v202, s[98:99]
	v_mfma_f32_16x16x32_bf16 v[78:81], v[30:33], v[132:135], v[78:81]
	ds_read_b128 v[226:229], v130 offset:49152
	s_add_u32 m0, s100, 0x6000
	v_mfma_f32_16x16x32_bf16 v[54:57], v[144:147], v[132:135], v[54:57]
	global_load_lds_dwordx4 v203, s[98:99]
	v_mfma_f32_16x16x32_bf16 v[70:73], v[148:151], v[132:135], v[70:73]
	ds_read_b128 v[132:135], v130 offset:51200
	s_add_u32 m0, s100, 0x3000
	s_waitcnt lgkmcnt(6)
	v_mfma_f32_16x16x32_bf16 v[58:61], v[26:29], v[140:143], v[58:61]
	global_load_lds_dwordx4 v204, s[98:99]
	v_mfma_f32_16x16x32_bf16 v[66:69], v[30:33], v[140:143], v[66:69]
	ds_read_b128 v[234:237], v130 offset:53248
	s_add_u32 m0, s100, 0x7000
	v_mfma_f32_16x16x32_bf16 v[62:65], v[144:147], v[140:143], v[62:65]
	global_load_lds_dwordx4 v205, s[98:99]
	v_mfma_f32_16x16x32_bf16 v[74:77], v[148:151], v[140:143], v[74:77]
	ds_read_b128 v[140:143], v130 offset:55296
	s_waitcnt lgkmcnt(3)
	v_mfma_f32_16x16x32_bf16 v[34:37], v[226:229], v[162:165], v[34:37]
	s_waitcnt lgkmcnt(2)
	v_mfma_f32_16x16x32_bf16 v[94:97], v[132:135], v[162:165], v[94:97]
	s_waitcnt lgkmcnt(1)
	v_mfma_f32_16x16x32_bf16 v[38:41], v[234:237], v[162:165], v[38:41]
	s_waitcnt lgkmcnt(0)
	v_mfma_f32_16x16x32_bf16 v[90:93], v[140:143], v[162:165], v[90:93]
	v_mfma_f32_16x16x32_bf16 v[42:45], v[226:229], v[198:201], v[42:45]
	v_mfma_f32_16x16x32_bf16 v[86:89], v[132:135], v[198:201], v[86:89]
	v_mfma_f32_16x16x32_bf16 v[46:49], v[234:237], v[198:201], v[46:49]
	v_mfma_f32_16x16x32_bf16 v[82:85], v[140:143], v[198:201], v[82:85]
	v_mfma_f32_16x16x32_bf16 v[50:53], v[226:229], v[206:209], v[50:53]
	v_mfma_f32_16x16x32_bf16 v[78:81], v[132:135], v[206:209], v[78:81]
	v_mfma_f32_16x16x32_bf16 v[54:57], v[234:237], v[206:209], v[54:57]
	v_mfma_f32_16x16x32_bf16 v[70:73], v[140:143], v[206:209], v[70:73]
	v_mfma_f32_16x16x32_bf16 v[58:61], v[226:229], v[214:217], v[58:61]
	v_mfma_f32_16x16x32_bf16 v[66:69], v[132:135], v[214:217], v[66:69]
	v_mfma_f32_16x16x32_bf16 v[62:65], v[234:237], v[214:217], v[62:65]
	v_mfma_f32_16x16x32_bf16 v[74:77], v[140:143], v[214:217], v[74:77]
	s_waitcnt vmcnt(0)
	s_setprio 0
	s_add_i32 s5, s5, 2
	s_add_u32 s38, s38, 0x100
	s_addc_u32 s39, s39, 0
	s_waitcnt lgkmcnt(0)
	s_barrier
.Lk3_mid_157:
	s_setprio 1
	s_add_u32 s98, s38, s36
	s_addc_u32 s99, s39, 0
	s_add_u32 s98, s98, 0x80
	s_addc_u32 s99, s99, 0
	v_add_u32_e32 v122, v119, v118
	v_add_u32_e32 v124, v119, v120
	v_add_u32_e32 v123, v121, v120
	ds_read_b128 v[126:129], v122 offset:16384
	ds_read_b128 v[144:147], v122 offset:18432
	ds_read_b128 v[158:161], v122 offset:20480
	ds_read_b128 v[162:165], v122 offset:22528
	ds_read_b128 v[130:133], v124
	ds_read_b128 v[134:137], v124 offset:2048
	ds_read_b128 v[140:143], v124 offset:4096
	ds_read_b128 v[148:151], v124 offset:6144
	s_add_u32 m0, s100, 0x8000
	s_waitcnt lgkmcnt(3)
	v_mfma_f32_16x16x32_bf16 v[34:37], v[126:129], v[130:133], v[34:37]
	global_load_lds_dwordx4 v194, s[98:99]
	v_mfma_f32_16x16x32_bf16 v[94:97], v[144:147], v[130:133], v[94:97]
	ds_read_b128 v[198:201], v123
	s_add_u32 m0, s100, 0xc000
	v_mfma_f32_16x16x32_bf16 v[38:41], v[158:161], v[130:133], v[38:41]
	global_load_lds_dwordx4 v195, s[98:99]
	v_mfma_f32_16x16x32_bf16 v[90:93], v[162:165], v[130:133], v[90:93]
	ds_read_b128 v[206:209], v123 offset:2048
	s_add_u32 m0, s100, 0x9000
	s_waitcnt lgkmcnt(4)
	v_mfma_f32_16x16x32_bf16 v[42:45], v[126:129], v[134:137], v[42:45]
	global_load_lds_dwordx4 v196, s[98:99]
	v_mfma_f32_16x16x32_bf16 v[86:89], v[144:147], v[134:137], v[86:89]
	ds_read_b128 v[214:217], v123 offset:4096
	s_add_u32 m0, s100, 0xd000
	v_mfma_f32_16x16x32_bf16 v[46:49], v[158:161], v[134:137], v[46:49]
	global_load_lds_dwordx4 v197, s[98:99]
	v_mfma_f32_16x16x32_bf16 v[82:85], v[162:165], v[134:137], v[82:85]
	v_add_u32_e32 v130, v121, v118
	ds_read_b128 v[132:135], v123 offset:6144
	s_add_u32 m0, s100, 0xa000
	s_waitcnt lgkmcnt(5)
	v_mfma_f32_16x16x32_bf16 v[50:53], v[126:129], v[140:143], v[50:53]
	global_load_lds_dwordx4 v202, s[98:99]
	v_mfma_f32_16x16x32_bf16 v[78:81], v[144:147], v[140:143], v[78:81]
	ds_read_b128 v[226:229], v130 offset:16384
	s_add_u32 m0, s100, 0xe000
	v_mfma_f32_16x16x32_bf16 v[54:57], v[158:161], v[140:143], v[54:57]
	global_load_lds_dwordx4 v203, s[98:99]
	v_mfma_f32_16x16x32_bf16 v[70:73], v[162:165], v[140:143], v[70:73]
	ds_read_b128 v[140:143], v130 offset:18432
	s_add_u32 m0, s100, 0xb000
	s_waitcnt lgkmcnt(6)
	v_mfma_f32_16x16x32_bf16 v[58:61], v[126:129], v[148:151], v[58:61]
	global_load_lds_dwordx4 v204, s[98:99]
	v_mfma_f32_16x16x32_bf16 v[66:69], v[144:147], v[148:151], v[66:69]
	ds_read_b128 v[144:147], v130 offset:20480
	s_add_u32 m0, s100, 0xf000
	v_mfma_f32_16x16x32_bf16 v[62:65], v[158:161], v[148:151], v[62:65]
	global_load_lds_dwordx4 v205, s[98:99]
	v_mfma_f32_16x16x32_bf16 v[74:77], v[162:165], v[148:151], v[74:77]
	ds_read_b128 v[148:151], v130 offset:22528
	s_waitcnt lgkmcnt(3)
	v_mfma_f32_16x16x32_bf16 v[34:37], v[226:229], v[198:201], v[34:37]
	s_waitcnt lgkmcnt(2)
	v_mfma_f32_16x16x32_bf16 v[94:97], v[140:143], v[198:201], v[94:97]
	s_waitcnt lgkmcnt(1)
	v_mfma_f32_16x16x32_bf16 v[38:41], v[144:147], v[198:201], v[38:41]
	s_waitcnt lgkmcnt(0)
	v_mfma_f32_16x16x32_bf16 v[90:93], v[148:151], v[198:201], v[90:93]
	v_mfma_f32_16x16x32_bf16 v[42:45], v[226:229], v[206:209], v[42:45]
	v_mfma_f32_16x16x32_bf16 v[86:89], v[140:143], v[206:209], v[86:89]
	v_mfma_f32_16x16x32_bf16 v[46:49], v[144:147], v[206:209], v[46:49]
	v_mfma_f32_16x16x32_bf16 v[82:85], v[148:151], v[206:209], v[82:85]
	v_mfma_f32_16x16x32_bf16 v[50:53], v[226:229], v[214:217], v[50:53]
	v_mfma_f32_16x16x32_bf16 v[78:81], v[140:143], v[214:217], v[78:81]
	v_mfma_f32_16x16x32_bf16 v[54:57], v[144:147], v[214:217], v[54:57]
	v_mfma_f32_16x16x32_bf16 v[70:73], v[148:151], v[214:217], v[70:73]
	v_mfma_f32_16x16x32_bf16 v[58:61], v[226:229], v[132:135], v[58:61]
	v_mfma_f32_16x16x32_bf16 v[66:69], v[140:143], v[132:135], v[66:69]
	v_mfma_f32_16x16x32_bf16 v[62:65], v[144:147], v[132:135], v[62:65]
	v_mfma_f32_16x16x32_bf16 v[74:77], v[148:151], v[132:135], v[74:77]
	s_waitcnt vmcnt(0)
	s_setprio 0
	s_waitcnt lgkmcnt(0)
	s_barrier
	s_setprio 1
	s_add_u32 s98, s98, 0x80
	s_addc_u32 s99, s99, 0
	ds_read_b128 v[26:29], v122 offset:49152
	ds_read_b128 v[30:33], v122 offset:51200
	ds_read_b128 v[144:147], v122 offset:53248
	ds_read_b128 v[148:151], v122 offset:55296
	ds_read_b128 v[10:13], v124 offset:32768
	ds_read_b128 v[18:21], v124 offset:34816
	ds_read_b128 v[132:135], v124 offset:36864
	ds_read_b128 v[140:143], v124 offset:38912
	s_add_u32 m0, s100, 0x0
	s_waitcnt lgkmcnt(3)
	v_mfma_f32_16x16x32_bf16 v[34:37], v[26:29], v[10:13], v[34:37]
	global_load_lds_dwordx4 v194, s[98:99]
	v_mfma_f32_16x16x32_bf16 v[94:97], v[30:33], v[10:13], v[94:97]
	ds_read_b128 v[162:165], v123 offset:32768
	s_add_u32 m0, s100, 0x4000
	v_mfma_f32_16x16x32_bf16 v[38:41], v[144:147], v[10:13], v[38:41]
	global_load_lds_dwordx4 v195, s[98:99]
	v_mfma_f32_16x16x32_bf16 v[90:93], v[148:151], v[10:13], v[90:93]
	ds_read_b128 v[198:201], v123 offset:34816
	s_add_u32 m0, s100, 0x1000
	s_waitcnt lgkmcnt(4)
	v_mfma_f32_16x16x32_bf16 v[42:45], v[26:29], v[18:21], v[42:45]
	global_load_lds_dwordx4 v196, s[98:99]
	v_mfma_f32_16x16x32_bf16 v[86:89], v[30:33], v[18:21], v[86:89]
	ds_read_b128 v[206:209], v123 offset:36864
	s_add_u32 m0, s100, 0x5000
	v_mfma_f32_16x16x32_bf16 v[46:49], v[144:147], v[18:21], v[46:49]
	global_load_lds_dwordx4 v197, s[98:99]
	v_mfma_f32_16x16x32_bf16 v[82:85], v[148:151], v[18:21], v[82:85]
	ds_read_b128 v[214:217], v123 offset:38912
	s_add_u32 m0, s100, 0x2000
	s_waitcnt lgkmcnt(5)
	v_mfma_f32_16x16x32_bf16 v[50:53], v[26:29], v[132:135], v[50:53]
	global_load_lds_dwordx4 v202, s[98:99]
	v_mfma_f32_16x16x32_bf16 v[78:81], v[30:33], v[132:135], v[78:81]
	ds_read_b128 v[226:229], v130 offset:49152
	s_add_u32 m0, s100, 0x6000
	v_mfma_f32_16x16x32_bf16 v[54:57], v[144:147], v[132:135], v[54:57]
	global_load_lds_dwordx4 v203, s[98:99]
	v_mfma_f32_16x16x32_bf16 v[70:73], v[148:151], v[132:135], v[70:73]
	ds_read_b128 v[132:135], v130 offset:51200
	s_add_u32 m0, s100, 0x3000
	s_waitcnt lgkmcnt(6)
	v_mfma_f32_16x16x32_bf16 v[58:61], v[26:29], v[140:143], v[58:61]
	global_load_lds_dwordx4 v204, s[98:99]
	v_mfma_f32_16x16x32_bf16 v[66:69], v[30:33], v[140:143], v[66:69]
	ds_read_b128 v[234:237], v130 offset:53248
	s_add_u32 m0, s100, 0x7000
	v_mfma_f32_16x16x32_bf16 v[62:65], v[144:147], v[140:143], v[62:65]
	global_load_lds_dwordx4 v205, s[98:99]
	v_mfma_f32_16x16x32_bf16 v[74:77], v[148:151], v[140:143], v[74:77]
	ds_read_b128 v[140:143], v130 offset:55296
	s_waitcnt lgkmcnt(3)
	v_mfma_f32_16x16x32_bf16 v[34:37], v[226:229], v[162:165], v[34:37]
	s_waitcnt lgkmcnt(2)
	v_mfma_f32_16x16x32_bf16 v[94:97], v[132:135], v[162:165], v[94:97]
	s_waitcnt lgkmcnt(1)
	v_mfma_f32_16x16x32_bf16 v[38:41], v[234:237], v[162:165], v[38:41]
	s_waitcnt lgkmcnt(0)
	v_mfma_f32_16x16x32_bf16 v[90:93], v[140:143], v[162:165], v[90:93]
	v_mfma_f32_16x16x32_bf16 v[42:45], v[226:229], v[198:201], v[42:45]
	v_mfma_f32_16x16x32_bf16 v[86:89], v[132:135], v[198:201], v[86:89]
	v_mfma_f32_16x16x32_bf16 v[46:49], v[234:237], v[198:201], v[46:49]
	v_mfma_f32_16x16x32_bf16 v[82:85], v[140:143], v[198:201], v[82:85]
	v_mfma_f32_16x16x32_bf16 v[50:53], v[226:229], v[206:209], v[50:53]
	v_mfma_f32_16x16x32_bf16 v[78:81], v[132:135], v[206:209], v[78:81]
	v_mfma_f32_16x16x32_bf16 v[54:57], v[234:237], v[206:209], v[54:57]
	v_mfma_f32_16x16x32_bf16 v[70:73], v[140:143], v[206:209], v[70:73]
	v_mfma_f32_16x16x32_bf16 v[58:61], v[226:229], v[214:217], v[58:61]
	v_mfma_f32_16x16x32_bf16 v[66:69], v[132:135], v[214:217], v[66:69]
	v_mfma_f32_16x16x32_bf16 v[62:65], v[234:237], v[214:217], v[62:65]
	v_mfma_f32_16x16x32_bf16 v[74:77], v[140:143], v[214:217], v[74:77]
	s_waitcnt vmcnt(0)
	s_setprio 0
	s_add_i32 s5, s5, 2
	s_add_u32 s38, s38, 0x100
	s_addc_u32 s39, s39, 0
	s_cmp_lt_u32 s5, 10
	s_waitcnt lgkmcnt(0)
	s_barrier
	s_cbranch_scc1 .Lk3_mid_157
	s_setprio 1
	s_add_u32 s98, s38, s36
	s_addc_u32 s99, s39, 0
	s_add_u32 s98, s98, 0x80
	s_addc_u32 s99, s99, 0
	v_add_u32_e32 v122, v119, v118
	v_add_u32_e32 v124, v119, v120
	v_add_u32_e32 v123, v121, v120
	ds_read_b128 v[126:129], v122 offset:16384
	ds_read_b128 v[144:147], v122 offset:18432
	ds_read_b128 v[158:161], v122 offset:20480
	ds_read_b128 v[162:165], v122 offset:22528
	ds_read_b128 v[130:133], v124
	ds_read_b128 v[134:137], v124 offset:2048
	ds_read_b128 v[140:143], v124 offset:4096
	ds_read_b128 v[148:151], v124 offset:6144
	s_add_u32 m0, s100, 0x8000
	s_waitcnt lgkmcnt(3)
	v_mfma_f32_16x16x32_bf16 v[34:37], v[126:129], v[130:133], v[34:37]
	global_load_lds_dwordx4 v194, s[98:99]
	v_mfma_f32_16x16x32_bf16 v[94:97], v[144:147], v[130:133], v[94:97]
	ds_read_b128 v[198:201], v123
	s_add_u32 m0, s100, 0xc000
	v_mfma_f32_16x16x32_bf16 v[38:41], v[158:161], v[130:133], v[38:41]
	global_load_lds_dwordx4 v195, s[98:99]
	v_mfma_f32_16x16x32_bf16 v[90:93], v[162:165], v[130:133], v[90:93]
	ds_read_b128 v[206:209], v123 offset:2048
	s_add_u32 m0, s100, 0x9000
	s_waitcnt lgkmcnt(4)
	v_mfma_f32_16x16x32_bf16 v[42:45], v[126:129], v[134:137], v[42:45]
	global_load_lds_dwordx4 v196, s[98:99]
	v_mfma_f32_16x16x32_bf16 v[86:89], v[144:147], v[134:137], v[86:89]
	ds_read_b128 v[214:217], v123 offset:4096
	s_add_u32 m0, s100, 0xd000
	v_mfma_f32_16x16x32_bf16 v[46:49], v[158:161], v[134:137], v[46:49]
	global_load_lds_dwordx4 v197, s[98:99]
	v_mfma_f32_16x16x32_bf16 v[82:85], v[162:165], v[134:137], v[82:85]
	v_add_u32_e32 v130, v121, v118
	ds_read_b128 v[132:135], v123 offset:6144
	s_add_u32 m0, s100, 0xa000
	s_waitcnt lgkmcnt(5)
	v_mfma_f32_16x16x32_bf16 v[50:53], v[126:129], v[140:143], v[50:53]
	global_load_lds_dwordx4 v202, s[98:99]
	v_mfma_f32_16x16x32_bf16 v[78:81], v[144:147], v[140:143], v[78:81]
	ds_read_b128 v[226:229], v130 offset:16384
	s_add_u32 m0, s100, 0xe000
	v_mfma_f32_16x16x32_bf16 v[54:57], v[158:161], v[140:143], v[54:57]
	global_load_lds_dwordx4 v203, s[98:99]
	v_mfma_f32_16x16x32_bf16 v[70:73], v[162:165], v[140:143], v[70:73]
	ds_read_b128 v[140:143], v130 offset:18432
	s_add_u32 m0, s100, 0xb000
	s_waitcnt lgkmcnt(6)
	v_mfma_f32_16x16x32_bf16 v[58:61], v[126:129], v[148:151], v[58:61]
	global_load_lds_dwordx4 v204, s[98:99]
	v_mfma_f32_16x16x32_bf16 v[66:69], v[144:147], v[148:151], v[66:69]
	ds_read_b128 v[144:147], v130 offset:20480
	s_add_u32 m0, s100, 0xf000
	v_mfma_f32_16x16x32_bf16 v[62:65], v[158:161], v[148:151], v[62:65]
	global_load_lds_dwordx4 v205, s[98:99]
	v_mfma_f32_16x16x32_bf16 v[74:77], v[162:165], v[148:151], v[74:77]
	ds_read_b128 v[148:151], v130 offset:22528
	s_waitcnt lgkmcnt(3)
	v_mfma_f32_16x16x32_bf16 v[34:37], v[226:229], v[198:201], v[34:37]
	s_waitcnt lgkmcnt(2)
	v_mfma_f32_16x16x32_bf16 v[94:97], v[140:143], v[198:201], v[94:97]
	s_waitcnt lgkmcnt(1)
	v_mfma_f32_16x16x32_bf16 v[38:41], v[144:147], v[198:201], v[38:41]
	s_waitcnt lgkmcnt(0)
	v_mfma_f32_16x16x32_bf16 v[90:93], v[148:151], v[198:201], v[90:93]
	v_mfma_f32_16x16x32_bf16 v[42:45], v[226:229], v[206:209], v[42:45]
	v_mfma_f32_16x16x32_bf16 v[86:89], v[140:143], v[206:209], v[86:89]
	v_mfma_f32_16x16x32_bf16 v[46:49], v[144:147], v[206:209], v[46:49]
	v_mfma_f32_16x16x32_bf16 v[82:85], v[148:151], v[206:209], v[82:85]
	v_mfma_f32_16x16x32_bf16 v[50:53], v[226:229], v[214:217], v[50:53]
	v_mfma_f32_16x16x32_bf16 v[78:81], v[140:143], v[214:217], v[78:81]
	v_mfma_f32_16x16x32_bf16 v[54:57], v[144:147], v[214:217], v[54:57]
	v_mfma_f32_16x16x32_bf16 v[70:73], v[148:151], v[214:217], v[70:73]
	v_mfma_f32_16x16x32_bf16 v[58:61], v[226:229], v[132:135], v[58:61]
	v_mfma_f32_16x16x32_bf16 v[66:69], v[140:143], v[132:135], v[66:69]
	v_mfma_f32_16x16x32_bf16 v[62:65], v[144:147], v[132:135], v[62:65]
	v_mfma_f32_16x16x32_bf16 v[74:77], v[148:151], v[132:135], v[74:77]
	s_waitcnt vmcnt(0)
	s_setprio 0
	s_waitcnt lgkmcnt(0)
	s_barrier
	s_setprio 1
	s_add_u32 s98, s98, 0x80
	s_addc_u32 s99, s99, 0
	ds_read_b128 v[26:29], v122 offset:49152
	ds_read_b128 v[30:33], v122 offset:51200
	ds_read_b128 v[144:147], v122 offset:53248
	ds_read_b128 v[148:151], v122 offset:55296
	ds_read_b128 v[10:13], v124 offset:32768
	ds_read_b128 v[18:21], v124 offset:34816
	ds_read_b128 v[132:135], v124 offset:36864
	ds_read_b128 v[140:143], v124 offset:38912
	s_add_u32 m0, s100, 0x0
	s_waitcnt lgkmcnt(3)
	v_mfma_f32_16x16x32_bf16 v[34:37], v[26:29], v[10:13], v[34:37]
	global_load_lds_dwordx4 v194, s[98:99]
	v_mfma_f32_16x16x32_bf16 v[94:97], v[30:33], v[10:13], v[94:97]
	ds_read_b128 v[162:165], v123 offset:32768
	s_add_u32 m0, s100, 0x4000
	v_mfma_f32_16x16x32_bf16 v[38:41], v[144:147], v[10:13], v[38:41]
	global_load_lds_dwordx4 v195, s[98:99]
	v_mfma_f32_16x16x32_bf16 v[90:93], v[148:151], v[10:13], v[90:93]
	ds_read_b128 v[198:201], v123 offset:34816
	s_add_u32 m0, s100, 0x1000
	s_waitcnt lgkmcnt(4)
	v_mfma_f32_16x16x32_bf16 v[42:45], v[26:29], v[18:21], v[42:45]
	global_load_lds_dwordx4 v196, s[98:99]
	v_mfma_f32_16x16x32_bf16 v[86:89], v[30:33], v[18:21], v[86:89]
	ds_read_b128 v[206:209], v123 offset:36864
	s_add_u32 m0, s100, 0x5000
	v_mfma_f32_16x16x32_bf16 v[46:49], v[144:147], v[18:21], v[46:49]
	global_load_lds_dwordx4 v197, s[98:99]
	v_mfma_f32_16x16x32_bf16 v[82:85], v[148:151], v[18:21], v[82:85]
	ds_read_b128 v[214:217], v123 offset:38912
	s_add_u32 m0, s100, 0x2000
	s_waitcnt lgkmcnt(5)
	v_mfma_f32_16x16x32_bf16 v[50:53], v[26:29], v[132:135], v[50:53]
	global_load_lds_dwordx4 v202, s[98:99]
	v_mfma_f32_16x16x32_bf16 v[78:81], v[30:33], v[132:135], v[78:81]
	ds_read_b128 v[226:229], v130 offset:49152
	s_add_u32 m0, s100, 0x6000
	v_mfma_f32_16x16x32_bf16 v[54:57], v[144:147], v[132:135], v[54:57]
	global_load_lds_dwordx4 v203, s[98:99]
	v_mfma_f32_16x16x32_bf16 v[70:73], v[148:151], v[132:135], v[70:73]
	ds_read_b128 v[132:135], v130 offset:51200
	s_add_u32 m0, s100, 0x3000
	s_waitcnt lgkmcnt(6)
	v_mfma_f32_16x16x32_bf16 v[58:61], v[26:29], v[140:143], v[58:61]
	global_load_lds_dwordx4 v204, s[98:99]
	v_mfma_f32_16x16x32_bf16 v[66:69], v[30:33], v[140:143], v[66:69]
	ds_read_b128 v[234:237], v130 offset:53248
	s_add_u32 m0, s100, 0x7000
	v_mfma_f32_16x16x32_bf16 v[62:65], v[144:147], v[140:143], v[62:65]
	global_load_lds_dwordx4 v205, s[98:99]
	v_mfma_f32_16x16x32_bf16 v[74:77], v[148:151], v[140:143], v[74:77]
	ds_read_b128 v[140:143], v130 offset:55296
	s_waitcnt lgkmcnt(3)
	v_mfma_f32_16x16x32_bf16 v[34:37], v[226:229], v[162:165], v[34:37]
	global_load_dwordx4 v[2:5], v210, s[98:99] offset:128
	s_waitcnt lgkmcnt(2)
	v_mfma_f32_16x16x32_bf16 v[94:97], v[132:135], v[162:165], v[94:97]
	s_waitcnt lgkmcnt(1)
	v_mfma_f32_16x16x32_bf16 v[38:41], v[234:237], v[162:165], v[38:41]
	global_load_dwordx4 v[6:9], v211, s[98:99] offset:128
	s_waitcnt lgkmcnt(0)
	v_mfma_f32_16x16x32_bf16 v[90:93], v[140:143], v[162:165], v[90:93]
	v_mfma_f32_16x16x32_bf16 v[42:45], v[226:229], v[198:201], v[42:45]
	global_load_dwordx4 v[10:13], v212, s[98:99] offset:128
	v_mfma_f32_16x16x32_bf16 v[86:89], v[132:135], v[198:201], v[86:89]
	v_mfma_f32_16x16x32_bf16 v[46:49], v[234:237], v[198:201], v[46:49]
	global_load_dwordx4 v[14:17], v213, s[98:99] offset:128
	v_mfma_f32_16x16x32_bf16 v[82:85], v[140:143], v[198:201], v[82:85]
	v_mfma_f32_16x16x32_bf16 v[50:53], v[226:229], v[206:209], v[50:53]
	global_load_dwordx4 v[18:21], v218, s[98:99] offset:128
	v_mfma_f32_16x16x32_bf16 v[78:81], v[132:135], v[206:209], v[78:81]
	v_mfma_f32_16x16x32_bf16 v[54:57], v[234:237], v[206:209], v[54:57]
	global_load_dwordx4 v[22:25], v219, s[98:99] offset:128
	v_mfma_f32_16x16x32_bf16 v[70:73], v[140:143], v[206:209], v[70:73]
	v_mfma_f32_16x16x32_bf16 v[58:61], v[226:229], v[214:217], v[58:61]
	global_load_dwordx4 v[26:29], v220, s[98:99] offset:128
	v_mfma_f32_16x16x32_bf16 v[66:69], v[132:135], v[214:217], v[66:69]
	v_mfma_f32_16x16x32_bf16 v[62:65], v[234:237], v[214:217], v[62:65]
	global_load_dwordx4 v[30:33], v221, s[98:99] offset:128
	v_mfma_f32_16x16x32_bf16 v[74:77], v[140:143], v[214:217], v[74:77]
	s_waitcnt vmcnt(8)
	s_setprio 0
	s_add_i32 s5, s5, 2
	s_add_u32 s38, s38, 0x100
	s_addc_u32 s39, s39, 0
	s_waitcnt lgkmcnt(0)
	s_barrier
	s_add_i32 s5, s11, s2
	s_cmpk_lt_u32 s5, 0x100
	s_cselect_b64 s[44:45], -1, 0
	s_and_b64 s[8:9], s[44:45], exec
	s_cselect_b32 s9, s5, s11
	s_lshr_b32 s8, s9, 3
	s_and_b32 s8, s8, 0x1fffff8
	s_add_i32 s8, s8, s21
	s_and_b32 s11, s9, 7
	v_mov_b32_e32 v0, v169
	s_or_b32 s8, s8, s11
	s_lshl_b32 s8, s8, 7
	v_lshrrev_b32_e32 v98, 3, v0
	v_lshlrev_b32_e32 v0, 3, v0
	v_add_u32_e32 v98, s8, v98
	v_and_b32_e32 v0, 56, v0
	v_lshl_or_b32 v0, v98, 10, v0
	v_mov_b32_e32 v98, v169
	s_lshl_b32 s9, s9, 4
	s_and_b32 s9, s9, 0x380
	v_lshrrev_b32_e32 v99, 3, v98
	v_lshlrev_b32_e32 v98, 3, v98
	v_add_u32_e32 v99, s9, v99
	v_and_b32_e32 v98, 56, v98
	v_add_u32_e32 v114, 0x8000, v0
	v_add_u32_e32 v136, 0x10000, v0
	v_lshl_or_b32 v162, v99, 10, v98
	v_add_u32_e32 v166, 0x18000, v0
	v_add_u32_e32 v174, 0x8000, v162
	v_add_u32_e32 v176, 0x10000, v162
	v_add_u32_e32 v178, 0x18000, v162
	s_setprio 1
	ds_read_b128 v[98:101], v122 offset:16384
	ds_read_b128 v[110:113], v122 offset:18432
	ds_read_b128 v[132:135], v122 offset:20480
	ds_read_b128 v[140:143], v122 offset:22528
	ds_read_b128 v[102:105], v124
	ds_read_b128 v[106:109], v124 offset:2048
	ds_read_b128 v[118:121], v124 offset:4096
	ds_read_b128 v[126:129], v124 offset:6144
	v_readlane_b32 s14, v254, 45
	v_readlane_b32 s15, v254, 46
	v_mov_b32_e32 v163, v1
	v_mov_b32_e32 v115, v1
	v_mov_b32_e32 v175, v1
	v_mov_b32_e32 v137, v1
	v_mov_b32_e32 v177, v1
	v_mov_b32_e32 v167, v1
	v_mov_b32_e32 v179, v1
	v_lshl_add_u64 v[180:181], v[0:1], 1, s[14:15]
	v_lshl_add_u64 v[186:187], v[162:163], 1, s[34:35]
	v_lshl_add_u64 v[188:189], v[114:115], 1, s[14:15]
	v_lshl_add_u64 v[174:175], v[174:175], 1, s[34:35]
	v_lshl_add_u64 v[136:137], v[136:137], 1, s[14:15]
	v_lshl_add_u64 v[176:177], v[176:177], 1, s[34:35]
	v_lshl_add_u64 v[166:167], v[166:167], 1, s[14:15]
	v_lshl_add_u64 v[178:179], v[178:179], 1, s[34:35]
	s_waitcnt lgkmcnt(3)
	v_mfma_f32_16x16x32_bf16 v[144:147], v[98:101], v[102:105], v[34:37]
	s_nop 2
	global_load_dwordx4 v[34:37], v[180:181], off
	v_mfma_f32_16x16x32_bf16 v[94:97], v[110:113], v[102:105], v[94:97]
	ds_read_b128 v[148:151], v123
	v_mfma_f32_16x16x32_bf16 v[158:161], v[132:135], v[102:105], v[38:41]
	s_nop 2
	global_load_dwordx4 v[38:41], v[186:187], off
	v_mfma_f32_16x16x32_bf16 v[90:93], v[140:143], v[102:105], v[90:93]
	ds_read_b128 v[102:105], v123 offset:2048
	s_waitcnt lgkmcnt(4)
	v_mfma_f32_16x16x32_bf16 v[162:165], v[98:101], v[106:109], v[42:45]
	s_nop 2
	global_load_dwordx4 v[42:45], v[188:189], off
	v_mfma_f32_16x16x32_bf16 v[86:89], v[110:113], v[106:109], v[86:89]
	ds_read_b128 v[194:197], v123 offset:4096
	v_mfma_f32_16x16x32_bf16 v[198:201], v[132:135], v[106:109], v[46:49]
	s_nop 2
	global_load_dwordx4 v[46:49], v[174:175], off
	v_mfma_f32_16x16x32_bf16 v[82:85], v[140:143], v[106:109], v[82:85]
	ds_read_b128 v[106:109], v123 offset:6144
	s_waitcnt lgkmcnt(5)
	v_mfma_f32_16x16x32_bf16 v[202:205], v[98:101], v[118:121], v[50:53]
	s_nop 2
	global_load_dwordx4 v[50:53], v[136:137], off
	v_mfma_f32_16x16x32_bf16 v[78:81], v[110:113], v[118:121], v[78:81]
	ds_read_b128 v[206:209], v130 offset:16384
	v_mfma_f32_16x16x32_bf16 v[210:213], v[132:135], v[118:121], v[54:57]
	s_nop 2
	global_load_dwordx4 v[54:57], v[176:177], off
	v_mfma_f32_16x16x32_bf16 v[70:73], v[140:143], v[118:121], v[70:73]
	ds_read_b128 v[118:121], v130 offset:18432
	s_waitcnt lgkmcnt(6)
	v_mfma_f32_16x16x32_bf16 v[98:101], v[98:101], v[126:129], v[58:61]
	s_nop 2
	global_load_dwordx4 v[58:61], v[166:167], off
	v_mfma_f32_16x16x32_bf16 v[66:69], v[110:113], v[126:129], v[66:69]
	ds_read_b128 v[110:113], v130 offset:20480
	v_mfma_f32_16x16x32_bf16 v[132:135], v[132:135], v[126:129], v[62:65]
	s_nop 2
	global_load_dwordx4 v[62:65], v[178:179], off
	v_mfma_f32_16x16x32_bf16 v[74:77], v[140:143], v[126:129], v[74:77]
	ds_read_b128 v[126:129], v130 offset:22528
	s_waitcnt lgkmcnt(3)
	v_mfma_f32_16x16x32_bf16 v[140:143], v[206:209], v[148:151], v[144:147]
	s_waitcnt vmcnt(15)
	ds_write_b128 v117, v[2:5] offset:32768
	s_waitcnt lgkmcnt(3)
	v_mfma_f32_16x16x32_bf16 v[94:97], v[118:121], v[148:151], v[94:97]
	s_waitcnt lgkmcnt(2)
	v_mfma_f32_16x16x32_bf16 v[144:147], v[110:113], v[148:151], v[158:161]
	s_waitcnt vmcnt(14)
	ds_write_b128 v116, v[6:9] offset:49152
	s_waitcnt lgkmcnt(2)
	v_mfma_f32_16x16x32_bf16 v[90:93], v[126:129], v[148:151], v[90:93]
	v_mfma_f32_16x16x32_bf16 v[148:151], v[206:209], v[102:105], v[162:165]
	s_waitcnt vmcnt(13)
	ds_write_b128 v117, v[10:13] offset:36864
	v_mfma_f32_16x16x32_bf16 v[86:89], v[118:121], v[102:105], v[86:89]
	v_mfma_f32_16x16x32_bf16 v[158:161], v[110:113], v[102:105], v[198:201]
	s_waitcnt vmcnt(12)
	ds_write_b128 v116, v[14:17] offset:53248
	v_mfma_f32_16x16x32_bf16 v[82:85], v[126:129], v[102:105], v[82:85]
	v_mfma_f32_16x16x32_bf16 v[102:105], v[206:209], v[194:197], v[202:205]
	s_waitcnt vmcnt(11)
	ds_write_b128 v117, v[18:21] offset:40960
	v_mfma_f32_16x16x32_bf16 v[78:81], v[118:121], v[194:197], v[78:81]
	v_mfma_f32_16x16x32_bf16 v[162:165], v[110:113], v[194:197], v[210:213]
	s_waitcnt vmcnt(10)
	ds_write_b128 v116, v[22:25] offset:57344
	v_mfma_f32_16x16x32_bf16 v[70:73], v[126:129], v[194:197], v[70:73]
	v_mfma_f32_16x16x32_bf16 v[98:101], v[206:209], v[106:109], v[98:101]
	s_waitcnt vmcnt(9)
	ds_write_b128 v117, v[26:29] offset:45056
	v_mfma_f32_16x16x32_bf16 v[66:69], v[118:121], v[106:109], v[66:69]
	v_mfma_f32_16x16x32_bf16 v[110:113], v[110:113], v[106:109], v[132:135]
	s_waitcnt vmcnt(8)
	ds_write_b128 v116, v[30:33] offset:61440
	v_mfma_f32_16x16x32_bf16 v[74:77], v[126:129], v[106:109], v[74:77]
	s_setprio 0
	s_waitcnt lgkmcnt(0)
	s_barrier
	s_setprio 1
	ds_read_b128 v[26:29], v122 offset:49152
	ds_read_b128 v[10:13], v124 offset:32768
	ds_read_b128 v[18:21], v124 offset:34816
	ds_read_b128 v[30:33], v122 offset:51200
	ds_read_b128 v[106:109], v124 offset:36864
	ds_read_b128 v[114:117], v124 offset:38912
	ds_read_b128 v[118:121], v122 offset:53248
	ds_read_b128 v[124:127], v122 offset:55296
	s_waitcnt lgkmcnt(6)
	v_mfma_f32_16x16x32_bf16 v[132:135], v[26:29], v[10:13], v[140:143]
	global_load_dwordx4 v[2:5], v[180:181], off offset:128
	s_waitcnt lgkmcnt(4)
	v_mfma_f32_16x16x32_bf16 v[94:97], v[30:33], v[10:13], v[94:97]
	ds_read_b128 v[140:143], v123 offset:32768
	s_waitcnt lgkmcnt(2)
	v_mfma_f32_16x16x32_bf16 v[144:147], v[118:121], v[10:13], v[144:147]
	global_load_dwordx4 v[6:9], v[186:187], off offset:128
	s_waitcnt lgkmcnt(1)
	v_mfma_f32_16x16x32_bf16 v[90:93], v[124:127], v[10:13], v[90:93]
	ds_read_b128 v[194:197], v123 offset:34816
	v_mfma_f32_16x16x32_bf16 v[148:151], v[26:29], v[18:21], v[148:151]
	global_load_dwordx4 v[10:13], v[188:189], off offset:128
	v_mfma_f32_16x16x32_bf16 v[86:89], v[30:33], v[18:21], v[86:89]
	ds_read_b128 v[198:201], v123 offset:36864
	v_mfma_f32_16x16x32_bf16 v[158:161], v[118:121], v[18:21], v[158:161]
	global_load_dwordx4 v[14:17], v[174:175], off offset:128
	v_mfma_f32_16x16x32_bf16 v[82:85], v[124:127], v[18:21], v[82:85]
	ds_read_b128 v[202:205], v123 offset:38912
	v_mfma_f32_16x16x32_bf16 v[206:209], v[26:29], v[106:109], v[102:105]
	global_load_dwordx4 v[18:21], v[136:137], off offset:128
	v_mfma_f32_16x16x32_bf16 v[78:81], v[30:33], v[106:109], v[78:81]
	ds_read_b128 v[210:213], v130 offset:49152
	v_mfma_f32_16x16x32_bf16 v[162:165], v[118:121], v[106:109], v[162:165]
	global_load_dwordx4 v[22:25], v[176:177], off offset:128
	v_mfma_f32_16x16x32_bf16 v[70:73], v[124:127], v[106:109], v[70:73]
	ds_read_b128 v[214:217], v130 offset:51200
	v_mfma_f32_16x16x32_bf16 v[218:221], v[26:29], v[114:117], v[98:101]
	global_load_dwordx4 v[26:29], v[166:167], off offset:128
	v_mfma_f32_16x16x32_bf16 v[66:69], v[30:33], v[114:117], v[66:69]
	ds_read_b128 v[222:225], v130 offset:53248
	v_mfma_f32_16x16x32_bf16 v[226:229], v[118:121], v[114:117], v[110:113]
	global_load_dwordx4 v[30:33], v[178:179], off offset:128
	v_mfma_f32_16x16x32_bf16 v[230:233], v[124:127], v[114:117], v[74:77]
	s_waitcnt lgkmcnt(2)
	v_mfma_f32_16x16x32_bf16 v[126:129], v[210:213], v[140:143], v[132:135]
	s_nop 2
	ds_read_b128 v[130:133], v130 offset:55296
	s_waitcnt lgkmcnt(2)
	v_mfma_f32_16x16x32_bf16 v[122:125], v[214:217], v[140:143], v[94:97]
	s_waitcnt lgkmcnt(1)
	v_mfma_f32_16x16x32_bf16 v[118:121], v[222:225], v[140:143], v[144:147]
	s_waitcnt lgkmcnt(0)
	v_mfma_f32_16x16x32_bf16 v[114:117], v[130:133], v[140:143], v[90:93]
	v_mfma_f32_16x16x32_bf16 v[110:113], v[210:213], v[194:197], v[148:151]
	v_mfma_f32_16x16x32_bf16 v[106:109], v[214:217], v[194:197], v[86:89]
	v_mfma_f32_16x16x32_bf16 v[102:105], v[222:225], v[194:197], v[158:161]
	v_mfma_f32_16x16x32_bf16 v[98:101], v[130:133], v[194:197], v[82:85]
	v_mfma_f32_16x16x32_bf16 v[94:97], v[210:213], v[198:201], v[206:209]
	v_mfma_f32_16x16x32_bf16 v[90:93], v[214:217], v[198:201], v[78:81]
	v_mfma_f32_16x16x32_bf16 v[86:89], v[222:225], v[198:201], v[162:165]
	v_mfma_f32_16x16x32_bf16 v[82:85], v[130:133], v[198:201], v[70:73]
	v_mfma_f32_16x16x32_bf16 v[78:81], v[210:213], v[202:205], v[218:221]
	v_mfma_f32_16x16x32_bf16 v[74:77], v[214:217], v[202:205], v[66:69]
	v_mfma_f32_16x16x32_bf16 v[70:73], v[222:225], v[202:205], v[226:229]
	v_mfma_f32_16x16x32_bf16 v[66:69], v[130:133], v[202:205], v[230:233]
	s_setprio 0
	v_add_u32_e32 v134, s4, v152
	v_ashrrev_i32_e32 v135, 31, v134
	v_lshlrev_b64 v[136:137], 12, v[134:135]
	v_or_b32_e32 v140, s10, v153
	v_mov_b32_e32 v141, v1
	v_cndmask_b32_e64 v0, 0, 1, s[42:43]
	v_lshl_add_u64 v[130:131], s[40:41], 0, v[136:137]
	v_cmp_ne_u32_e64 s[38:39], 1, v0
	s_andn2_b64 vcc, exec, s[42:43]
	v_lshl_add_u64 v[146:147], v[140:141], 2, v[130:131]
	s_barrier
	s_cbranch_vccnz .LBB0_160
	global_load_dwordx4 v[130:133], v[146:147], off
	s_mov_b64 s[46:47], 0
	s_branch .LBB0_161

.LBB0_474:
	v_mov_b32_e32 v67, v169
	s_mov_b32 s11, s8
	v_lshrrev_b32_e32 v69, 4, v67
	v_ashrrev_i32_e32 v71, 3, v67
	v_lshrrev_b32_e32 v77, 1, v67
	v_and_b32_e32 v80, 4, v69
	v_and_b32_e32 v81, 3, v71
	v_and_b32_e32 v73, 7, v67
	v_xor_b32_e32 v75, v71, v67
	v_and_b32_e32 v77, 16, v77
	v_and_b32_e32 v79, 8, v69
	v_or_b32_e32 v82, v80, v81
	v_lshlrev_b32_e32 v75, 4, v75
	v_or3_b32 v77, v77, v79, v82
	v_bitop3_b32 v79, v80, v73, v81 bitop3:0x36
	v_lshlrev_b32_e32 v71, 7, v71
	v_lshlrev_b32_e32 v79, 4, v79
	v_and_or_b32 v115, v75, s24, v71
	v_lshl_or_b32 v114, v77, 7, v79
	s_waitcnt vmcnt(15)
	ds_write_b128 v115, v[34:37]
	s_waitcnt vmcnt(13)
	ds_write_b128 v114, v[38:41] offset:16384
	s_waitcnt vmcnt(11)
	ds_write_b128 v115, v[42:45] offset:4096
	s_waitcnt vmcnt(9)
	ds_write_b128 v114, v[46:49] offset:20480
	s_waitcnt vmcnt(7)
	ds_write_b128 v115, v[50:53] offset:8192
	s_waitcnt vmcnt(5)
	ds_write_b128 v114, v[54:57] offset:24576
	s_waitcnt vmcnt(3)
	ds_write_b128 v115, v[58:61] offset:12288
	s_waitcnt vmcnt(1)
	ds_write_b128 v114, v[62:65] offset:28672
	v_lshlrev_b32_e32 v35, 7, v67
	v_bfe_u32 v34, v67, 4, 2
	v_and_b32_e32 v36, 0x780, v35
	v_and_b32_e32 v116, 0x2780, v35
	v_bitop3_b32 v35, v69, v73, 3 bitop3:0x6c
	v_mov_b32_e32 v75, v1
	v_lshlrev_b32_e32 v117, 4, v35
	v_lshlrev_b32_e32 v35, 6, v67
	v_bitop3_b32 v34, v34, v73, 4 bitop3:0x36
	v_mov_b32_e32 v73, v1
	v_mov_b32_e32 v67, v1
	v_mov_b32_e32 v69, v1
	v_mov_b32_e32 v77, v1
	v_mov_b32_e32 v71, v1
	v_mov_b32_e32 v79, v1
	v_lshl_add_u64 v[100:101], v[74:75], 1, s[0:1]
	v_mov_b32_e32 v74, 0
	s_mov_b32 s16, s10
	v_and_or_b32 v118, v35, s30, v36
	v_lshlrev_b32_e32 v119, 4, v34
	v_lshl_add_u64 v[98:99], v[72:73], 1, s[0:1]
	v_lshl_add_u64 v[102:103], v[76:77], 1, s[0:1]
	v_lshl_add_u64 v[104:105], v[78:79], 1, s[0:1]
	v_lshlrev_b64 v[106:107], 1, v[0:1]
	s_waitcnt lgkmcnt(8)
	v_lshlrev_b64 v[108:109], 1, v[66:67]
	v_lshlrev_b64 v[110:111], 1, v[68:69]
	v_lshlrev_b64 v[112:113], 1, v[70:71]
	s_mov_b32 s8, -2
	s_mov_b64 s[28:29], s[34:35]
	v_mov_b32_e32 v75, v74
	v_mov_b32_e32 v76, v74
	v_mov_b32_e32 v77, v74
	v_mov_b32_e32 v62, v74
	v_mov_b32_e32 v63, v74
	v_mov_b32_e32 v64, v74
	v_mov_b32_e32 v65, v74
	v_mov_b32_e32 v66, v74
	v_mov_b32_e32 v67, v74
	v_mov_b32_e32 v68, v74
	v_mov_b32_e32 v69, v74
	v_mov_b32_e32 v58, v74
	v_mov_b32_e32 v59, v74
	v_mov_b32_e32 v60, v74
	v_mov_b32_e32 v61, v74
	v_mov_b32_e32 v70, v74
	v_mov_b32_e32 v71, v74
	v_mov_b32_e32 v72, v74
	v_mov_b32_e32 v73, v74
	v_mov_b32_e32 v54, v74
	v_mov_b32_e32 v55, v74
	v_mov_b32_e32 v56, v74
	v_mov_b32_e32 v57, v74
	v_mov_b32_e32 v78, v74
	v_mov_b32_e32 v79, v74
	v_mov_b32_e32 v80, v74
	v_mov_b32_e32 v81, v74
	v_mov_b32_e32 v50, v74
	v_mov_b32_e32 v51, v74
	v_mov_b32_e32 v52, v74
	v_mov_b32_e32 v53, v74
	v_mov_b32_e32 v82, v74
	v_mov_b32_e32 v83, v74
	v_mov_b32_e32 v84, v74
	v_mov_b32_e32 v85, v74
	v_mov_b32_e32 v46, v74
	v_mov_b32_e32 v47, v74
	v_mov_b32_e32 v48, v74
	v_mov_b32_e32 v49, v74
	v_mov_b32_e32 v86, v74
	v_mov_b32_e32 v87, v74
	v_mov_b32_e32 v88, v74
	v_mov_b32_e32 v89, v74
	v_mov_b32_e32 v42, v74
	v_mov_b32_e32 v43, v74
	v_mov_b32_e32 v44, v74
	v_mov_b32_e32 v45, v74
	v_mov_b32_e32 v90, v74
	v_mov_b32_e32 v91, v74
	v_mov_b32_e32 v92, v74
	v_mov_b32_e32 v93, v74
	v_mov_b32_e32 v38, v74
	v_mov_b32_e32 v39, v74
	v_mov_b32_e32 v40, v74
	v_mov_b32_e32 v41, v74
	v_mov_b32_e32 v94, v74
	v_mov_b32_e32 v95, v74
	v_mov_b32_e32 v96, v74
	v_mov_b32_e32 v97, v74
	v_mov_b32_e32 v34, v74
	v_mov_b32_e32 v35, v74
	v_mov_b32_e32 v36, v74
	v_mov_b32_e32 v37, v74
	s_waitcnt lgkmcnt(0)
	s_barrier
	v_lshrrev_b32_e32 v218, 6, v169
	v_lshlrev_b32_e32 v218, 10, v218
	v_lshrrev_b32_e32 v219, 3, v169
	v_readfirstlane_b32 s100, v218
	v_and_b32_e32 v218, 3, v219
	v_bfe_u32 v220, v219, 4, 1
	v_lshl_or_b32 v218, v220, 2, v218
	v_bfe_u32 v220, v219, 2, 1
	v_lshl_or_b32 v218, v220, 3, v218
	v_bfe_u32 v220, v219, 3, 1
	v_lshl_or_b32 v218, v220, 4, v218
	v_sub_u32_e32 v218, v218, v219
	v_mul_i32_i24_e32 v218, 0x800, v218
	v_and_b32_e32 v219, 7, v219
	v_lshlrev_b32_e32 v219, 4, v219
	v_add_u32_e32 v206, 0x4991000, v106
	v_xor_b32_e32 v164, v206, v219
	v_mov_b32_e32 v207, v98
	v_add_u32_e32 v165, v207, v218
	v_xor_b32_e32 v165, v165, v219
	v_add_u32_e32 v208, 0x4991000, v108
	v_xor_b32_e32 v166, v208, v219
	v_mov_b32_e32 v209, v100
	v_add_u32_e32 v167, v209, v218
	v_xor_b32_e32 v167, v167, v219
	v_add_u32_e32 v214, 0x4991000, v110
	v_xor_b32_e32 v198, v214, v219
	v_mov_b32_e32 v215, v102
	v_add_u32_e32 v199, v215, v218
	v_xor_b32_e32 v199, v199, v219
	v_add_u32_e32 v216, 0x4991000, v112
	v_xor_b32_e32 v200, v216, v219
	v_mov_b32_e32 v217, v104
	v_add_u32_e32 v201, v217, v218
	v_xor_b32_e32 v201, v201, v219
.LBB0_475:
	s_setprio 1
	s_add_u32 s98, s28, 0x80
	s_addc_u32 s99, s29, 0
	v_add_u32_e32 v120, v117, v116
	v_add_u32_e32 v122, v117, v118
	v_add_u32_e32 v121, v119, v118
	ds_read_b128 v[124:127], v120 offset:16384
	ds_read_b128 v[144:147], v120 offset:18432
	ds_read_b128 v[156:159], v120 offset:20480
	ds_read_b128 v[160:163], v120 offset:22528
	ds_read_b128 v[128:131], v122
	ds_read_b128 v[132:135], v122 offset:2048
	ds_read_b128 v[148:151], v122 offset:4096
	ds_read_b128 v[152:155], v122 offset:6144
	s_waitcnt lgkmcnt(3)
	v_mfma_f32_16x16x32_bf16 v[34:37], v[124:127], v[128:131], v[34:37]
	v_mfma_f32_16x16x32_bf16 v[94:97], v[144:147], v[128:131], v[94:97]
	ds_read_b128 v[194:197], v121
	v_mfma_f32_16x16x32_bf16 v[38:41], v[156:159], v[128:131], v[38:41]
	v_mfma_f32_16x16x32_bf16 v[90:93], v[160:163], v[128:131], v[90:93]
	v_add_u32_e32 v130, v119, v116
	ds_read_b128 v[202:205], v121 offset:2048
	s_waitcnt lgkmcnt(4)
	v_mfma_f32_16x16x32_bf16 v[42:45], v[124:127], v[132:135], v[42:45]
	v_mfma_f32_16x16x32_bf16 v[86:89], v[144:147], v[132:135], v[86:89]
	ds_read_b128 v[210:213], v121 offset:4096
	v_mfma_f32_16x16x32_bf16 v[46:49], v[156:159], v[132:135], v[46:49]
	v_mfma_f32_16x16x32_bf16 v[82:85], v[160:163], v[132:135], v[82:85]
	ds_read_b128 v[132:135], v121 offset:6144
	s_waitcnt lgkmcnt(5)
	v_mfma_f32_16x16x32_bf16 v[50:53], v[124:127], v[148:151], v[50:53]
	v_mfma_f32_16x16x32_bf16 v[78:81], v[144:147], v[148:151], v[78:81]
	ds_read_b128 v[222:225], v130 offset:16384
	v_mfma_f32_16x16x32_bf16 v[54:57], v[156:159], v[148:151], v[54:57]
	v_mfma_f32_16x16x32_bf16 v[70:73], v[160:163], v[148:151], v[70:73]
	ds_read_b128 v[148:151], v130 offset:18432
	s_waitcnt lgkmcnt(6)
	v_mfma_f32_16x16x32_bf16 v[58:61], v[124:127], v[152:155], v[58:61]
	v_mfma_f32_16x16x32_bf16 v[66:69], v[144:147], v[152:155], v[66:69]
	ds_read_b128 v[144:147], v130 offset:20480
	v_mfma_f32_16x16x32_bf16 v[62:65], v[156:159], v[152:155], v[62:65]
	v_mfma_f32_16x16x32_bf16 v[74:77], v[160:163], v[152:155], v[74:77]
	ds_read_b128 v[152:155], v130 offset:22528
	s_waitcnt lgkmcnt(3)
	v_mfma_f32_16x16x32_bf16 v[34:37], v[222:225], v[194:197], v[34:37]
	s_waitcnt vmcnt(7)
	ds_write_b128 v115, v[2:5] offset:32768
	s_waitcnt lgkmcnt(3)
	v_mfma_f32_16x16x32_bf16 v[94:97], v[148:151], v[194:197], v[94:97]
	s_waitcnt lgkmcnt(2)
	v_mfma_f32_16x16x32_bf16 v[38:41], v[144:147], v[194:197], v[38:41]
	s_waitcnt vmcnt(6)
	ds_write_b128 v114, v[6:9] offset:49152
	s_waitcnt lgkmcnt(2)
	v_mfma_f32_16x16x32_bf16 v[90:93], v[152:155], v[194:197], v[90:93]
	v_mfma_f32_16x16x32_bf16 v[42:45], v[222:225], v[202:205], v[42:45]
	s_waitcnt vmcnt(5)
	ds_write_b128 v115, v[10:13] offset:36864
	v_mfma_f32_16x16x32_bf16 v[86:89], v[148:151], v[202:205], v[86:89]
	v_mfma_f32_16x16x32_bf16 v[46:49], v[144:147], v[202:205], v[46:49]
	s_waitcnt vmcnt(4)
	ds_write_b128 v114, v[14:17] offset:53248
	v_mfma_f32_16x16x32_bf16 v[82:85], v[152:155], v[202:205], v[82:85]
	v_mfma_f32_16x16x32_bf16 v[50:53], v[222:225], v[210:213], v[50:53]
	s_waitcnt vmcnt(3)
	ds_write_b128 v115, v[18:21] offset:40960
	v_mfma_f32_16x16x32_bf16 v[78:81], v[148:151], v[210:213], v[78:81]
	v_mfma_f32_16x16x32_bf16 v[54:57], v[144:147], v[210:213], v[54:57]
	s_waitcnt vmcnt(2)
	ds_write_b128 v114, v[22:25] offset:57344
	v_mfma_f32_16x16x32_bf16 v[70:73], v[152:155], v[210:213], v[70:73]
	v_mfma_f32_16x16x32_bf16 v[58:61], v[222:225], v[132:135], v[58:61]
	s_waitcnt vmcnt(1)
	ds_write_b128 v115, v[26:29] offset:45056
	v_mfma_f32_16x16x32_bf16 v[66:69], v[148:151], v[132:135], v[66:69]
	v_mfma_f32_16x16x32_bf16 v[62:65], v[144:147], v[132:135], v[62:65]
	s_waitcnt vmcnt(0)
	ds_write_b128 v114, v[30:33] offset:61440
	v_mfma_f32_16x16x32_bf16 v[74:77], v[152:155], v[132:135], v[74:77]
	s_setprio 0
	s_waitcnt lgkmcnt(0)
	s_barrier
	s_setprio 1
	s_add_u32 s98, s98, 0x80
	s_addc_u32 s99, s99, 0
	ds_read_b128 v[26:29], v120 offset:49152
	ds_read_b128 v[30:33], v120 offset:51200
	ds_read_b128 v[148:151], v120 offset:53248
	ds_read_b128 v[152:155], v120 offset:55296
	ds_read_b128 v[10:13], v122 offset:32768
	ds_read_b128 v[18:21], v122 offset:34816
	ds_read_b128 v[132:135], v122 offset:36864
	ds_read_b128 v[144:147], v122 offset:38912
	s_add_u32 m0, s100, 0x0
	s_waitcnt lgkmcnt(3)
	v_mfma_f32_16x16x32_bf16 v[34:37], v[26:29], v[10:13], v[34:37]
	global_load_lds_dwordx4 v164, s[98:99]
	v_mfma_f32_16x16x32_bf16 v[94:97], v[30:33], v[10:13], v[94:97]
	ds_read_b128 v[160:163], v121 offset:32768
	s_add_u32 m0, s100, 0x4000
	v_mfma_f32_16x16x32_bf16 v[38:41], v[148:151], v[10:13], v[38:41]
	global_load_lds_dwordx4 v165, s[98:99]
	v_mfma_f32_16x16x32_bf16 v[90:93], v[152:155], v[10:13], v[90:93]
	ds_read_b128 v[194:197], v121 offset:34816
	s_add_u32 m0, s100, 0x1000
	s_waitcnt lgkmcnt(4)
	v_mfma_f32_16x16x32_bf16 v[42:45], v[26:29], v[18:21], v[42:45]
	global_load_lds_dwordx4 v166, s[98:99]
	v_mfma_f32_16x16x32_bf16 v[86:89], v[30:33], v[18:21], v[86:89]
	ds_read_b128 v[202:205], v121 offset:36864
	s_add_u32 m0, s100, 0x5000
	v_mfma_f32_16x16x32_bf16 v[46:49], v[148:151], v[18:21], v[46:49]
	global_load_lds_dwordx4 v167, s[98:99]
	v_mfma_f32_16x16x32_bf16 v[82:85], v[152:155], v[18:21], v[82:85]
	ds_read_b128 v[210:213], v121 offset:38912
	s_add_u32 m0, s100, 0x2000
	s_waitcnt lgkmcnt(5)
	v_mfma_f32_16x16x32_bf16 v[50:53], v[26:29], v[132:135], v[50:53]
	global_load_lds_dwordx4 v198, s[98:99]
	v_mfma_f32_16x16x32_bf16 v[78:81], v[30:33], v[132:135], v[78:81]
	ds_read_b128 v[222:225], v130 offset:49152
	s_add_u32 m0, s100, 0x6000
	v_mfma_f32_16x16x32_bf16 v[54:57], v[148:151], v[132:135], v[54:57]
	global_load_lds_dwordx4 v199, s[98:99]
	v_mfma_f32_16x16x32_bf16 v[70:73], v[152:155], v[132:135], v[70:73]
	ds_read_b128 v[132:135], v130 offset:51200
	s_add_u32 m0, s100, 0x3000
	s_waitcnt lgkmcnt(6)
	v_mfma_f32_16x16x32_bf16 v[58:61], v[26:29], v[144:147], v[58:61]
	global_load_lds_dwordx4 v200, s[98:99]
	v_mfma_f32_16x16x32_bf16 v[66:69], v[30:33], v[144:147], v[66:69]
	ds_read_b128 v[230:233], v130 offset:53248
	s_add_u32 m0, s100, 0x7000
	v_mfma_f32_16x16x32_bf16 v[62:65], v[148:151], v[144:147], v[62:65]
	global_load_lds_dwordx4 v201, s[98:99]
	v_mfma_f32_16x16x32_bf16 v[74:77], v[152:155], v[144:147], v[74:77]
	ds_read_b128 v[144:147], v130 offset:55296
	s_waitcnt lgkmcnt(3)
	v_mfma_f32_16x16x32_bf16 v[34:37], v[222:225], v[160:163], v[34:37]
	s_waitcnt lgkmcnt(2)
	v_mfma_f32_16x16x32_bf16 v[94:97], v[132:135], v[160:163], v[94:97]
	s_waitcnt lgkmcnt(1)
	v_mfma_f32_16x16x32_bf16 v[38:41], v[230:233], v[160:163], v[38:41]
	s_waitcnt lgkmcnt(0)
	v_mfma_f32_16x16x32_bf16 v[90:93], v[144:147], v[160:163], v[90:93]
	v_mfma_f32_16x16x32_bf16 v[42:45], v[222:225], v[194:197], v[42:45]
	v_mfma_f32_16x16x32_bf16 v[86:89], v[132:135], v[194:197], v[86:89]
	v_mfma_f32_16x16x32_bf16 v[46:49], v[230:233], v[194:197], v[46:49]
	v_mfma_f32_16x16x32_bf16 v[82:85], v[144:147], v[194:197], v[82:85]
	v_mfma_f32_16x16x32_bf16 v[50:53], v[222:225], v[202:205], v[50:53]
	v_mfma_f32_16x16x32_bf16 v[78:81], v[132:135], v[202:205], v[78:81]
	v_mfma_f32_16x16x32_bf16 v[54:57], v[230:233], v[202:205], v[54:57]
	v_mfma_f32_16x16x32_bf16 v[70:73], v[144:147], v[202:205], v[70:73]
	v_mfma_f32_16x16x32_bf16 v[58:61], v[222:225], v[210:213], v[58:61]
	v_mfma_f32_16x16x32_bf16 v[66:69], v[132:135], v[210:213], v[66:69]
	v_mfma_f32_16x16x32_bf16 v[62:65], v[230:233], v[210:213], v[62:65]
	v_mfma_f32_16x16x32_bf16 v[74:77], v[144:147], v[210:213], v[74:77]
	s_waitcnt vmcnt(0)
	s_setprio 0
	s_add_i32 s8, s8, 2
	s_add_u32 s28, s28, 0x100
	s_addc_u32 s29, s29, 0
	s_waitcnt lgkmcnt(0)
	s_barrier
.Lk3_mid_475:
	s_setprio 1
	s_add_u32 s98, s28, 0x80
	s_addc_u32 s99, s29, 0
	v_add_u32_e32 v120, v117, v116
	v_add_u32_e32 v122, v117, v118
	v_add_u32_e32 v121, v119, v118
	ds_read_b128 v[124:127], v120 offset:16384
	ds_read_b128 v[144:147], v120 offset:18432
	ds_read_b128 v[156:159], v120 offset:20480
	ds_read_b128 v[160:163], v120 offset:22528
	ds_read_b128 v[128:131], v122
	ds_read_b128 v[132:135], v122 offset:2048
	ds_read_b128 v[148:151], v122 offset:4096
	ds_read_b128 v[152:155], v122 offset:6144
	s_add_u32 m0, s100, 0x8000
	s_waitcnt lgkmcnt(3)
	v_mfma_f32_16x16x32_bf16 v[34:37], v[124:127], v[128:131], v[34:37]
	global_load_lds_dwordx4 v164, s[98:99]
	v_mfma_f32_16x16x32_bf16 v[94:97], v[144:147], v[128:131], v[94:97]
	ds_read_b128 v[194:197], v121
	s_add_u32 m0, s100, 0xc000
	v_mfma_f32_16x16x32_bf16 v[38:41], v[156:159], v[128:131], v[38:41]
	global_load_lds_dwordx4 v165, s[98:99]
	v_mfma_f32_16x16x32_bf16 v[90:93], v[160:163], v[128:131], v[90:93]
	v_add_u32_e32 v130, v119, v116
	ds_read_b128 v[202:205], v121 offset:2048
	s_add_u32 m0, s100, 0x9000
	s_waitcnt lgkmcnt(4)
	v_mfma_f32_16x16x32_bf16 v[42:45], v[124:127], v[132:135], v[42:45]
	global_load_lds_dwordx4 v166, s[98:99]
	v_mfma_f32_16x16x32_bf16 v[86:89], v[144:147], v[132:135], v[86:89]
	ds_read_b128 v[210:213], v121 offset:4096
	s_add_u32 m0, s100, 0xd000
	v_mfma_f32_16x16x32_bf16 v[46:49], v[156:159], v[132:135], v[46:49]
	global_load_lds_dwordx4 v167, s[98:99]
	v_mfma_f32_16x16x32_bf16 v[82:85], v[160:163], v[132:135], v[82:85]
	ds_read_b128 v[132:135], v121 offset:6144
	s_add_u32 m0, s100, 0xa000
	s_waitcnt lgkmcnt(5)
	v_mfma_f32_16x16x32_bf16 v[50:53], v[124:127], v[148:151], v[50:53]
	global_load_lds_dwordx4 v198, s[98:99]
	v_mfma_f32_16x16x32_bf16 v[78:81], v[144:147], v[148:151], v[78:81]
	ds_read_b128 v[222:225], v130 offset:16384
	s_add_u32 m0, s100, 0xe000
	v_mfma_f32_16x16x32_bf16 v[54:57], v[156:159], v[148:151], v[54:57]
	global_load_lds_dwordx4 v199, s[98:99]
	v_mfma_f32_16x16x32_bf16 v[70:73], v[160:163], v[148:151], v[70:73]
	ds_read_b128 v[148:151], v130 offset:18432
	s_add_u32 m0, s100, 0xb000
	s_waitcnt lgkmcnt(6)
	v_mfma_f32_16x16x32_bf16 v[58:61], v[124:127], v[152:155], v[58:61]
	global_load_lds_dwordx4 v200, s[98:99]
	v_mfma_f32_16x16x32_bf16 v[66:69], v[144:147], v[152:155], v[66:69]
	ds_read_b128 v[144:147], v130 offset:20480
	s_add_u32 m0, s100, 0xf000
	v_mfma_f32_16x16x32_bf16 v[62:65], v[156:159], v[152:155], v[62:65]
	global_load_lds_dwordx4 v201, s[98:99]
	v_mfma_f32_16x16x32_bf16 v[74:77], v[160:163], v[152:155], v[74:77]
	ds_read_b128 v[152:155], v130 offset:22528
	s_waitcnt lgkmcnt(3)
	v_mfma_f32_16x16x32_bf16 v[34:37], v[222:225], v[194:197], v[34:37]
	s_waitcnt lgkmcnt(2)
	v_mfma_f32_16x16x32_bf16 v[94:97], v[148:151], v[194:197], v[94:97]
	s_waitcnt lgkmcnt(1)
	v_mfma_f32_16x16x32_bf16 v[38:41], v[144:147], v[194:197], v[38:41]
	s_waitcnt lgkmcnt(0)
	v_mfma_f32_16x16x32_bf16 v[90:93], v[152:155], v[194:197], v[90:93]
	v_mfma_f32_16x16x32_bf16 v[42:45], v[222:225], v[202:205], v[42:45]
	v_mfma_f32_16x16x32_bf16 v[86:89], v[148:151], v[202:205], v[86:89]
	v_mfma_f32_16x16x32_bf16 v[46:49], v[144:147], v[202:205], v[46:49]
	v_mfma_f32_16x16x32_bf16 v[82:85], v[152:155], v[202:205], v[82:85]
	v_mfma_f32_16x16x32_bf16 v[50:53], v[222:225], v[210:213], v[50:53]
	v_mfma_f32_16x16x32_bf16 v[78:81], v[148:151], v[210:213], v[78:81]
	v_mfma_f32_16x16x32_bf16 v[54:57], v[144:147], v[210:213], v[54:57]
	v_mfma_f32_16x16x32_bf16 v[70:73], v[152:155], v[210:213], v[70:73]
	v_mfma_f32_16x16x32_bf16 v[58:61], v[222:225], v[132:135], v[58:61]
	v_mfma_f32_16x16x32_bf16 v[66:69], v[148:151], v[132:135], v[66:69]
	v_mfma_f32_16x16x32_bf16 v[62:65], v[144:147], v[132:135], v[62:65]
	v_mfma_f32_16x16x32_bf16 v[74:77], v[152:155], v[132:135], v[74:77]
	s_waitcnt vmcnt(0)
	s_setprio 0
	s_waitcnt lgkmcnt(0)
	s_barrier
	s_setprio 1
	s_add_u32 s98, s98, 0x80
	s_addc_u32 s99, s99, 0
	ds_read_b128 v[26:29], v120 offset:49152
	ds_read_b128 v[30:33], v120 offset:51200
	ds_read_b128 v[148:151], v120 offset:53248
	ds_read_b128 v[152:155], v120 offset:55296
	ds_read_b128 v[10:13], v122 offset:32768
	ds_read_b128 v[18:21], v122 offset:34816
	ds_read_b128 v[132:135], v122 offset:36864
	ds_read_b128 v[144:147], v122 offset:38912
	s_add_u32 m0, s100, 0x0
	s_waitcnt lgkmcnt(3)
	v_mfma_f32_16x16x32_bf16 v[34:37], v[26:29], v[10:13], v[34:37]
	global_load_lds_dwordx4 v164, s[98:99]
	v_mfma_f32_16x16x32_bf16 v[94:97], v[30:33], v[10:13], v[94:97]
	ds_read_b128 v[160:163], v121 offset:32768
	s_add_u32 m0, s100, 0x4000
	v_mfma_f32_16x16x32_bf16 v[38:41], v[148:151], v[10:13], v[38:41]
	global_load_lds_dwordx4 v165, s[98:99]
	v_mfma_f32_16x16x32_bf16 v[90:93], v[152:155], v[10:13], v[90:93]
	ds_read_b128 v[194:197], v121 offset:34816
	s_add_u32 m0, s100, 0x1000
	s_waitcnt lgkmcnt(4)
	v_mfma_f32_16x16x32_bf16 v[42:45], v[26:29], v[18:21], v[42:45]
	global_load_lds_dwordx4 v166, s[98:99]
	v_mfma_f32_16x16x32_bf16 v[86:89], v[30:33], v[18:21], v[86:89]
	ds_read_b128 v[202:205], v121 offset:36864
	s_add_u32 m0, s100, 0x5000
	v_mfma_f32_16x16x32_bf16 v[46:49], v[148:151], v[18:21], v[46:49]
	global_load_lds_dwordx4 v167, s[98:99]
	v_mfma_f32_16x16x32_bf16 v[82:85], v[152:155], v[18:21], v[82:85]
	ds_read_b128 v[210:213], v121 offset:38912
	s_add_u32 m0, s100, 0x2000
	s_waitcnt lgkmcnt(5)
	v_mfma_f32_16x16x32_bf16 v[50:53], v[26:29], v[132:135], v[50:53]
	global_load_lds_dwordx4 v198, s[98:99]
	v_mfma_f32_16x16x32_bf16 v[78:81], v[30:33], v[132:135], v[78:81]
	ds_read_b128 v[222:225], v130 offset:49152
	s_add_u32 m0, s100, 0x6000
	v_mfma_f32_16x16x32_bf16 v[54:57], v[148:151], v[132:135], v[54:57]
	global_load_lds_dwordx4 v199, s[98:99]
	v_mfma_f32_16x16x32_bf16 v[70:73], v[152:155], v[132:135], v[70:73]
	ds_read_b128 v[132:135], v130 offset:51200
	s_add_u32 m0, s100, 0x3000
	s_waitcnt lgkmcnt(6)
	v_mfma_f32_16x16x32_bf16 v[58:61], v[26:29], v[144:147], v[58:61]
	global_load_lds_dwordx4 v200, s[98:99]
	v_mfma_f32_16x16x32_bf16 v[66:69], v[30:33], v[144:147], v[66:69]
	ds_read_b128 v[230:233], v130 offset:53248
	s_add_u32 m0, s100, 0x7000
	v_mfma_f32_16x16x32_bf16 v[62:65], v[148:151], v[144:147], v[62:65]
	global_load_lds_dwordx4 v201, s[98:99]
	v_mfma_f32_16x16x32_bf16 v[74:77], v[152:155], v[144:147], v[74:77]
	ds_read_b128 v[144:147], v130 offset:55296
	s_waitcnt lgkmcnt(3)
	v_mfma_f32_16x16x32_bf16 v[34:37], v[222:225], v[160:163], v[34:37]
	s_waitcnt lgkmcnt(2)
	v_mfma_f32_16x16x32_bf16 v[94:97], v[132:135], v[160:163], v[94:97]
	s_waitcnt lgkmcnt(1)
	v_mfma_f32_16x16x32_bf16 v[38:41], v[230:233], v[160:163], v[38:41]
	s_waitcnt lgkmcnt(0)
	v_mfma_f32_16x16x32_bf16 v[90:93], v[144:147], v[160:163], v[90:93]
	v_mfma_f32_16x16x32_bf16 v[42:45], v[222:225], v[194:197], v[42:45]
	v_mfma_f32_16x16x32_bf16 v[86:89], v[132:135], v[194:197], v[86:89]
	v_mfma_f32_16x16x32_bf16 v[46:49], v[230:233], v[194:197], v[46:49]
	v_mfma_f32_16x16x32_bf16 v[82:85], v[144:147], v[194:197], v[82:85]
	v_mfma_f32_16x16x32_bf16 v[50:53], v[222:225], v[202:205], v[50:53]
	v_mfma_f32_16x16x32_bf16 v[78:81], v[132:135], v[202:205], v[78:81]
	v_mfma_f32_16x16x32_bf16 v[54:57], v[230:233], v[202:205], v[54:57]
	v_mfma_f32_16x16x32_bf16 v[70:73], v[144:147], v[202:205], v[70:73]
	v_mfma_f32_16x16x32_bf16 v[58:61], v[222:225], v[210:213], v[58:61]
	v_mfma_f32_16x16x32_bf16 v[66:69], v[132:135], v[210:213], v[66:69]
	v_mfma_f32_16x16x32_bf16 v[62:65], v[230:233], v[210:213], v[62:65]
	v_mfma_f32_16x16x32_bf16 v[74:77], v[144:147], v[210:213], v[74:77]
	s_waitcnt vmcnt(0)
	s_setprio 0
	s_add_i32 s8, s8, 2
	s_add_u32 s28, s28, 0x100
	s_addc_u32 s29, s29, 0
	s_cmp_lt_u32 s8, 10
	s_waitcnt lgkmcnt(0)
	s_barrier
	s_cbranch_scc1 .Lk3_mid_475
	s_setprio 1
	s_add_u32 s98, s28, 0x80
	s_addc_u32 s99, s29, 0
	v_add_u32_e32 v120, v117, v116
	v_add_u32_e32 v122, v117, v118
	v_add_u32_e32 v121, v119, v118
	ds_read_b128 v[124:127], v120 offset:16384
	ds_read_b128 v[144:147], v120 offset:18432
	ds_read_b128 v[156:159], v120 offset:20480
	ds_read_b128 v[160:163], v120 offset:22528
	ds_read_b128 v[128:131], v122
	ds_read_b128 v[132:135], v122 offset:2048
	ds_read_b128 v[148:151], v122 offset:4096
	ds_read_b128 v[152:155], v122 offset:6144
	s_add_u32 m0, s100, 0x8000
	s_waitcnt lgkmcnt(3)
	v_mfma_f32_16x16x32_bf16 v[34:37], v[124:127], v[128:131], v[34:37]
	global_load_lds_dwordx4 v164, s[98:99]
	v_mfma_f32_16x16x32_bf16 v[94:97], v[144:147], v[128:131], v[94:97]
	ds_read_b128 v[194:197], v121
	s_add_u32 m0, s100, 0xc000
	v_mfma_f32_16x16x32_bf16 v[38:41], v[156:159], v[128:131], v[38:41]
	global_load_lds_dwordx4 v165, s[98:99]
	v_mfma_f32_16x16x32_bf16 v[90:93], v[160:163], v[128:131], v[90:93]
	v_add_u32_e32 v130, v119, v116
	ds_read_b128 v[202:205], v121 offset:2048
	s_add_u32 m0, s100, 0x9000
	s_waitcnt lgkmcnt(4)
	v_mfma_f32_16x16x32_bf16 v[42:45], v[124:127], v[132:135], v[42:45]
	global_load_lds_dwordx4 v166, s[98:99]
	v_mfma_f32_16x16x32_bf16 v[86:89], v[144:147], v[132:135], v[86:89]
	ds_read_b128 v[210:213], v121 offset:4096
	s_add_u32 m0, s100, 0xd000
	v_mfma_f32_16x16x32_bf16 v[46:49], v[156:159], v[132:135], v[46:49]
	global_load_lds_dwordx4 v167, s[98:99]
	v_mfma_f32_16x16x32_bf16 v[82:85], v[160:163], v[132:135], v[82:85]
	ds_read_b128 v[132:135], v121 offset:6144
	s_add_u32 m0, s100, 0xa000
	s_waitcnt lgkmcnt(5)
	v_mfma_f32_16x16x32_bf16 v[50:53], v[124:127], v[148:151], v[50:53]
	global_load_lds_dwordx4 v198, s[98:99]
	v_mfma_f32_16x16x32_bf16 v[78:81], v[144:147], v[148:151], v[78:81]
	ds_read_b128 v[222:225], v130 offset:16384
	s_add_u32 m0, s100, 0xe000
	v_mfma_f32_16x16x32_bf16 v[54:57], v[156:159], v[148:151], v[54:57]
	global_load_lds_dwordx4 v199, s[98:99]
	v_mfma_f32_16x16x32_bf16 v[70:73], v[160:163], v[148:151], v[70:73]
	ds_read_b128 v[148:151], v130 offset:18432
	s_add_u32 m0, s100, 0xb000
	s_waitcnt lgkmcnt(6)
	v_mfma_f32_16x16x32_bf16 v[58:61], v[124:127], v[152:155], v[58:61]
	global_load_lds_dwordx4 v200, s[98:99]
	v_mfma_f32_16x16x32_bf16 v[66:69], v[144:147], v[152:155], v[66:69]
	ds_read_b128 v[144:147], v130 offset:20480
	s_add_u32 m0, s100, 0xf000
	v_mfma_f32_16x16x32_bf16 v[62:65], v[156:159], v[152:155], v[62:65]
	global_load_lds_dwordx4 v201, s[98:99]
	v_mfma_f32_16x16x32_bf16 v[74:77], v[160:163], v[152:155], v[74:77]
	ds_read_b128 v[152:155], v130 offset:22528
	s_waitcnt lgkmcnt(3)
	v_mfma_f32_16x16x32_bf16 v[34:37], v[222:225], v[194:197], v[34:37]
	s_waitcnt lgkmcnt(2)
	v_mfma_f32_16x16x32_bf16 v[94:97], v[148:151], v[194:197], v[94:97]
	s_waitcnt lgkmcnt(1)
	v_mfma_f32_16x16x32_bf16 v[38:41], v[144:147], v[194:197], v[38:41]
	s_waitcnt lgkmcnt(0)
	v_mfma_f32_16x16x32_bf16 v[90:93], v[152:155], v[194:197], v[90:93]
	v_mfma_f32_16x16x32_bf16 v[42:45], v[222:225], v[202:205], v[42:45]
	v_mfma_f32_16x16x32_bf16 v[86:89], v[148:151], v[202:205], v[86:89]
	v_mfma_f32_16x16x32_bf16 v[46:49], v[144:147], v[202:205], v[46:49]
	v_mfma_f32_16x16x32_bf16 v[82:85], v[152:155], v[202:205], v[82:85]
	v_mfma_f32_16x16x32_bf16 v[50:53], v[222:225], v[210:213], v[50:53]
	v_mfma_f32_16x16x32_bf16 v[78:81], v[148:151], v[210:213], v[78:81]
	v_mfma_f32_16x16x32_bf16 v[54:57], v[144:147], v[210:213], v[54:57]
	v_mfma_f32_16x16x32_bf16 v[70:73], v[152:155], v[210:213], v[70:73]
	v_mfma_f32_16x16x32_bf16 v[58:61], v[222:225], v[132:135], v[58:61]
	v_mfma_f32_16x16x32_bf16 v[66:69], v[148:151], v[132:135], v[66:69]
	v_mfma_f32_16x16x32_bf16 v[62:65], v[144:147], v[132:135], v[62:65]
	v_mfma_f32_16x16x32_bf16 v[74:77], v[152:155], v[132:135], v[74:77]
	s_waitcnt vmcnt(0)
	s_setprio 0
	s_waitcnt lgkmcnt(0)
	s_barrier
	s_setprio 1
	s_add_u32 s98, s98, 0x80
	s_addc_u32 s99, s99, 0
	ds_read_b128 v[26:29], v120 offset:49152
	ds_read_b128 v[30:33], v120 offset:51200
	ds_read_b128 v[148:151], v120 offset:53248
	ds_read_b128 v[152:155], v120 offset:55296
	ds_read_b128 v[10:13], v122 offset:32768
	ds_read_b128 v[18:21], v122 offset:34816
	ds_read_b128 v[132:135], v122 offset:36864
	ds_read_b128 v[144:147], v122 offset:38912
	s_add_u32 m0, s100, 0x0
	s_waitcnt lgkmcnt(3)
	v_mfma_f32_16x16x32_bf16 v[34:37], v[26:29], v[10:13], v[34:37]
	global_load_lds_dwordx4 v164, s[98:99]
	v_mfma_f32_16x16x32_bf16 v[94:97], v[30:33], v[10:13], v[94:97]
	ds_read_b128 v[160:163], v121 offset:32768
	s_add_u32 m0, s100, 0x4000
	v_mfma_f32_16x16x32_bf16 v[38:41], v[148:151], v[10:13], v[38:41]
	global_load_lds_dwordx4 v165, s[98:99]
	v_mfma_f32_16x16x32_bf16 v[90:93], v[152:155], v[10:13], v[90:93]
	ds_read_b128 v[194:197], v121 offset:34816
	s_add_u32 m0, s100, 0x1000
	s_waitcnt lgkmcnt(4)
	v_mfma_f32_16x16x32_bf16 v[42:45], v[26:29], v[18:21], v[42:45]
	global_load_lds_dwordx4 v166, s[98:99]
	v_mfma_f32_16x16x32_bf16 v[86:89], v[30:33], v[18:21], v[86:89]
	ds_read_b128 v[202:205], v121 offset:36864
	s_add_u32 m0, s100, 0x5000
	v_mfma_f32_16x16x32_bf16 v[46:49], v[148:151], v[18:21], v[46:49]
	global_load_lds_dwordx4 v167, s[98:99]
	v_mfma_f32_16x16x32_bf16 v[82:85], v[152:155], v[18:21], v[82:85]
	ds_read_b128 v[210:213], v121 offset:38912
	s_add_u32 m0, s100, 0x2000
	s_waitcnt lgkmcnt(5)
	v_mfma_f32_16x16x32_bf16 v[50:53], v[26:29], v[132:135], v[50:53]
	global_load_lds_dwordx4 v198, s[98:99]
	v_mfma_f32_16x16x32_bf16 v[78:81], v[30:33], v[132:135], v[78:81]
	ds_read_b128 v[222:225], v130 offset:49152
	s_add_u32 m0, s100, 0x6000
	v_mfma_f32_16x16x32_bf16 v[54:57], v[148:151], v[132:135], v[54:57]
	global_load_lds_dwordx4 v199, s[98:99]
	v_mfma_f32_16x16x32_bf16 v[70:73], v[152:155], v[132:135], v[70:73]
	ds_read_b128 v[132:135], v130 offset:51200
	s_add_u32 m0, s100, 0x3000
	s_waitcnt lgkmcnt(6)
	v_mfma_f32_16x16x32_bf16 v[58:61], v[26:29], v[144:147], v[58:61]
	global_load_lds_dwordx4 v200, s[98:99]
	v_mfma_f32_16x16x32_bf16 v[66:69], v[30:33], v[144:147], v[66:69]
	ds_read_b128 v[230:233], v130 offset:53248
	s_add_u32 m0, s100, 0x7000
	v_mfma_f32_16x16x32_bf16 v[62:65], v[148:151], v[144:147], v[62:65]
	global_load_lds_dwordx4 v201, s[98:99]
	v_mfma_f32_16x16x32_bf16 v[74:77], v[152:155], v[144:147], v[74:77]
	ds_read_b128 v[144:147], v130 offset:55296
	s_waitcnt lgkmcnt(3)
	v_mfma_f32_16x16x32_bf16 v[34:37], v[222:225], v[160:163], v[34:37]
	global_load_dwordx4 v[2:5], v206, s[98:99] offset:128
	s_waitcnt lgkmcnt(2)
	v_mfma_f32_16x16x32_bf16 v[94:97], v[132:135], v[160:163], v[94:97]
	s_waitcnt lgkmcnt(1)
	v_mfma_f32_16x16x32_bf16 v[38:41], v[230:233], v[160:163], v[38:41]
	global_load_dwordx4 v[6:9], v207, s[98:99] offset:128
	s_waitcnt lgkmcnt(0)
	v_mfma_f32_16x16x32_bf16 v[90:93], v[144:147], v[160:163], v[90:93]
	v_mfma_f32_16x16x32_bf16 v[42:45], v[222:225], v[194:197], v[42:45]
	global_load_dwordx4 v[10:13], v208, s[98:99] offset:128
	v_mfma_f32_16x16x32_bf16 v[86:89], v[132:135], v[194:197], v[86:89]
	v_mfma_f32_16x16x32_bf16 v[46:49], v[230:233], v[194:197], v[46:49]
	global_load_dwordx4 v[14:17], v209, s[98:99] offset:128
	v_mfma_f32_16x16x32_bf16 v[82:85], v[144:147], v[194:197], v[82:85]
	v_mfma_f32_16x16x32_bf16 v[50:53], v[222:225], v[202:205], v[50:53]
	global_load_dwordx4 v[18:21], v214, s[98:99] offset:128
	v_mfma_f32_16x16x32_bf16 v[78:81], v[132:135], v[202:205], v[78:81]
	v_mfma_f32_16x16x32_bf16 v[54:57], v[230:233], v[202:205], v[54:57]
	global_load_dwordx4 v[22:25], v215, s[98:99] offset:128
	v_mfma_f32_16x16x32_bf16 v[70:73], v[144:147], v[202:205], v[70:73]
	v_mfma_f32_16x16x32_bf16 v[58:61], v[222:225], v[210:213], v[58:61]
	global_load_dwordx4 v[26:29], v216, s[98:99] offset:128
	v_mfma_f32_16x16x32_bf16 v[66:69], v[132:135], v[210:213], v[66:69]
	v_mfma_f32_16x16x32_bf16 v[62:65], v[230:233], v[210:213], v[62:65]
	global_load_dwordx4 v[30:33], v217, s[98:99] offset:128
	v_mfma_f32_16x16x32_bf16 v[74:77], v[144:147], v[210:213], v[74:77]
	s_waitcnt vmcnt(8)
	s_setprio 0
	s_add_i32 s8, s8, 2
	s_add_u32 s28, s28, 0x100
	s_addc_u32 s29, s29, 0
	s_waitcnt lgkmcnt(0)
	s_barrier
	s_add_i32 s8, s11, s2
	s_cmpk_lt_u32 s8, 0x420
	s_cselect_b64 s[56:57], -1, 0
	s_and_b64 s[14:15], s[56:57], exec
	s_cselect_b32 s10, s8, s11
	s_mul_hi_u32 s11, s10, 0x3e0f83e1
	s_lshr_b32 s11, s11, 6
	s_mul_i32 s14, s11, 0x108
	v_mov_b32_e32 v0, v169
	s_sub_i32 s10, s10, s14
	s_lshl_b32 s11, s11, 3
	s_add_i32 s11, s11, s21
	s_and_b32 s14, s10, 7
	v_lshlrev_b32_e32 v98, 3, v0
	v_lshlrev_b32_e32 v0, 7, v0
	s_or_b32 s11, s11, s14
	v_and_b32_e32 v0, 0xfffffc00, v0
	v_lshl_add_u32 v0, s11, 17, v0
	v_and_or_b32 v0, v98, 56, v0
	v_mov_b32_e32 v98, v169
	s_lshl_b32 s10, s10, 4
	s_and_b32 s10, s10, 0x1f80
	v_lshrrev_b32_e32 v99, 3, v98
	v_lshlrev_b32_e32 v98, 3, v98
	v_add_u32_e32 v99, s10, v99
	v_and_b32_e32 v98, 56, v98
	v_add_u32_e32 v128, 0x8000, v0
	v_add_u32_e32 v136, 0x10000, v0
	v_lshl_or_b32 v160, v99, 10, v98
	v_add_u32_e32 v210, 0x18000, v0
	v_add_u32_e32 v198, 0x8000, v160
	v_add_u32_e32 v212, 0x10000, v160
	v_add_u32_e32 v214, 0x18000, v160
	s_setprio 1
	ds_read_b128 v[98:101], v120 offset:16384
	ds_read_b128 v[110:113], v120 offset:18432
	ds_read_b128 v[132:135], v120 offset:20480
	ds_read_b128 v[144:147], v120 offset:22528
	ds_read_b128 v[102:105], v122
	ds_read_b128 v[106:109], v122 offset:2048
	ds_read_b128 v[116:119], v122 offset:4096
	ds_read_b128 v[124:127], v122 offset:6144
	v_mov_b32_e32 v161, v1
	v_mov_b32_e32 v129, v1
	v_mov_b32_e32 v199, v1
	v_mov_b32_e32 v137, v1
	v_mov_b32_e32 v213, v1
	v_mov_b32_e32 v211, v1
	v_mov_b32_e32 v215, v1
	v_lshl_add_u64 v[216:217], v[0:1], 1, s[48:49]
	v_lshl_add_u64 v[218:219], v[160:161], 1, s[50:51]
	v_lshl_add_u64 v[220:221], v[128:129], 1, s[48:49]
	v_lshl_add_u64 v[222:223], v[198:199], 1, s[50:51]
	v_lshl_add_u64 v[136:137], v[136:137], 1, s[48:49]
	v_lshl_add_u64 v[212:213], v[212:213], 1, s[50:51]
	v_lshl_add_u64 v[224:225], v[210:211], 1, s[48:49]
	v_lshl_add_u64 v[226:227], v[214:215], 1, s[50:51]
	s_waitcnt lgkmcnt(3)
	v_mfma_f32_16x16x32_bf16 v[148:151], v[98:101], v[102:105], v[34:37]
	s_nop 2
	global_load_dwordx4 v[34:37], v[216:217], off
	v_mfma_f32_16x16x32_bf16 v[94:97], v[110:113], v[102:105], v[94:97]
	ds_read_b128 v[152:155], v121
	v_mfma_f32_16x16x32_bf16 v[156:159], v[132:135], v[102:105], v[38:41]
	s_nop 2
	global_load_dwordx4 v[38:41], v[218:219], off
	v_mfma_f32_16x16x32_bf16 v[90:93], v[144:147], v[102:105], v[90:93]
	ds_read_b128 v[102:105], v121 offset:2048
	s_waitcnt lgkmcnt(4)
	v_mfma_f32_16x16x32_bf16 v[160:163], v[98:101], v[106:109], v[42:45]
	s_nop 2
	global_load_dwordx4 v[42:45], v[220:221], off
	v_mfma_f32_16x16x32_bf16 v[86:89], v[110:113], v[106:109], v[86:89]
	ds_read_b128 v[164:167], v121 offset:4096
	v_mfma_f32_16x16x32_bf16 v[194:197], v[132:135], v[106:109], v[46:49]
	s_nop 2
	global_load_dwordx4 v[46:49], v[222:223], off
	v_mfma_f32_16x16x32_bf16 v[82:85], v[144:147], v[106:109], v[82:85]
	ds_read_b128 v[106:109], v121 offset:6144
	s_waitcnt lgkmcnt(5)
	v_mfma_f32_16x16x32_bf16 v[198:201], v[98:101], v[116:119], v[50:53]
	s_nop 2
	global_load_dwordx4 v[50:53], v[136:137], off
	v_mfma_f32_16x16x32_bf16 v[78:81], v[110:113], v[116:119], v[78:81]
	ds_read_b128 v[202:205], v130 offset:16384
	v_mfma_f32_16x16x32_bf16 v[206:209], v[132:135], v[116:119], v[54:57]
	s_nop 2
	global_load_dwordx4 v[54:57], v[212:213], off
	v_mfma_f32_16x16x32_bf16 v[70:73], v[144:147], v[116:119], v[70:73]
	ds_read_b128 v[116:119], v130 offset:18432
	s_waitcnt lgkmcnt(6)
	v_mfma_f32_16x16x32_bf16 v[98:101], v[98:101], v[124:127], v[58:61]
	s_nop 2
	global_load_dwordx4 v[58:61], v[224:225], off
	v_mfma_f32_16x16x32_bf16 v[66:69], v[110:113], v[124:127], v[66:69]
	ds_read_b128 v[110:113], v130 offset:20480
	v_mfma_f32_16x16x32_bf16 v[132:135], v[132:135], v[124:127], v[62:65]
	s_nop 2
	global_load_dwordx4 v[62:65], v[226:227], off
	v_mfma_f32_16x16x32_bf16 v[74:77], v[144:147], v[124:127], v[74:77]
	ds_read_b128 v[124:127], v130 offset:22528
	s_waitcnt lgkmcnt(3)
	v_mfma_f32_16x16x32_bf16 v[144:147], v[202:205], v[152:155], v[148:151]
	s_waitcnt vmcnt(15)
	ds_write_b128 v115, v[2:5] offset:32768
	s_waitcnt lgkmcnt(3)
	v_mfma_f32_16x16x32_bf16 v[94:97], v[116:119], v[152:155], v[94:97]
	s_waitcnt lgkmcnt(2)
	v_mfma_f32_16x16x32_bf16 v[148:151], v[110:113], v[152:155], v[156:159]
	s_waitcnt vmcnt(14)
	ds_write_b128 v114, v[6:9] offset:49152
	s_waitcnt lgkmcnt(2)
	v_mfma_f32_16x16x32_bf16 v[90:93], v[124:127], v[152:155], v[90:93]
	v_mfma_f32_16x16x32_bf16 v[152:155], v[202:205], v[102:105], v[160:163]
	s_waitcnt vmcnt(13)
	ds_write_b128 v115, v[10:13] offset:36864
	v_mfma_f32_16x16x32_bf16 v[86:89], v[116:119], v[102:105], v[86:89]
	v_mfma_f32_16x16x32_bf16 v[156:159], v[110:113], v[102:105], v[194:197]
	s_waitcnt vmcnt(12)
	ds_write_b128 v114, v[14:17] offset:53248
	v_mfma_f32_16x16x32_bf16 v[82:85], v[124:127], v[102:105], v[82:85]
	v_mfma_f32_16x16x32_bf16 v[102:105], v[202:205], v[164:167], v[198:201]
	s_waitcnt vmcnt(11)
	ds_write_b128 v115, v[18:21] offset:40960
	v_mfma_f32_16x16x32_bf16 v[78:81], v[116:119], v[164:167], v[78:81]
	v_mfma_f32_16x16x32_bf16 v[160:163], v[110:113], v[164:167], v[206:209]
	s_waitcnt vmcnt(10)
	ds_write_b128 v114, v[22:25] offset:57344
	v_mfma_f32_16x16x32_bf16 v[70:73], v[124:127], v[164:167], v[70:73]
	v_mfma_f32_16x16x32_bf16 v[98:101], v[202:205], v[106:109], v[98:101]
	s_waitcnt vmcnt(9)
	ds_write_b128 v115, v[26:29] offset:45056
	v_mfma_f32_16x16x32_bf16 v[66:69], v[116:119], v[106:109], v[66:69]
	v_mfma_f32_16x16x32_bf16 v[110:113], v[110:113], v[106:109], v[132:135]
	s_waitcnt vmcnt(8)
	ds_write_b128 v114, v[30:33] offset:61440
	v_mfma_f32_16x16x32_bf16 v[74:77], v[124:127], v[106:109], v[74:77]
	s_setprio 0
	s_waitcnt lgkmcnt(0)
	s_barrier
	s_setprio 1
	ds_read_b128 v[26:29], v120 offset:49152
	ds_read_b128 v[10:13], v122 offset:32768
	ds_read_b128 v[18:21], v122 offset:34816
	ds_read_b128 v[30:33], v120 offset:51200
	ds_read_b128 v[106:109], v122 offset:36864
	ds_read_b128 v[114:117], v122 offset:38912
	ds_read_b128 v[122:125], v120 offset:53248
	ds_read_b128 v[126:129], v120 offset:55296
	s_waitcnt lgkmcnt(6)
	v_mfma_f32_16x16x32_bf16 v[132:135], v[26:29], v[10:13], v[144:147]
	global_load_dwordx4 v[2:5], v[216:217], off offset:128
	s_waitcnt lgkmcnt(4)
	v_mfma_f32_16x16x32_bf16 v[94:97], v[30:33], v[10:13], v[94:97]
	ds_read_b128 v[144:147], v121 offset:32768
	s_waitcnt lgkmcnt(2)
	v_mfma_f32_16x16x32_bf16 v[148:151], v[122:125], v[10:13], v[148:151]
	global_load_dwordx4 v[6:9], v[218:219], off offset:128
	s_waitcnt lgkmcnt(1)
	v_mfma_f32_16x16x32_bf16 v[90:93], v[126:129], v[10:13], v[90:93]
	ds_read_b128 v[164:167], v121 offset:34816
	v_mfma_f32_16x16x32_bf16 v[152:155], v[26:29], v[18:21], v[152:155]
	global_load_dwordx4 v[10:13], v[220:221], off offset:128
	v_mfma_f32_16x16x32_bf16 v[86:89], v[30:33], v[18:21], v[86:89]
	ds_read_b128 v[194:197], v121 offset:36864
	v_mfma_f32_16x16x32_bf16 v[156:159], v[122:125], v[18:21], v[156:159]
	global_load_dwordx4 v[14:17], v[222:223], off offset:128
	v_mfma_f32_16x16x32_bf16 v[82:85], v[126:129], v[18:21], v[82:85]
	ds_read_b128 v[198:201], v121 offset:38912
	v_mfma_f32_16x16x32_bf16 v[202:205], v[26:29], v[106:109], v[102:105]
	global_load_dwordx4 v[18:21], v[136:137], off offset:128
	v_mfma_f32_16x16x32_bf16 v[78:81], v[30:33], v[106:109], v[78:81]
	ds_read_b128 v[206:209], v130 offset:49152
	v_mfma_f32_16x16x32_bf16 v[160:163], v[122:125], v[106:109], v[160:163]
	global_load_dwordx4 v[22:25], v[212:213], off offset:128
	v_mfma_f32_16x16x32_bf16 v[70:73], v[126:129], v[106:109], v[70:73]
	ds_read_b128 v[210:213], v130 offset:51200
	v_mfma_f32_16x16x32_bf16 v[214:217], v[26:29], v[114:117], v[98:101]
	global_load_dwordx4 v[26:29], v[224:225], off offset:128
	v_mfma_f32_16x16x32_bf16 v[66:69], v[30:33], v[114:117], v[66:69]
	ds_read_b128 v[218:221], v130 offset:53248
	v_mfma_f32_16x16x32_bf16 v[222:225], v[122:125], v[114:117], v[110:113]
	global_load_dwordx4 v[30:33], v[226:227], off offset:128
	v_mfma_f32_16x16x32_bf16 v[226:229], v[126:129], v[114:117], v[74:77]
	s_waitcnt lgkmcnt(2)
	v_mfma_f32_16x16x32_bf16 v[126:129], v[206:209], v[144:147], v[132:135]
	s_nop 2
	ds_read_b128 v[130:133], v130 offset:55296
	s_waitcnt lgkmcnt(2)
	v_mfma_f32_16x16x32_bf16 v[122:125], v[210:213], v[144:147], v[94:97]
	s_waitcnt lgkmcnt(1)
	v_mfma_f32_16x16x32_bf16 v[118:121], v[218:221], v[144:147], v[148:151]
	s_waitcnt lgkmcnt(0)
	v_mfma_f32_16x16x32_bf16 v[114:117], v[130:133], v[144:147], v[90:93]
	v_mfma_f32_16x16x32_bf16 v[110:113], v[206:209], v[164:167], v[152:155]
	v_mfma_f32_16x16x32_bf16 v[106:109], v[210:213], v[164:167], v[86:89]
	v_mfma_f32_16x16x32_bf16 v[102:105], v[218:221], v[164:167], v[156:159]
	v_mfma_f32_16x16x32_bf16 v[98:101], v[130:133], v[164:167], v[82:85]
	v_mfma_f32_16x16x32_bf16 v[94:97], v[206:209], v[194:197], v[202:205]
	v_mfma_f32_16x16x32_bf16 v[90:93], v[210:213], v[194:197], v[78:81]
	v_mfma_f32_16x16x32_bf16 v[86:89], v[218:221], v[194:197], v[160:163]
	v_mfma_f32_16x16x32_bf16 v[82:85], v[130:133], v[194:197], v[70:73]
	v_mfma_f32_16x16x32_bf16 v[74:77], v[206:209], v[198:201], v[214:217]
	v_mfma_f32_16x16x32_bf16 v[70:73], v[210:213], v[198:201], v[66:69]
	v_mfma_f32_16x16x32_bf16 v[66:69], v[218:221], v[198:201], v[222:225]
	v_mfma_f32_16x16x32_bf16 v[78:81], v[130:133], v[198:201], v[226:229]
	s_setprio 0
	s_cmpk_gt_u32 s16, 0x9ff
	s_cselect_b64 s[42:43], -1, 0
	s_and_b32 s17, s16, 0x1f00
	s_cmpk_eq_i32 s17, 0xe00
	s_cselect_b64 s[40:41], -1, 0
	s_cmpk_gt_u32 s16, 0x5ff
	s_cselect_b64 s[46:47], -1, 0
	s_cmpk_gt_u32 s16, 0xbff
	s_cselect_b64 s[62:63], -1, 0
	s_cmpk_lt_u32 s16, 0xd00
	s_cselect_b64 s[14:15], -1, 0
	s_and_b64 s[26:27], s[14:15], exec
	s_movk_i32 s21, 0xf300
	s_cselect_b32 s28, 0xfffff400, s21
	s_nor_b64 s[60:61], s[14:15], s[40:41]
	s_cmpk_gt_u32 s16, 0xfff
	s_cselect_b64 s[58:59], -1, 0
	s_cmpk_lt_u32 s16, 0xe00
	v_add_u32_e32 v0, s9, v141
	s_cselect_b64 s[14:15], -1, 0
	v_or_b32_e32 v136, v0, v140
	s_movk_i32 s21, 0xc0
	s_and_b64 s[14:15], s[14:15], exec
	v_mad_i64_i32 v[134:135], s[26:27], v136, s21, 0
	s_movk_i32 s21, 0x1fcf
	s_movk_i32 s14, 0xf100
	v_bitop3_b32 v144, v0, s21, v140 bitop3:0xc8
	v_ashrrev_i32_e32 v0, 5, v0
	s_cselect_b32 s15, 0xfffff300, s14
	s_mov_b32 s14, 0x18991000
	v_ashrrev_i32_e32 v137, 31, v136
	v_and_b32_e32 v0, 0xffffff00, v0
	s_cselect_b32 s14, s14, 0x19991000
	v_add_u32_e32 v145, s15, v0
	v_lshlrev_b64 v[132:133], 10, v[136:137]
	v_lshlrev_b64 v[130:131], 11, v[136:137]
	v_or_b32_e32 v0, s16, v142
	s_mov_b64 s[44:45], -1
	s_and_b64 vcc, exec, s[46:47]
	s_barrier
	s_cbranch_vccz .LBB0_496
	s_and_b64 vcc, exec, s[42:43]
	s_cbranch_vccz .LBB0_493
	s_and_b64 vcc, exec, s[62:63]
	s_cbranch_vccz .LBB0_490
	s_and_b64 vcc, exec, s[60:61]
	s_cbranch_vccz .LBB0_487
	s_and_b64 vcc, exec, s[58:59]
	s_cbranch_vccz .LBB0_484
	v_cmp_gt_u32_e32 vcc, s7, v0
	s_and_saveexec_b64 s[44:45], vcc
	s_cbranch_execz .LBB0_483
	v_mul_f32_e32 v137, 0xbfb8aa3b, v126
	v_exp_f32_e32 v137, v137
	v_mul_f32_e32 v143, 0xbfb8aa3b, v127
	v_exp_f32_e32 v143, v143
	v_mul_f32_e32 v147, 0xbfb8aa3b, v129
	v_add_f32_e32 v137, 1.0, v137
	v_rcp_f32_e32 v146, v137
	v_mul_f32_e32 v137, 0xbfb8aa3b, v128
	v_exp_f32_e32 v137, v137
	v_exp_f32_e32 v149, v147
	v_add_f32_e32 v143, 1.0, v143
	v_rcp_f32_e32 v147, v143
	v_add_f32_e32 v137, 1.0, v137
	v_mul_f32_e32 v143, 0xbfb8aa3b, v122
	v_rcp_f32_e32 v148, v137
	v_add_f32_e32 v137, 1.0, v149
	v_exp_f32_e32 v143, v143
	v_mul_f32_e32 v149, 0xbfb8aa3b, v123
	v_exp_f32_e32 v151, v149
	v_rcp_f32_e32 v149, v137
	v_add_f32_e32 v137, 1.0, v143
	v_mul_f32_e32 v143, 0xbfb8aa3b, v124
	v_rcp_f32_e32 v150, v137
	v_add_f32_e32 v137, 1.0, v151
	v_exp_f32_e32 v143, v143
	v_mul_f32_e32 v151, 0xbfb8aa3b, v125
	v_exp_f32_e32 v153, v151
	v_rcp_f32_e32 v151, v137
	v_add_f32_e32 v137, 1.0, v143
	v_rcp_f32_e32 v152, v137
	v_add_f32_e32 v137, 1.0, v153
	v_lshl_add_u64 v[154:155], s[34:35], 0, v[134:135]
	v_rcp_f32_e32 v153, v137
	v_lshl_add_u64 v[154:155], v[0:1], 2, v[154:155]
	v_add_co_u32_e32 v154, vcc, 0x438d000, v154
	s_nop 1
	v_addc_co_u32_e32 v155, vcc, 0, v155, vcc
	global_store_dwordx4 v[154:155], v[146:149], off
	global_store_dwordx4 v[154:155], v[150:153], off offset:16
